# gather_v: 4 lanes per pick, 48 B (three dwordx4) per lane, 16 picks per round, 64 accumulators per lane, 4-stage reduce-scatter (25% fewer vector-memory instructions)
# baseline (speedup 1.0000x reference)
.Lgv0_start:
	s_mov_b64 exec, -1
	v_and_b32_e32 v228, 63, v205
	v_lshrrev_b32_e32 v227, 6, v205
	v_lshlrev_b32_e32 v216, 2, v228
	v_readfirstlane_b32 s18, v227
	v_bfe_u32 v227, v228, 1, 2
	v_mul_u32_u24_e32 v219, 48, v227
	v_lshlrev_b32_e32 v220, 5, v227
	s_nop 3
	s_lshl_b32 s15, s18, 14
	s_add_i32 s101, s93, s18
	v_lshrrev_b32_e32 v227, 5, v228
	v_lshl_add_u32 v220, v227, 4, v220
	v_bfe_u32 v227, v228, 3, 2
	v_and_b32_e32 v217, 1, v228
	v_lshl_or_b32 v227, v227, 1, v217
	v_lshl_add_u32 v220, v227, 9, v220
	v_lshrrev_b32_e32 v227, 3, v228
	v_lshl_or_b32 v227, v227, 1, v217
	v_lshl_add_u32 v217, v227, 2, s15
	v_add_u32_e32 v218, 0x2000, v217
	v_add_u32_e32 v225, s15, v216
	v_add_u32_e32 v226, 0x2000, v225
	v_lshlrev_b32_e32 v229, 4, v228
.Lgv0_chunk:
	s_movk_i32 s100, 0xc0
	s_lshl_b32 s16, s92, 14
	s_add_u32 s12, s26, 0xd800000
	s_addc_u32 s13, s27, 0
	s_lshl_b32 s15, s101, 9
	s_add_u32 s12, s12, s15
	s_addc_u32 s13, s13, 0
	s_lshl_b32 s18, s92, 11
	global_load_dword v96, v216, s[12:13]
	global_load_dword v97, v216, s[12:13] offset:256
	s_add_u32 s12, s12, s18
	s_addc_u32 s13, s13, 0
	global_load_dword v98, v216, s[12:13]
	global_load_dword v99, v216, s[12:13] offset:256
	s_add_u32 s12, s12, s18
	s_addc_u32 s13, s13, 0
	global_load_dword v100, v216, s[12:13]
	global_load_dword v101, v216, s[12:13] offset:256
	s_add_u32 s12, s12, s18
	s_addc_u32 s13, s13, 0
	global_load_dword v102, v216, s[12:13]
	global_load_dword v103, v216, s[12:13] offset:256
	s_add_u32 s12, s12, s18
	s_addc_u32 s13, s13, 0
	global_load_dword v104, v216, s[12:13]
	global_load_dword v105, v216, s[12:13] offset:256
	s_add_u32 s12, s12, s18
	s_addc_u32 s13, s13, 0
	global_load_dword v106, v216, s[12:13]
	global_load_dword v107, v216, s[12:13] offset:256
	s_add_u32 s12, s12, s18
	s_addc_u32 s13, s13, 0
	global_load_dword v108, v216, s[12:13]
	global_load_dword v109, v216, s[12:13] offset:256
	s_add_u32 s12, s12, s18
	s_addc_u32 s13, s13, 0
	global_load_dword v110, v216, s[12:13]
	global_load_dword v111, v216, s[12:13] offset:256
	s_add_u32 s12, s12, s18
	s_addc_u32 s13, s13, 0
	global_load_dword v112, v216, s[12:13]
	global_load_dword v113, v216, s[12:13] offset:256
	s_add_u32 s12, s12, s18
	s_addc_u32 s13, s13, 0
	global_load_dword v114, v216, s[12:13]
	global_load_dword v115, v216, s[12:13] offset:256
	s_add_u32 s12, s12, s18
	s_addc_u32 s13, s13, 0
	global_load_dword v116, v216, s[12:13]
	global_load_dword v117, v216, s[12:13] offset:256
	s_add_u32 s12, s12, s18
	s_addc_u32 s13, s13, 0
	global_load_dword v118, v216, s[12:13]
	global_load_dword v119, v216, s[12:13] offset:256
	s_add_u32 s12, s12, s18
	s_addc_u32 s13, s13, 0
	global_load_dword v120, v216, s[12:13]
	global_load_dword v121, v216, s[12:13] offset:256
	s_add_u32 s12, s12, s18
	s_addc_u32 s13, s13, 0
	global_load_dword v122, v216, s[12:13]
	global_load_dword v123, v216, s[12:13] offset:256
	s_add_u32 s12, s12, s18
	s_addc_u32 s13, s13, 0
	global_load_dword v124, v216, s[12:13]
	global_load_dword v125, v216, s[12:13] offset:256
	s_add_u32 s12, s12, s18
	s_addc_u32 s13, s13, 0
	global_load_dword v126, v216, s[12:13]
	global_load_dword v127, v216, s[12:13] offset:256
	s_add_u32 s12, s12, s18
	s_addc_u32 s13, s13, 0
	s_waitcnt vmcnt(0)
	ds_write2st64_b32 v225, v96, v97 offset0:0 offset1:1
	ds_write2st64_b32 v225, v98, v99 offset0:2 offset1:3
	ds_write2st64_b32 v225, v100, v101 offset0:4 offset1:5
	ds_write2st64_b32 v225, v102, v103 offset0:6 offset1:7
	ds_write2st64_b32 v225, v104, v105 offset0:8 offset1:9
	ds_write2st64_b32 v225, v106, v107 offset0:10 offset1:11
	ds_write2st64_b32 v225, v108, v109 offset0:12 offset1:13
	ds_write2st64_b32 v225, v110, v111 offset0:14 offset1:15
	ds_write2st64_b32 v225, v112, v113 offset0:16 offset1:17
	ds_write2st64_b32 v225, v114, v115 offset0:18 offset1:19
	ds_write2st64_b32 v225, v116, v117 offset0:20 offset1:21
	ds_write2st64_b32 v225, v118, v119 offset0:22 offset1:23
	ds_write2st64_b32 v225, v120, v121 offset0:24 offset1:25
	ds_write2st64_b32 v225, v122, v123 offset0:26 offset1:27
	ds_write2st64_b32 v225, v124, v125 offset0:28 offset1:29
	ds_write2st64_b32 v225, v126, v127 offset0:30 offset1:31
	s_add_u32 s12, s26, 0xf800000
	s_addc_u32 s13, s27, 0
	s_lshl_b32 s15, s101, 9
	s_add_u32 s12, s12, s15
	s_addc_u32 s13, s13, 0
	s_lshl_b32 s18, s92, 11
	global_load_dword v96, v216, s[12:13]
	global_load_dword v97, v216, s[12:13] offset:256
	s_add_u32 s12, s12, s18
	s_addc_u32 s13, s13, 0
	global_load_dword v98, v216, s[12:13]
	global_load_dword v99, v216, s[12:13] offset:256
	s_add_u32 s12, s12, s18
	s_addc_u32 s13, s13, 0
	global_load_dword v100, v216, s[12:13]
	global_load_dword v101, v216, s[12:13] offset:256
	s_add_u32 s12, s12, s18
	s_addc_u32 s13, s13, 0
	global_load_dword v102, v216, s[12:13]
	global_load_dword v103, v216, s[12:13] offset:256
	s_add_u32 s12, s12, s18
	s_addc_u32 s13, s13, 0
	global_load_dword v104, v216, s[12:13]
	global_load_dword v105, v216, s[12:13] offset:256
	s_add_u32 s12, s12, s18
	s_addc_u32 s13, s13, 0
	global_load_dword v106, v216, s[12:13]
	global_load_dword v107, v216, s[12:13] offset:256
	s_add_u32 s12, s12, s18
	s_addc_u32 s13, s13, 0
	global_load_dword v108, v216, s[12:13]
	global_load_dword v109, v216, s[12:13] offset:256
	s_add_u32 s12, s12, s18
	s_addc_u32 s13, s13, 0
	global_load_dword v110, v216, s[12:13]
	global_load_dword v111, v216, s[12:13] offset:256
	s_add_u32 s12, s12, s18
	s_addc_u32 s13, s13, 0
	global_load_dword v112, v216, s[12:13]
	global_load_dword v113, v216, s[12:13] offset:256
	s_add_u32 s12, s12, s18
	s_addc_u32 s13, s13, 0
	global_load_dword v114, v216, s[12:13]
	global_load_dword v115, v216, s[12:13] offset:256
	s_add_u32 s12, s12, s18
	s_addc_u32 s13, s13, 0
	global_load_dword v116, v216, s[12:13]
	global_load_dword v117, v216, s[12:13] offset:256
	s_add_u32 s12, s12, s18
	s_addc_u32 s13, s13, 0
	global_load_dword v118, v216, s[12:13]
	global_load_dword v119, v216, s[12:13] offset:256
	s_add_u32 s12, s12, s18
	s_addc_u32 s13, s13, 0
	global_load_dword v120, v216, s[12:13]
	global_load_dword v121, v216, s[12:13] offset:256
	s_add_u32 s12, s12, s18
	s_addc_u32 s13, s13, 0
	global_load_dword v122, v216, s[12:13]
	global_load_dword v123, v216, s[12:13] offset:256
	s_add_u32 s12, s12, s18
	s_addc_u32 s13, s13, 0
	global_load_dword v124, v216, s[12:13]
	global_load_dword v125, v216, s[12:13] offset:256
	s_add_u32 s12, s12, s18
	s_addc_u32 s13, s13, 0
	global_load_dword v126, v216, s[12:13]
	global_load_dword v127, v216, s[12:13] offset:256
	s_add_u32 s12, s12, s18
	s_addc_u32 s13, s13, 0
	s_waitcnt vmcnt(0)
	ds_write2st64_b32 v226, v96, v97 offset0:0 offset1:1
	ds_write2st64_b32 v226, v98, v99 offset0:2 offset1:3
	ds_write2st64_b32 v226, v100, v101 offset0:4 offset1:5
	ds_write2st64_b32 v226, v102, v103 offset0:6 offset1:7
	ds_write2st64_b32 v226, v104, v105 offset0:8 offset1:9
	ds_write2st64_b32 v226, v106, v107 offset0:10 offset1:11
	ds_write2st64_b32 v226, v108, v109 offset0:12 offset1:13
	ds_write2st64_b32 v226, v110, v111 offset0:14 offset1:15
	ds_write2st64_b32 v226, v112, v113 offset0:16 offset1:17
	ds_write2st64_b32 v226, v114, v115 offset0:18 offset1:19
	ds_write2st64_b32 v226, v116, v117 offset0:20 offset1:21
	ds_write2st64_b32 v226, v118, v119 offset0:22 offset1:23
	ds_write2st64_b32 v226, v120, v121 offset0:24 offset1:25
	ds_write2st64_b32 v226, v122, v123 offset0:26 offset1:27
	ds_write2st64_b32 v226, v124, v125 offset0:28 offset1:29
	ds_write2st64_b32 v226, v126, v127 offset0:30 offset1:31
	s_waitcnt lgkmcnt(0)
	s_mov_b32 s14, 0
	s_mov_b32 s18, 0
	s_and_b32 s19, s18, 15
	s_lshr_b32 s98, s18, 4
	s_lshl_b32 s99, s19, 9
	s_mul_i32 s15, s19, s16
	s_lshl_b32 s18, s98, 7
	s_add_u32 s15, s15, s18
	s_lshl_b32 s18, s101, 12
	s_add_u32 s15, s15, s18
	s_add_u32 s8, s24, s15
	s_addc_u32 s9, s25, 0
	s_mul_i32 s15, s98, 0x300000
	s_add_u32 s4, s26, 0x3800000
	s_addc_u32 s5, s27, 0
	s_add_u32 s4, s4, s15
	s_addc_u32 s5, s5, 0
	v_add_u32_e32 v221, s99, v217
	v_add_u32_e32 v223, s99, v218
	ds_read2_b32 v[192:193], v221 offset0:0 offset1:16
	ds_read2_b32 v[194:195], v221 offset0:32 offset1:48
	s_waitcnt lgkmcnt(0)
	v_mad_u32_u24 v192, v192, s100, v219
	v_mad_u32_u24 v193, v193, s100, v219
	v_mad_u32_u24 v194, v194, s100, v219
	v_mad_u32_u24 v195, v195, s100, v219
	global_load_dwordx4 v[96:99], v192, s[4:5]
	global_load_dwordx4 v[100:103], v192, s[4:5] offset:16
	global_load_dwordx4 v[104:107], v192, s[4:5] offset:32
	global_load_dwordx4 v[108:111], v193, s[4:5]
	global_load_dwordx4 v[112:115], v193, s[4:5] offset:16
	global_load_dwordx4 v[116:119], v193, s[4:5] offset:32
	global_load_dwordx4 v[120:123], v194, s[4:5]
	global_load_dwordx4 v[124:127], v194, s[4:5] offset:16
	global_load_dwordx4 v[128:131], v194, s[4:5] offset:32
	global_load_dwordx4 v[132:135], v195, s[4:5]
	global_load_dwordx4 v[136:139], v195, s[4:5] offset:16
	global_load_dwordx4 v[140:143], v195, s[4:5] offset:32
	ds_read2_b32 v[196:197], v221 offset0:64 offset1:80
	ds_read2_b32 v[198:199], v221 offset0:96 offset1:112
	s_waitcnt lgkmcnt(0)
	v_mad_u32_u24 v196, v196, s100, v219
	v_mad_u32_u24 v197, v197, s100, v219
	v_mad_u32_u24 v198, v198, s100, v219
	v_mad_u32_u24 v199, v199, s100, v219
	global_load_dwordx4 v[144:147], v196, s[4:5]
	global_load_dwordx4 v[148:151], v196, s[4:5] offset:16
	global_load_dwordx4 v[152:155], v196, s[4:5] offset:32
	global_load_dwordx4 v[156:159], v197, s[4:5]
	global_load_dwordx4 v[160:163], v197, s[4:5] offset:16
	global_load_dwordx4 v[164:167], v197, s[4:5] offset:32
	global_load_dwordx4 v[168:171], v198, s[4:5]
	global_load_dwordx4 v[172:175], v198, s[4:5] offset:16
	global_load_dwordx4 v[176:179], v198, s[4:5] offset:32
	global_load_dwordx4 v[180:183], v199, s[4:5]
	global_load_dwordx4 v[184:187], v199, s[4:5] offset:16
	global_load_dwordx4 v[188:191], v199, s[4:5] offset:32
	global_load_dword v227, v220, s[8:9]
	ds_read2_b32 v[200:201], v223 offset0:0 offset1:16
	ds_read2_b32 v[202:203], v223 offset0:32 offset1:48
	s_mov_b32 s18, 1
	s_and_b32 s19, s18, 15
	s_lshr_b32 s98, s18, 4
	s_lshl_b32 s99, s19, 9
	s_mul_i32 s15, s19, s16
	s_lshl_b32 s18, s98, 7
	s_add_u32 s15, s15, s18
	s_lshl_b32 s18, s101, 12
	s_add_u32 s15, s15, s18
	s_add_u32 s10, s24, s15
	s_addc_u32 s11, s25, 0
	s_mul_i32 s15, s98, 0x300000
	s_add_u32 s4, s26, 0x3800000
	s_addc_u32 s5, s27, 0
	s_add_u32 s4, s4, s15
	s_addc_u32 s5, s5, 0
	v_add_u32_e32 v222, s99, v217
	v_add_u32_e32 v224, s99, v218
	ds_read2_b32 v[192:193], v222 offset0:0 offset1:16
	ds_read2_b32 v[194:195], v222 offset0:32 offset1:48
	s_waitcnt lgkmcnt(0)
.Lgv0_loop:
	global_load_dwordx4 v[212:215], v220, s[8:9]
	ds_read2_b32 v[208:209], v223 offset0:64 offset1:80
	ds_read2_b32 v[210:211], v223 offset0:96 offset1:112
	s_waitcnt vmcnt(23)
	v_cvt_scalef32_pk32_f32_fp6 v[64:95], v[96:101], 1.0
	v_pk_mul_f32 v[0:1], v[200:201], v[64:65] op_sel_hi:[0,1]
	v_pk_mul_f32 v[2:3], v[200:201], v[66:67] op_sel_hi:[0,1]
	v_pk_mul_f32 v[4:5], v[200:201], v[68:69] op_sel_hi:[0,1]
	v_pk_mul_f32 v[6:7], v[200:201], v[70:71] op_sel_hi:[0,1]
	v_pk_mul_f32 v[8:9], v[200:201], v[72:73] op_sel_hi:[0,1]
	v_pk_mul_f32 v[10:11], v[200:201], v[74:75] op_sel_hi:[0,1]
	v_pk_mul_f32 v[12:13], v[200:201], v[76:77] op_sel_hi:[0,1]
	v_pk_mul_f32 v[14:15], v[200:201], v[78:79] op_sel_hi:[0,1]
	v_pk_mul_f32 v[16:17], v[200:201], v[80:81] op_sel_hi:[0,1]
	v_pk_mul_f32 v[18:19], v[200:201], v[82:83] op_sel_hi:[0,1]
	v_pk_mul_f32 v[20:21], v[200:201], v[84:85] op_sel_hi:[0,1]
	v_pk_mul_f32 v[22:23], v[200:201], v[86:87] op_sel_hi:[0,1]
	v_pk_mul_f32 v[24:25], v[200:201], v[88:89] op_sel_hi:[0,1]
	v_pk_mul_f32 v[26:27], v[200:201], v[90:91] op_sel_hi:[0,1]
	v_pk_mul_f32 v[28:29], v[200:201], v[92:93] op_sel_hi:[0,1]
	v_pk_mul_f32 v[30:31], v[200:201], v[94:95] op_sel_hi:[0,1]
	v_cvt_scalef32_pk32_f32_fp6 v[64:95], v[102:107], 1.0
	v_pk_mul_f32 v[32:33], v[200:201], v[64:65] op_sel_hi:[0,1]
	v_pk_mul_f32 v[34:35], v[200:201], v[66:67] op_sel_hi:[0,1]
	v_pk_mul_f32 v[36:37], v[200:201], v[68:69] op_sel_hi:[0,1]
	v_pk_mul_f32 v[38:39], v[200:201], v[70:71] op_sel_hi:[0,1]
	v_pk_mul_f32 v[40:41], v[200:201], v[72:73] op_sel_hi:[0,1]
	v_pk_mul_f32 v[42:43], v[200:201], v[74:75] op_sel_hi:[0,1]
	v_pk_mul_f32 v[44:45], v[200:201], v[76:77] op_sel_hi:[0,1]
	v_pk_mul_f32 v[46:47], v[200:201], v[78:79] op_sel_hi:[0,1]
	v_pk_mul_f32 v[48:49], v[200:201], v[80:81] op_sel_hi:[0,1]
	v_pk_mul_f32 v[50:51], v[200:201], v[82:83] op_sel_hi:[0,1]
	v_pk_mul_f32 v[52:53], v[200:201], v[84:85] op_sel_hi:[0,1]
	v_pk_mul_f32 v[54:55], v[200:201], v[86:87] op_sel_hi:[0,1]
	v_pk_mul_f32 v[56:57], v[200:201], v[88:89] op_sel_hi:[0,1]
	v_pk_mul_f32 v[58:59], v[200:201], v[90:91] op_sel_hi:[0,1]
	v_pk_mul_f32 v[60:61], v[200:201], v[92:93] op_sel_hi:[0,1]
	v_pk_mul_f32 v[62:63], v[200:201], v[94:95] op_sel_hi:[0,1]
	s_waitcnt vmcnt(20)
	v_cvt_scalef32_pk32_f32_fp6 v[64:95], v[108:113], 1.0
	v_pk_fma_f32 v[0:1], v[200:201], v[64:65], v[0:1] op_sel:[1,0,0] op_sel_hi:[1,1,1]
	v_pk_fma_f32 v[2:3], v[200:201], v[66:67], v[2:3] op_sel:[1,0,0] op_sel_hi:[1,1,1]
	v_pk_fma_f32 v[4:5], v[200:201], v[68:69], v[4:5] op_sel:[1,0,0] op_sel_hi:[1,1,1]
	v_pk_fma_f32 v[6:7], v[200:201], v[70:71], v[6:7] op_sel:[1,0,0] op_sel_hi:[1,1,1]
	v_pk_fma_f32 v[8:9], v[200:201], v[72:73], v[8:9] op_sel:[1,0,0] op_sel_hi:[1,1,1]
	v_pk_fma_f32 v[10:11], v[200:201], v[74:75], v[10:11] op_sel:[1,0,0] op_sel_hi:[1,1,1]
	v_pk_fma_f32 v[12:13], v[200:201], v[76:77], v[12:13] op_sel:[1,0,0] op_sel_hi:[1,1,1]
	v_pk_fma_f32 v[14:15], v[200:201], v[78:79], v[14:15] op_sel:[1,0,0] op_sel_hi:[1,1,1]
	v_pk_fma_f32 v[16:17], v[200:201], v[80:81], v[16:17] op_sel:[1,0,0] op_sel_hi:[1,1,1]
	v_pk_fma_f32 v[18:19], v[200:201], v[82:83], v[18:19] op_sel:[1,0,0] op_sel_hi:[1,1,1]
	v_pk_fma_f32 v[20:21], v[200:201], v[84:85], v[20:21] op_sel:[1,0,0] op_sel_hi:[1,1,1]
	v_pk_fma_f32 v[22:23], v[200:201], v[86:87], v[22:23] op_sel:[1,0,0] op_sel_hi:[1,1,1]
	v_pk_fma_f32 v[24:25], v[200:201], v[88:89], v[24:25] op_sel:[1,0,0] op_sel_hi:[1,1,1]
	v_pk_fma_f32 v[26:27], v[200:201], v[90:91], v[26:27] op_sel:[1,0,0] op_sel_hi:[1,1,1]
	v_pk_fma_f32 v[28:29], v[200:201], v[92:93], v[28:29] op_sel:[1,0,0] op_sel_hi:[1,1,1]
	v_pk_fma_f32 v[30:31], v[200:201], v[94:95], v[30:31] op_sel:[1,0,0] op_sel_hi:[1,1,1]
	v_cvt_scalef32_pk32_f32_fp6 v[64:95], v[114:119], 1.0
	v_pk_fma_f32 v[32:33], v[200:201], v[64:65], v[32:33] op_sel:[1,0,0] op_sel_hi:[1,1,1]
	v_pk_fma_f32 v[34:35], v[200:201], v[66:67], v[34:35] op_sel:[1,0,0] op_sel_hi:[1,1,1]
	v_pk_fma_f32 v[36:37], v[200:201], v[68:69], v[36:37] op_sel:[1,0,0] op_sel_hi:[1,1,1]
	v_pk_fma_f32 v[38:39], v[200:201], v[70:71], v[38:39] op_sel:[1,0,0] op_sel_hi:[1,1,1]
	v_pk_fma_f32 v[40:41], v[200:201], v[72:73], v[40:41] op_sel:[1,0,0] op_sel_hi:[1,1,1]
	v_pk_fma_f32 v[42:43], v[200:201], v[74:75], v[42:43] op_sel:[1,0,0] op_sel_hi:[1,1,1]
	v_pk_fma_f32 v[44:45], v[200:201], v[76:77], v[44:45] op_sel:[1,0,0] op_sel_hi:[1,1,1]
	v_pk_fma_f32 v[46:47], v[200:201], v[78:79], v[46:47] op_sel:[1,0,0] op_sel_hi:[1,1,1]
	v_pk_fma_f32 v[48:49], v[200:201], v[80:81], v[48:49] op_sel:[1,0,0] op_sel_hi:[1,1,1]
	v_pk_fma_f32 v[50:51], v[200:201], v[82:83], v[50:51] op_sel:[1,0,0] op_sel_hi:[1,1,1]
	v_pk_fma_f32 v[52:53], v[200:201], v[84:85], v[52:53] op_sel:[1,0,0] op_sel_hi:[1,1,1]
	v_pk_fma_f32 v[54:55], v[200:201], v[86:87], v[54:55] op_sel:[1,0,0] op_sel_hi:[1,1,1]
	v_pk_fma_f32 v[56:57], v[200:201], v[88:89], v[56:57] op_sel:[1,0,0] op_sel_hi:[1,1,1]
	v_pk_fma_f32 v[58:59], v[200:201], v[90:91], v[58:59] op_sel:[1,0,0] op_sel_hi:[1,1,1]
	v_pk_fma_f32 v[60:61], v[200:201], v[92:93], v[60:61] op_sel:[1,0,0] op_sel_hi:[1,1,1]
	v_pk_fma_f32 v[62:63], v[200:201], v[94:95], v[62:63] op_sel:[1,0,0] op_sel_hi:[1,1,1]
	s_waitcnt vmcnt(17)
	v_cvt_scalef32_pk32_f32_fp6 v[64:95], v[120:125], 1.0
	v_pk_fma_f32 v[0:1], v[202:203], v[64:65], v[0:1] op_sel_hi:[0,1,1]
	v_pk_fma_f32 v[2:3], v[202:203], v[66:67], v[2:3] op_sel_hi:[0,1,1]
	v_pk_fma_f32 v[4:5], v[202:203], v[68:69], v[4:5] op_sel_hi:[0,1,1]
	v_pk_fma_f32 v[6:7], v[202:203], v[70:71], v[6:7] op_sel_hi:[0,1,1]
	v_pk_fma_f32 v[8:9], v[202:203], v[72:73], v[8:9] op_sel_hi:[0,1,1]
	v_pk_fma_f32 v[10:11], v[202:203], v[74:75], v[10:11] op_sel_hi:[0,1,1]
	v_pk_fma_f32 v[12:13], v[202:203], v[76:77], v[12:13] op_sel_hi:[0,1,1]
	v_pk_fma_f32 v[14:15], v[202:203], v[78:79], v[14:15] op_sel_hi:[0,1,1]
	v_pk_fma_f32 v[16:17], v[202:203], v[80:81], v[16:17] op_sel_hi:[0,1,1]
	v_pk_fma_f32 v[18:19], v[202:203], v[82:83], v[18:19] op_sel_hi:[0,1,1]
	v_pk_fma_f32 v[20:21], v[202:203], v[84:85], v[20:21] op_sel_hi:[0,1,1]
	v_pk_fma_f32 v[22:23], v[202:203], v[86:87], v[22:23] op_sel_hi:[0,1,1]
	v_pk_fma_f32 v[24:25], v[202:203], v[88:89], v[24:25] op_sel_hi:[0,1,1]
	v_pk_fma_f32 v[26:27], v[202:203], v[90:91], v[26:27] op_sel_hi:[0,1,1]
	v_pk_fma_f32 v[28:29], v[202:203], v[92:93], v[28:29] op_sel_hi:[0,1,1]
	v_pk_fma_f32 v[30:31], v[202:203], v[94:95], v[30:31] op_sel_hi:[0,1,1]
	v_cvt_scalef32_pk32_f32_fp6 v[64:95], v[126:131], 1.0
	v_pk_fma_f32 v[32:33], v[202:203], v[64:65], v[32:33] op_sel_hi:[0,1,1]
	v_pk_fma_f32 v[34:35], v[202:203], v[66:67], v[34:35] op_sel_hi:[0,1,1]
	v_pk_fma_f32 v[36:37], v[202:203], v[68:69], v[36:37] op_sel_hi:[0,1,1]
	v_pk_fma_f32 v[38:39], v[202:203], v[70:71], v[38:39] op_sel_hi:[0,1,1]
	v_pk_fma_f32 v[40:41], v[202:203], v[72:73], v[40:41] op_sel_hi:[0,1,1]
	v_pk_fma_f32 v[42:43], v[202:203], v[74:75], v[42:43] op_sel_hi:[0,1,1]
	v_pk_fma_f32 v[44:45], v[202:203], v[76:77], v[44:45] op_sel_hi:[0,1,1]
	v_pk_fma_f32 v[46:47], v[202:203], v[78:79], v[46:47] op_sel_hi:[0,1,1]
	v_pk_fma_f32 v[48:49], v[202:203], v[80:81], v[48:49] op_sel_hi:[0,1,1]
	v_pk_fma_f32 v[50:51], v[202:203], v[82:83], v[50:51] op_sel_hi:[0,1,1]
	v_pk_fma_f32 v[52:53], v[202:203], v[84:85], v[52:53] op_sel_hi:[0,1,1]
	v_pk_fma_f32 v[54:55], v[202:203], v[86:87], v[54:55] op_sel_hi:[0,1,1]
	v_pk_fma_f32 v[56:57], v[202:203], v[88:89], v[56:57] op_sel_hi:[0,1,1]
	v_pk_fma_f32 v[58:59], v[202:203], v[90:91], v[58:59] op_sel_hi:[0,1,1]
	v_pk_fma_f32 v[60:61], v[202:203], v[92:93], v[60:61] op_sel_hi:[0,1,1]
	v_pk_fma_f32 v[62:63], v[202:203], v[94:95], v[62:63] op_sel_hi:[0,1,1]
	s_waitcnt vmcnt(14)
	v_cvt_scalef32_pk32_f32_fp6 v[64:95], v[132:137], 1.0
	v_pk_fma_f32 v[0:1], v[202:203], v[64:65], v[0:1] op_sel:[1,0,0] op_sel_hi:[1,1,1]
	v_pk_fma_f32 v[2:3], v[202:203], v[66:67], v[2:3] op_sel:[1,0,0] op_sel_hi:[1,1,1]
	v_pk_fma_f32 v[4:5], v[202:203], v[68:69], v[4:5] op_sel:[1,0,0] op_sel_hi:[1,1,1]
	v_pk_fma_f32 v[6:7], v[202:203], v[70:71], v[6:7] op_sel:[1,0,0] op_sel_hi:[1,1,1]
	v_pk_fma_f32 v[8:9], v[202:203], v[72:73], v[8:9] op_sel:[1,0,0] op_sel_hi:[1,1,1]
	v_pk_fma_f32 v[10:11], v[202:203], v[74:75], v[10:11] op_sel:[1,0,0] op_sel_hi:[1,1,1]
	v_pk_fma_f32 v[12:13], v[202:203], v[76:77], v[12:13] op_sel:[1,0,0] op_sel_hi:[1,1,1]
	v_pk_fma_f32 v[14:15], v[202:203], v[78:79], v[14:15] op_sel:[1,0,0] op_sel_hi:[1,1,1]
	v_pk_fma_f32 v[16:17], v[202:203], v[80:81], v[16:17] op_sel:[1,0,0] op_sel_hi:[1,1,1]
	v_pk_fma_f32 v[18:19], v[202:203], v[82:83], v[18:19] op_sel:[1,0,0] op_sel_hi:[1,1,1]
	v_pk_fma_f32 v[20:21], v[202:203], v[84:85], v[20:21] op_sel:[1,0,0] op_sel_hi:[1,1,1]
	v_pk_fma_f32 v[22:23], v[202:203], v[86:87], v[22:23] op_sel:[1,0,0] op_sel_hi:[1,1,1]
	v_pk_fma_f32 v[24:25], v[202:203], v[88:89], v[24:25] op_sel:[1,0,0] op_sel_hi:[1,1,1]
	v_pk_fma_f32 v[26:27], v[202:203], v[90:91], v[26:27] op_sel:[1,0,0] op_sel_hi:[1,1,1]
	v_pk_fma_f32 v[28:29], v[202:203], v[92:93], v[28:29] op_sel:[1,0,0] op_sel_hi:[1,1,1]
	v_pk_fma_f32 v[30:31], v[202:203], v[94:95], v[30:31] op_sel:[1,0,0] op_sel_hi:[1,1,1]
	v_cvt_scalef32_pk32_f32_fp6 v[64:95], v[138:143], 1.0
	v_pk_fma_f32 v[32:33], v[202:203], v[64:65], v[32:33] op_sel:[1,0,0] op_sel_hi:[1,1,1]
	v_pk_fma_f32 v[34:35], v[202:203], v[66:67], v[34:35] op_sel:[1,0,0] op_sel_hi:[1,1,1]
	v_pk_fma_f32 v[36:37], v[202:203], v[68:69], v[36:37] op_sel:[1,0,0] op_sel_hi:[1,1,1]
	v_pk_fma_f32 v[38:39], v[202:203], v[70:71], v[38:39] op_sel:[1,0,0] op_sel_hi:[1,1,1]
	v_pk_fma_f32 v[40:41], v[202:203], v[72:73], v[40:41] op_sel:[1,0,0] op_sel_hi:[1,1,1]
	v_pk_fma_f32 v[42:43], v[202:203], v[74:75], v[42:43] op_sel:[1,0,0] op_sel_hi:[1,1,1]
	v_pk_fma_f32 v[44:45], v[202:203], v[76:77], v[44:45] op_sel:[1,0,0] op_sel_hi:[1,1,1]
	v_pk_fma_f32 v[46:47], v[202:203], v[78:79], v[46:47] op_sel:[1,0,0] op_sel_hi:[1,1,1]
	v_pk_fma_f32 v[48:49], v[202:203], v[80:81], v[48:49] op_sel:[1,0,0] op_sel_hi:[1,1,1]
	v_pk_fma_f32 v[50:51], v[202:203], v[82:83], v[50:51] op_sel:[1,0,0] op_sel_hi:[1,1,1]
	v_pk_fma_f32 v[52:53], v[202:203], v[84:85], v[52:53] op_sel:[1,0,0] op_sel_hi:[1,1,1]
	v_pk_fma_f32 v[54:55], v[202:203], v[86:87], v[54:55] op_sel:[1,0,0] op_sel_hi:[1,1,1]
	v_pk_fma_f32 v[56:57], v[202:203], v[88:89], v[56:57] op_sel:[1,0,0] op_sel_hi:[1,1,1]
	v_pk_fma_f32 v[58:59], v[202:203], v[90:91], v[58:59] op_sel:[1,0,0] op_sel_hi:[1,1,1]
	v_pk_fma_f32 v[60:61], v[202:203], v[92:93], v[60:61] op_sel:[1,0,0] op_sel_hi:[1,1,1]
	v_pk_fma_f32 v[62:63], v[202:203], v[94:95], v[62:63] op_sel:[1,0,0] op_sel_hi:[1,1,1]
	s_waitcnt lgkmcnt(0)
	v_mad_u32_u24 v192, v192, s100, v219
	v_mad_u32_u24 v193, v193, s100, v219
	v_mad_u32_u24 v194, v194, s100, v219
	v_mad_u32_u24 v195, v195, s100, v219
	global_load_dwordx4 v[96:99], v192, s[4:5]
	global_load_dwordx4 v[100:103], v192, s[4:5] offset:16
	global_load_dwordx4 v[104:107], v192, s[4:5] offset:32
	global_load_dwordx4 v[108:111], v193, s[4:5]
	global_load_dwordx4 v[112:115], v193, s[4:5] offset:16
	global_load_dwordx4 v[116:119], v193, s[4:5] offset:32
	global_load_dwordx4 v[120:123], v194, s[4:5]
	global_load_dwordx4 v[124:127], v194, s[4:5] offset:16
	global_load_dwordx4 v[128:131], v194, s[4:5] offset:32
	global_load_dwordx4 v[132:135], v195, s[4:5]
	global_load_dwordx4 v[136:139], v195, s[4:5] offset:16
	global_load_dwordx4 v[140:143], v195, s[4:5] offset:32
	ds_read2_b32 v[196:197], v222 offset0:64 offset1:80
	ds_read2_b32 v[198:199], v222 offset0:96 offset1:112
	ds_read2_b32 v[200:201], v224 offset0:0 offset1:16
	ds_read2_b32 v[202:203], v224 offset0:32 offset1:48
	s_waitcnt vmcnt(23)
	v_cvt_scalef32_pk32_f32_fp6 v[64:95], v[144:149], 1.0
	v_pk_fma_f32 v[0:1], v[208:209], v[64:65], v[0:1] op_sel_hi:[0,1,1]
	v_pk_fma_f32 v[2:3], v[208:209], v[66:67], v[2:3] op_sel_hi:[0,1,1]
	v_pk_fma_f32 v[4:5], v[208:209], v[68:69], v[4:5] op_sel_hi:[0,1,1]
	v_pk_fma_f32 v[6:7], v[208:209], v[70:71], v[6:7] op_sel_hi:[0,1,1]
	v_pk_fma_f32 v[8:9], v[208:209], v[72:73], v[8:9] op_sel_hi:[0,1,1]
	v_pk_fma_f32 v[10:11], v[208:209], v[74:75], v[10:11] op_sel_hi:[0,1,1]
	v_pk_fma_f32 v[12:13], v[208:209], v[76:77], v[12:13] op_sel_hi:[0,1,1]
	v_pk_fma_f32 v[14:15], v[208:209], v[78:79], v[14:15] op_sel_hi:[0,1,1]
	v_pk_fma_f32 v[16:17], v[208:209], v[80:81], v[16:17] op_sel_hi:[0,1,1]
	v_pk_fma_f32 v[18:19], v[208:209], v[82:83], v[18:19] op_sel_hi:[0,1,1]
	v_pk_fma_f32 v[20:21], v[208:209], v[84:85], v[20:21] op_sel_hi:[0,1,1]
	v_pk_fma_f32 v[22:23], v[208:209], v[86:87], v[22:23] op_sel_hi:[0,1,1]
	v_pk_fma_f32 v[24:25], v[208:209], v[88:89], v[24:25] op_sel_hi:[0,1,1]
	v_pk_fma_f32 v[26:27], v[208:209], v[90:91], v[26:27] op_sel_hi:[0,1,1]
	v_pk_fma_f32 v[28:29], v[208:209], v[92:93], v[28:29] op_sel_hi:[0,1,1]
	v_pk_fma_f32 v[30:31], v[208:209], v[94:95], v[30:31] op_sel_hi:[0,1,1]
	v_cvt_scalef32_pk32_f32_fp6 v[64:95], v[150:155], 1.0
	v_pk_fma_f32 v[32:33], v[208:209], v[64:65], v[32:33] op_sel_hi:[0,1,1]
	v_pk_fma_f32 v[34:35], v[208:209], v[66:67], v[34:35] op_sel_hi:[0,1,1]
	v_pk_fma_f32 v[36:37], v[208:209], v[68:69], v[36:37] op_sel_hi:[0,1,1]
	v_pk_fma_f32 v[38:39], v[208:209], v[70:71], v[38:39] op_sel_hi:[0,1,1]
	v_pk_fma_f32 v[40:41], v[208:209], v[72:73], v[40:41] op_sel_hi:[0,1,1]
	v_pk_fma_f32 v[42:43], v[208:209], v[74:75], v[42:43] op_sel_hi:[0,1,1]
	v_pk_fma_f32 v[44:45], v[208:209], v[76:77], v[44:45] op_sel_hi:[0,1,1]
	v_pk_fma_f32 v[46:47], v[208:209], v[78:79], v[46:47] op_sel_hi:[0,1,1]
	v_pk_fma_f32 v[48:49], v[208:209], v[80:81], v[48:49] op_sel_hi:[0,1,1]
	v_pk_fma_f32 v[50:51], v[208:209], v[82:83], v[50:51] op_sel_hi:[0,1,1]
	v_pk_fma_f32 v[52:53], v[208:209], v[84:85], v[52:53] op_sel_hi:[0,1,1]
	v_pk_fma_f32 v[54:55], v[208:209], v[86:87], v[54:55] op_sel_hi:[0,1,1]
	v_pk_fma_f32 v[56:57], v[208:209], v[88:89], v[56:57] op_sel_hi:[0,1,1]
	v_pk_fma_f32 v[58:59], v[208:209], v[90:91], v[58:59] op_sel_hi:[0,1,1]
	v_pk_fma_f32 v[60:61], v[208:209], v[92:93], v[60:61] op_sel_hi:[0,1,1]
	v_pk_fma_f32 v[62:63], v[208:209], v[94:95], v[62:63] op_sel_hi:[0,1,1]
	s_waitcnt vmcnt(20)
	v_cvt_scalef32_pk32_f32_fp6 v[64:95], v[156:161], 1.0
	v_pk_fma_f32 v[0:1], v[208:209], v[64:65], v[0:1] op_sel:[1,0,0] op_sel_hi:[1,1,1]
	v_pk_fma_f32 v[2:3], v[208:209], v[66:67], v[2:3] op_sel:[1,0,0] op_sel_hi:[1,1,1]
	v_pk_fma_f32 v[4:5], v[208:209], v[68:69], v[4:5] op_sel:[1,0,0] op_sel_hi:[1,1,1]
	v_pk_fma_f32 v[6:7], v[208:209], v[70:71], v[6:7] op_sel:[1,0,0] op_sel_hi:[1,1,1]
	v_pk_fma_f32 v[8:9], v[208:209], v[72:73], v[8:9] op_sel:[1,0,0] op_sel_hi:[1,1,1]
	v_pk_fma_f32 v[10:11], v[208:209], v[74:75], v[10:11] op_sel:[1,0,0] op_sel_hi:[1,1,1]
	v_pk_fma_f32 v[12:13], v[208:209], v[76:77], v[12:13] op_sel:[1,0,0] op_sel_hi:[1,1,1]
	v_pk_fma_f32 v[14:15], v[208:209], v[78:79], v[14:15] op_sel:[1,0,0] op_sel_hi:[1,1,1]
	v_pk_fma_f32 v[16:17], v[208:209], v[80:81], v[16:17] op_sel:[1,0,0] op_sel_hi:[1,1,1]
	v_pk_fma_f32 v[18:19], v[208:209], v[82:83], v[18:19] op_sel:[1,0,0] op_sel_hi:[1,1,1]
	v_pk_fma_f32 v[20:21], v[208:209], v[84:85], v[20:21] op_sel:[1,0,0] op_sel_hi:[1,1,1]
	v_pk_fma_f32 v[22:23], v[208:209], v[86:87], v[22:23] op_sel:[1,0,0] op_sel_hi:[1,1,1]
	v_pk_fma_f32 v[24:25], v[208:209], v[88:89], v[24:25] op_sel:[1,0,0] op_sel_hi:[1,1,1]
	v_pk_fma_f32 v[26:27], v[208:209], v[90:91], v[26:27] op_sel:[1,0,0] op_sel_hi:[1,1,1]
	v_pk_fma_f32 v[28:29], v[208:209], v[92:93], v[28:29] op_sel:[1,0,0] op_sel_hi:[1,1,1]
	v_pk_fma_f32 v[30:31], v[208:209], v[94:95], v[30:31] op_sel:[1,0,0] op_sel_hi:[1,1,1]
	v_cvt_scalef32_pk32_f32_fp6 v[64:95], v[162:167], 1.0
	v_pk_fma_f32 v[32:33], v[208:209], v[64:65], v[32:33] op_sel:[1,0,0] op_sel_hi:[1,1,1]
	v_pk_fma_f32 v[34:35], v[208:209], v[66:67], v[34:35] op_sel:[1,0,0] op_sel_hi:[1,1,1]
	v_pk_fma_f32 v[36:37], v[208:209], v[68:69], v[36:37] op_sel:[1,0,0] op_sel_hi:[1,1,1]
	v_pk_fma_f32 v[38:39], v[208:209], v[70:71], v[38:39] op_sel:[1,0,0] op_sel_hi:[1,1,1]
	v_pk_fma_f32 v[40:41], v[208:209], v[72:73], v[40:41] op_sel:[1,0,0] op_sel_hi:[1,1,1]
	v_pk_fma_f32 v[42:43], v[208:209], v[74:75], v[42:43] op_sel:[1,0,0] op_sel_hi:[1,1,1]
	v_pk_fma_f32 v[44:45], v[208:209], v[76:77], v[44:45] op_sel:[1,0,0] op_sel_hi:[1,1,1]
	v_pk_fma_f32 v[46:47], v[208:209], v[78:79], v[46:47] op_sel:[1,0,0] op_sel_hi:[1,1,1]
	v_pk_fma_f32 v[48:49], v[208:209], v[80:81], v[48:49] op_sel:[1,0,0] op_sel_hi:[1,1,1]
	v_pk_fma_f32 v[50:51], v[208:209], v[82:83], v[50:51] op_sel:[1,0,0] op_sel_hi:[1,1,1]
	v_pk_fma_f32 v[52:53], v[208:209], v[84:85], v[52:53] op_sel:[1,0,0] op_sel_hi:[1,1,1]
	v_pk_fma_f32 v[54:55], v[208:209], v[86:87], v[54:55] op_sel:[1,0,0] op_sel_hi:[1,1,1]
	v_pk_fma_f32 v[56:57], v[208:209], v[88:89], v[56:57] op_sel:[1,0,0] op_sel_hi:[1,1,1]
	v_pk_fma_f32 v[58:59], v[208:209], v[90:91], v[58:59] op_sel:[1,0,0] op_sel_hi:[1,1,1]
	v_pk_fma_f32 v[60:61], v[208:209], v[92:93], v[60:61] op_sel:[1,0,0] op_sel_hi:[1,1,1]
	v_pk_fma_f32 v[62:63], v[208:209], v[94:95], v[62:63] op_sel:[1,0,0] op_sel_hi:[1,1,1]
	s_waitcnt vmcnt(17)
	v_cvt_scalef32_pk32_f32_fp6 v[64:95], v[168:173], 1.0
	v_pk_fma_f32 v[0:1], v[210:211], v[64:65], v[0:1] op_sel_hi:[0,1,1]
	v_pk_fma_f32 v[2:3], v[210:211], v[66:67], v[2:3] op_sel_hi:[0,1,1]
	v_pk_fma_f32 v[4:5], v[210:211], v[68:69], v[4:5] op_sel_hi:[0,1,1]
	v_pk_fma_f32 v[6:7], v[210:211], v[70:71], v[6:7] op_sel_hi:[0,1,1]
	v_pk_fma_f32 v[8:9], v[210:211], v[72:73], v[8:9] op_sel_hi:[0,1,1]
	v_pk_fma_f32 v[10:11], v[210:211], v[74:75], v[10:11] op_sel_hi:[0,1,1]
	v_pk_fma_f32 v[12:13], v[210:211], v[76:77], v[12:13] op_sel_hi:[0,1,1]
	v_pk_fma_f32 v[14:15], v[210:211], v[78:79], v[14:15] op_sel_hi:[0,1,1]
	v_pk_fma_f32 v[16:17], v[210:211], v[80:81], v[16:17] op_sel_hi:[0,1,1]
	v_pk_fma_f32 v[18:19], v[210:211], v[82:83], v[18:19] op_sel_hi:[0,1,1]
	v_pk_fma_f32 v[20:21], v[210:211], v[84:85], v[20:21] op_sel_hi:[0,1,1]
	v_pk_fma_f32 v[22:23], v[210:211], v[86:87], v[22:23] op_sel_hi:[0,1,1]
	v_pk_fma_f32 v[24:25], v[210:211], v[88:89], v[24:25] op_sel_hi:[0,1,1]
	v_pk_fma_f32 v[26:27], v[210:211], v[90:91], v[26:27] op_sel_hi:[0,1,1]
	v_pk_fma_f32 v[28:29], v[210:211], v[92:93], v[28:29] op_sel_hi:[0,1,1]
	v_pk_fma_f32 v[30:31], v[210:211], v[94:95], v[30:31] op_sel_hi:[0,1,1]
	v_cvt_scalef32_pk32_f32_fp6 v[64:95], v[174:179], 1.0
	v_pk_fma_f32 v[32:33], v[210:211], v[64:65], v[32:33] op_sel_hi:[0,1,1]
	v_pk_fma_f32 v[34:35], v[210:211], v[66:67], v[34:35] op_sel_hi:[0,1,1]
	v_pk_fma_f32 v[36:37], v[210:211], v[68:69], v[36:37] op_sel_hi:[0,1,1]
	v_pk_fma_f32 v[38:39], v[210:211], v[70:71], v[38:39] op_sel_hi:[0,1,1]
	v_pk_fma_f32 v[40:41], v[210:211], v[72:73], v[40:41] op_sel_hi:[0,1,1]
	v_pk_fma_f32 v[42:43], v[210:211], v[74:75], v[42:43] op_sel_hi:[0,1,1]
	v_pk_fma_f32 v[44:45], v[210:211], v[76:77], v[44:45] op_sel_hi:[0,1,1]
	v_pk_fma_f32 v[46:47], v[210:211], v[78:79], v[46:47] op_sel_hi:[0,1,1]
	v_pk_fma_f32 v[48:49], v[210:211], v[80:81], v[48:49] op_sel_hi:[0,1,1]
	v_pk_fma_f32 v[50:51], v[210:211], v[82:83], v[50:51] op_sel_hi:[0,1,1]
	v_pk_fma_f32 v[52:53], v[210:211], v[84:85], v[52:53] op_sel_hi:[0,1,1]
	v_pk_fma_f32 v[54:55], v[210:211], v[86:87], v[54:55] op_sel_hi:[0,1,1]
	v_pk_fma_f32 v[56:57], v[210:211], v[88:89], v[56:57] op_sel_hi:[0,1,1]
	v_pk_fma_f32 v[58:59], v[210:211], v[90:91], v[58:59] op_sel_hi:[0,1,1]
	v_pk_fma_f32 v[60:61], v[210:211], v[92:93], v[60:61] op_sel_hi:[0,1,1]
	v_pk_fma_f32 v[62:63], v[210:211], v[94:95], v[62:63] op_sel_hi:[0,1,1]
	s_waitcnt vmcnt(14)
	v_cvt_scalef32_pk32_f32_fp6 v[64:95], v[180:185], 1.0
	v_pk_fma_f32 v[0:1], v[210:211], v[64:65], v[0:1] op_sel:[1,0,0] op_sel_hi:[1,1,1]
	v_pk_fma_f32 v[2:3], v[210:211], v[66:67], v[2:3] op_sel:[1,0,0] op_sel_hi:[1,1,1]
	v_pk_fma_f32 v[4:5], v[210:211], v[68:69], v[4:5] op_sel:[1,0,0] op_sel_hi:[1,1,1]
	v_pk_fma_f32 v[6:7], v[210:211], v[70:71], v[6:7] op_sel:[1,0,0] op_sel_hi:[1,1,1]
	v_pk_fma_f32 v[8:9], v[210:211], v[72:73], v[8:9] op_sel:[1,0,0] op_sel_hi:[1,1,1]
	v_pk_fma_f32 v[10:11], v[210:211], v[74:75], v[10:11] op_sel:[1,0,0] op_sel_hi:[1,1,1]
	v_pk_fma_f32 v[12:13], v[210:211], v[76:77], v[12:13] op_sel:[1,0,0] op_sel_hi:[1,1,1]
	v_pk_fma_f32 v[14:15], v[210:211], v[78:79], v[14:15] op_sel:[1,0,0] op_sel_hi:[1,1,1]
	v_pk_fma_f32 v[16:17], v[210:211], v[80:81], v[16:17] op_sel:[1,0,0] op_sel_hi:[1,1,1]
	v_pk_fma_f32 v[18:19], v[210:211], v[82:83], v[18:19] op_sel:[1,0,0] op_sel_hi:[1,1,1]
	v_pk_fma_f32 v[20:21], v[210:211], v[84:85], v[20:21] op_sel:[1,0,0] op_sel_hi:[1,1,1]
	v_pk_fma_f32 v[22:23], v[210:211], v[86:87], v[22:23] op_sel:[1,0,0] op_sel_hi:[1,1,1]
	v_pk_fma_f32 v[24:25], v[210:211], v[88:89], v[24:25] op_sel:[1,0,0] op_sel_hi:[1,1,1]
	v_pk_fma_f32 v[26:27], v[210:211], v[90:91], v[26:27] op_sel:[1,0,0] op_sel_hi:[1,1,1]
	v_pk_fma_f32 v[28:29], v[210:211], v[92:93], v[28:29] op_sel:[1,0,0] op_sel_hi:[1,1,1]
	v_pk_fma_f32 v[30:31], v[210:211], v[94:95], v[30:31] op_sel:[1,0,0] op_sel_hi:[1,1,1]
	v_cvt_scalef32_pk32_f32_fp6 v[64:95], v[186:191], 1.0
	v_pk_fma_f32 v[32:33], v[210:211], v[64:65], v[32:33] op_sel:[1,0,0] op_sel_hi:[1,1,1]
	v_pk_fma_f32 v[34:35], v[210:211], v[66:67], v[34:35] op_sel:[1,0,0] op_sel_hi:[1,1,1]
	v_pk_fma_f32 v[36:37], v[210:211], v[68:69], v[36:37] op_sel:[1,0,0] op_sel_hi:[1,1,1]
	v_pk_fma_f32 v[38:39], v[210:211], v[70:71], v[38:39] op_sel:[1,0,0] op_sel_hi:[1,1,1]
	v_pk_fma_f32 v[40:41], v[210:211], v[72:73], v[40:41] op_sel:[1,0,0] op_sel_hi:[1,1,1]
	v_pk_fma_f32 v[42:43], v[210:211], v[74:75], v[42:43] op_sel:[1,0,0] op_sel_hi:[1,1,1]
	v_pk_fma_f32 v[44:45], v[210:211], v[76:77], v[44:45] op_sel:[1,0,0] op_sel_hi:[1,1,1]
	v_pk_fma_f32 v[46:47], v[210:211], v[78:79], v[46:47] op_sel:[1,0,0] op_sel_hi:[1,1,1]
	v_pk_fma_f32 v[48:49], v[210:211], v[80:81], v[48:49] op_sel:[1,0,0] op_sel_hi:[1,1,1]
	v_pk_fma_f32 v[50:51], v[210:211], v[82:83], v[50:51] op_sel:[1,0,0] op_sel_hi:[1,1,1]
	v_pk_fma_f32 v[52:53], v[210:211], v[84:85], v[52:53] op_sel:[1,0,0] op_sel_hi:[1,1,1]
	v_pk_fma_f32 v[54:55], v[210:211], v[86:87], v[54:55] op_sel:[1,0,0] op_sel_hi:[1,1,1]
	v_pk_fma_f32 v[56:57], v[210:211], v[88:89], v[56:57] op_sel:[1,0,0] op_sel_hi:[1,1,1]
	v_pk_fma_f32 v[58:59], v[210:211], v[90:91], v[58:59] op_sel:[1,0,0] op_sel_hi:[1,1,1]
	v_pk_fma_f32 v[60:61], v[210:211], v[92:93], v[60:61] op_sel:[1,0,0] op_sel_hi:[1,1,1]
	v_pk_fma_f32 v[62:63], v[210:211], v[94:95], v[62:63] op_sel:[1,0,0] op_sel_hi:[1,1,1]
	s_waitcnt lgkmcnt(0)
	v_mad_u32_u24 v196, v196, s100, v219
	v_mad_u32_u24 v197, v197, s100, v219
	v_mad_u32_u24 v198, v198, s100, v219
	v_mad_u32_u24 v199, v199, s100, v219
	global_load_dwordx4 v[144:147], v196, s[4:5]
	global_load_dwordx4 v[148:151], v196, s[4:5] offset:16
	global_load_dwordx4 v[152:155], v196, s[4:5] offset:32
	global_load_dwordx4 v[156:159], v197, s[4:5]
	global_load_dwordx4 v[160:163], v197, s[4:5] offset:16
	global_load_dwordx4 v[164:167], v197, s[4:5] offset:32
	global_load_dwordx4 v[168:171], v198, s[4:5]
	global_load_dwordx4 v[172:175], v198, s[4:5] offset:16
	global_load_dwordx4 v[176:179], v198, s[4:5] offset:32
	global_load_dwordx4 v[180:183], v199, s[4:5]
	global_load_dwordx4 v[184:187], v199, s[4:5] offset:16
	global_load_dwordx4 v[188:191], v199, s[4:5] offset:32
	s_nop 1
	v_permlane32_swap_b32_e32 v0, v32
	v_permlane32_swap_b32_e32 v1, v33
	v_permlane32_swap_b32_e32 v2, v34
	v_permlane32_swap_b32_e32 v3, v35
	v_permlane32_swap_b32_e32 v4, v36
	v_permlane32_swap_b32_e32 v5, v37
	v_permlane32_swap_b32_e32 v6, v38
	v_permlane32_swap_b32_e32 v7, v39
	v_permlane32_swap_b32_e32 v8, v40
	v_permlane32_swap_b32_e32 v9, v41
	v_permlane32_swap_b32_e32 v10, v42
	v_permlane32_swap_b32_e32 v11, v43
	v_permlane32_swap_b32_e32 v12, v44
	v_permlane32_swap_b32_e32 v13, v45
	v_permlane32_swap_b32_e32 v14, v46
	v_permlane32_swap_b32_e32 v15, v47
	v_permlane32_swap_b32_e32 v16, v48
	v_permlane32_swap_b32_e32 v17, v49
	v_permlane32_swap_b32_e32 v18, v50
	v_permlane32_swap_b32_e32 v19, v51
	v_permlane32_swap_b32_e32 v20, v52
	v_permlane32_swap_b32_e32 v21, v53
	v_permlane32_swap_b32_e32 v22, v54
	v_permlane32_swap_b32_e32 v23, v55
	v_permlane32_swap_b32_e32 v24, v56
	v_permlane32_swap_b32_e32 v25, v57
	v_permlane32_swap_b32_e32 v26, v58
	v_permlane32_swap_b32_e32 v27, v59
	v_permlane32_swap_b32_e32 v28, v60
	v_permlane32_swap_b32_e32 v29, v61
	v_permlane32_swap_b32_e32 v30, v62
	v_permlane32_swap_b32_e32 v31, v63
	v_pk_add_f32 v[0:1], v[0:1], v[32:33]
	v_pk_add_f32 v[2:3], v[2:3], v[34:35]
	v_pk_add_f32 v[4:5], v[4:5], v[36:37]
	v_pk_add_f32 v[6:7], v[6:7], v[38:39]
	v_pk_add_f32 v[8:9], v[8:9], v[40:41]
	v_pk_add_f32 v[10:11], v[10:11], v[42:43]
	v_pk_add_f32 v[12:13], v[12:13], v[44:45]
	v_pk_add_f32 v[14:15], v[14:15], v[46:47]
	v_pk_add_f32 v[16:17], v[16:17], v[48:49]
	v_pk_add_f32 v[18:19], v[18:19], v[50:51]
	v_pk_add_f32 v[20:21], v[20:21], v[52:53]
	v_pk_add_f32 v[22:23], v[22:23], v[54:55]
	v_pk_add_f32 v[24:25], v[24:25], v[56:57]
	v_pk_add_f32 v[26:27], v[26:27], v[58:59]
	v_pk_add_f32 v[28:29], v[28:29], v[60:61]
	v_pk_add_f32 v[30:31], v[30:31], v[62:63]
	s_nop 1
	v_permlane16_swap_b32_e32 v0, v16
	v_permlane16_swap_b32_e32 v1, v17
	v_permlane16_swap_b32_e32 v2, v18
	v_permlane16_swap_b32_e32 v3, v19
	v_permlane16_swap_b32_e32 v4, v20
	v_permlane16_swap_b32_e32 v5, v21
	v_permlane16_swap_b32_e32 v6, v22
	v_permlane16_swap_b32_e32 v7, v23
	v_permlane16_swap_b32_e32 v8, v24
	v_permlane16_swap_b32_e32 v9, v25
	v_permlane16_swap_b32_e32 v10, v26
	v_permlane16_swap_b32_e32 v11, v27
	v_permlane16_swap_b32_e32 v12, v28
	v_permlane16_swap_b32_e32 v13, v29
	v_permlane16_swap_b32_e32 v14, v30
	v_permlane16_swap_b32_e32 v15, v31
	v_pk_add_f32 v[0:1], v[0:1], v[16:17]
	v_pk_add_f32 v[2:3], v[2:3], v[18:19]
	v_pk_add_f32 v[4:5], v[4:5], v[20:21]
	v_pk_add_f32 v[6:7], v[6:7], v[22:23]
	v_pk_add_f32 v[8:9], v[8:9], v[24:25]
	v_pk_add_f32 v[10:11], v[10:11], v[26:27]
	v_pk_add_f32 v[12:13], v[12:13], v[28:29]
	v_pk_add_f32 v[14:15], v[14:15], v[30:31]
	s_nop 1
	v_add_f32_dpp v0, v0, v0 row_ror:8 row_mask:0xf bank_mask:0x3
	v_add_f32_dpp v1, v1, v1 row_ror:8 row_mask:0xf bank_mask:0x3
	v_add_f32_dpp v2, v2, v2 row_ror:8 row_mask:0xf bank_mask:0x3
	v_add_f32_dpp v3, v3, v3 row_ror:8 row_mask:0xf bank_mask:0x3
	v_add_f32_dpp v4, v4, v4 row_ror:8 row_mask:0xf bank_mask:0x3
	v_add_f32_dpp v5, v5, v5 row_ror:8 row_mask:0xf bank_mask:0x3
	v_add_f32_dpp v6, v6, v6 row_ror:8 row_mask:0xf bank_mask:0x3
	v_add_f32_dpp v7, v7, v7 row_ror:8 row_mask:0xf bank_mask:0x3
	v_add_f32_dpp v0, v8, v8 row_ror:8 row_mask:0xf bank_mask:0xc
	v_add_f32_dpp v1, v9, v9 row_ror:8 row_mask:0xf bank_mask:0xc
	v_add_f32_dpp v2, v10, v10 row_ror:8 row_mask:0xf bank_mask:0xc
	v_add_f32_dpp v3, v11, v11 row_ror:8 row_mask:0xf bank_mask:0xc
	v_add_f32_dpp v4, v12, v12 row_ror:8 row_mask:0xf bank_mask:0xc
	v_add_f32_dpp v5, v13, v13 row_ror:8 row_mask:0xf bank_mask:0xc
	v_add_f32_dpp v6, v14, v14 row_ror:8 row_mask:0xf bank_mask:0xc
	v_add_f32_dpp v7, v15, v15 row_ror:8 row_mask:0xf bank_mask:0xc
	s_mov_b32 vcc_lo, 0xaaaaaaaa
	s_mov_b32 vcc_hi, 0xaaaaaaaa
	v_cndmask_b32_e32 v64, v0, v4, vcc
	v_cndmask_b32_e32 v65, v1, v5, vcc
	v_cndmask_b32_e32 v66, v2, v6, vcc
	v_cndmask_b32_e32 v67, v3, v7, vcc
	v_cndmask_b32_e32 v68, v4, v0, vcc
	v_cndmask_b32_e32 v69, v5, v1, vcc
	v_cndmask_b32_e32 v70, v6, v2, vcc
	v_cndmask_b32_e32 v71, v7, v3, vcc
	s_nop 1
	v_add_f32_dpp v0, v68, v64 quad_perm:[1,0,3,2] row_mask:0xf bank_mask:0xf
	v_add_f32_dpp v1, v69, v65 quad_perm:[1,0,3,2] row_mask:0xf bank_mask:0xf
	v_add_f32_dpp v2, v70, v66 quad_perm:[1,0,3,2] row_mask:0xf bank_mask:0xf
	v_add_f32_dpp v3, v71, v67 quad_perm:[1,0,3,2] row_mask:0xf bank_mask:0xf
	s_waitcnt vmcnt(24)
	v_pk_add_f32 v[212:213], v[212:213], v[0:1]
	v_pk_add_f32 v[214:215], v[214:215], v[2:3]
	global_store_dwordx4 v220, v[212:215], s[8:9]
	s_add_u32 s14, s14, 1
	s_and_b32 s14, s14, 63
	s_add_u32 s18, s14, 1
	s_and_b32 s98, s18, 63
	s_mov_b32 s100, s98
	s_and_b32 s19, s100, 15
	s_lshr_b32 s98, s100, 4
	s_lshl_b32 s99, s19, 9
	s_mul_i32 s15, s19, s16
	s_lshl_b32 s18, s98, 7
	s_add_u32 s15, s15, s18
	s_lshl_b32 s18, s101, 12
	s_add_u32 s15, s15, s18
	s_add_u32 s8, s24, s15
	s_addc_u32 s9, s25, 0
	s_mul_i32 s15, s98, 0x300000
	s_add_u32 s4, s26, 0x3800000
	s_addc_u32 s5, s27, 0
	s_add_u32 s4, s4, s15
	s_addc_u32 s5, s5, 0
	v_add_u32_e32 v221, s99, v217
	v_add_u32_e32 v223, s99, v218
	s_movk_i32 s100, 0xc0
	ds_read2_b32 v[192:193], v221 offset0:0 offset1:16
	ds_read2_b32 v[194:195], v221 offset0:32 offset1:48
	global_load_dwordx4 v[212:215], v220, s[10:11]
	ds_read2_b32 v[208:209], v224 offset0:64 offset1:80
	ds_read2_b32 v[210:211], v224 offset0:96 offset1:112
	s_waitcnt vmcnt(23)
	v_cvt_scalef32_pk32_f32_fp6 v[64:95], v[96:101], 1.0
	v_pk_mul_f32 v[0:1], v[200:201], v[64:65] op_sel_hi:[0,1]
	v_pk_mul_f32 v[2:3], v[200:201], v[66:67] op_sel_hi:[0,1]
	v_pk_mul_f32 v[4:5], v[200:201], v[68:69] op_sel_hi:[0,1]
	v_pk_mul_f32 v[6:7], v[200:201], v[70:71] op_sel_hi:[0,1]
	v_pk_mul_f32 v[8:9], v[200:201], v[72:73] op_sel_hi:[0,1]
	v_pk_mul_f32 v[10:11], v[200:201], v[74:75] op_sel_hi:[0,1]
	v_pk_mul_f32 v[12:13], v[200:201], v[76:77] op_sel_hi:[0,1]
	v_pk_mul_f32 v[14:15], v[200:201], v[78:79] op_sel_hi:[0,1]
	v_pk_mul_f32 v[16:17], v[200:201], v[80:81] op_sel_hi:[0,1]
	v_pk_mul_f32 v[18:19], v[200:201], v[82:83] op_sel_hi:[0,1]
	v_pk_mul_f32 v[20:21], v[200:201], v[84:85] op_sel_hi:[0,1]
	v_pk_mul_f32 v[22:23], v[200:201], v[86:87] op_sel_hi:[0,1]
	v_pk_mul_f32 v[24:25], v[200:201], v[88:89] op_sel_hi:[0,1]
	v_pk_mul_f32 v[26:27], v[200:201], v[90:91] op_sel_hi:[0,1]
	v_pk_mul_f32 v[28:29], v[200:201], v[92:93] op_sel_hi:[0,1]
	v_pk_mul_f32 v[30:31], v[200:201], v[94:95] op_sel_hi:[0,1]
	v_cvt_scalef32_pk32_f32_fp6 v[64:95], v[102:107], 1.0
	v_pk_mul_f32 v[32:33], v[200:201], v[64:65] op_sel_hi:[0,1]
	v_pk_mul_f32 v[34:35], v[200:201], v[66:67] op_sel_hi:[0,1]
	v_pk_mul_f32 v[36:37], v[200:201], v[68:69] op_sel_hi:[0,1]
	v_pk_mul_f32 v[38:39], v[200:201], v[70:71] op_sel_hi:[0,1]
	v_pk_mul_f32 v[40:41], v[200:201], v[72:73] op_sel_hi:[0,1]
	v_pk_mul_f32 v[42:43], v[200:201], v[74:75] op_sel_hi:[0,1]
	v_pk_mul_f32 v[44:45], v[200:201], v[76:77] op_sel_hi:[0,1]
	v_pk_mul_f32 v[46:47], v[200:201], v[78:79] op_sel_hi:[0,1]
	v_pk_mul_f32 v[48:49], v[200:201], v[80:81] op_sel_hi:[0,1]
	v_pk_mul_f32 v[50:51], v[200:201], v[82:83] op_sel_hi:[0,1]
	v_pk_mul_f32 v[52:53], v[200:201], v[84:85] op_sel_hi:[0,1]
	v_pk_mul_f32 v[54:55], v[200:201], v[86:87] op_sel_hi:[0,1]
	v_pk_mul_f32 v[56:57], v[200:201], v[88:89] op_sel_hi:[0,1]
	v_pk_mul_f32 v[58:59], v[200:201], v[90:91] op_sel_hi:[0,1]
	v_pk_mul_f32 v[60:61], v[200:201], v[92:93] op_sel_hi:[0,1]
	v_pk_mul_f32 v[62:63], v[200:201], v[94:95] op_sel_hi:[0,1]
	s_waitcnt vmcnt(20)
	v_cvt_scalef32_pk32_f32_fp6 v[64:95], v[108:113], 1.0
	v_pk_fma_f32 v[0:1], v[200:201], v[64:65], v[0:1] op_sel:[1,0,0] op_sel_hi:[1,1,1]
	v_pk_fma_f32 v[2:3], v[200:201], v[66:67], v[2:3] op_sel:[1,0,0] op_sel_hi:[1,1,1]
	v_pk_fma_f32 v[4:5], v[200:201], v[68:69], v[4:5] op_sel:[1,0,0] op_sel_hi:[1,1,1]
	v_pk_fma_f32 v[6:7], v[200:201], v[70:71], v[6:7] op_sel:[1,0,0] op_sel_hi:[1,1,1]
	v_pk_fma_f32 v[8:9], v[200:201], v[72:73], v[8:9] op_sel:[1,0,0] op_sel_hi:[1,1,1]
	v_pk_fma_f32 v[10:11], v[200:201], v[74:75], v[10:11] op_sel:[1,0,0] op_sel_hi:[1,1,1]
	v_pk_fma_f32 v[12:13], v[200:201], v[76:77], v[12:13] op_sel:[1,0,0] op_sel_hi:[1,1,1]
	v_pk_fma_f32 v[14:15], v[200:201], v[78:79], v[14:15] op_sel:[1,0,0] op_sel_hi:[1,1,1]
	v_pk_fma_f32 v[16:17], v[200:201], v[80:81], v[16:17] op_sel:[1,0,0] op_sel_hi:[1,1,1]
	v_pk_fma_f32 v[18:19], v[200:201], v[82:83], v[18:19] op_sel:[1,0,0] op_sel_hi:[1,1,1]
	v_pk_fma_f32 v[20:21], v[200:201], v[84:85], v[20:21] op_sel:[1,0,0] op_sel_hi:[1,1,1]
	v_pk_fma_f32 v[22:23], v[200:201], v[86:87], v[22:23] op_sel:[1,0,0] op_sel_hi:[1,1,1]
	v_pk_fma_f32 v[24:25], v[200:201], v[88:89], v[24:25] op_sel:[1,0,0] op_sel_hi:[1,1,1]
	v_pk_fma_f32 v[26:27], v[200:201], v[90:91], v[26:27] op_sel:[1,0,0] op_sel_hi:[1,1,1]
	v_pk_fma_f32 v[28:29], v[200:201], v[92:93], v[28:29] op_sel:[1,0,0] op_sel_hi:[1,1,1]
	v_pk_fma_f32 v[30:31], v[200:201], v[94:95], v[30:31] op_sel:[1,0,0] op_sel_hi:[1,1,1]
	v_cvt_scalef32_pk32_f32_fp6 v[64:95], v[114:119], 1.0
	v_pk_fma_f32 v[32:33], v[200:201], v[64:65], v[32:33] op_sel:[1,0,0] op_sel_hi:[1,1,1]
	v_pk_fma_f32 v[34:35], v[200:201], v[66:67], v[34:35] op_sel:[1,0,0] op_sel_hi:[1,1,1]
	v_pk_fma_f32 v[36:37], v[200:201], v[68:69], v[36:37] op_sel:[1,0,0] op_sel_hi:[1,1,1]
	v_pk_fma_f32 v[38:39], v[200:201], v[70:71], v[38:39] op_sel:[1,0,0] op_sel_hi:[1,1,1]
	v_pk_fma_f32 v[40:41], v[200:201], v[72:73], v[40:41] op_sel:[1,0,0] op_sel_hi:[1,1,1]
	v_pk_fma_f32 v[42:43], v[200:201], v[74:75], v[42:43] op_sel:[1,0,0] op_sel_hi:[1,1,1]
	v_pk_fma_f32 v[44:45], v[200:201], v[76:77], v[44:45] op_sel:[1,0,0] op_sel_hi:[1,1,1]
	v_pk_fma_f32 v[46:47], v[200:201], v[78:79], v[46:47] op_sel:[1,0,0] op_sel_hi:[1,1,1]
	v_pk_fma_f32 v[48:49], v[200:201], v[80:81], v[48:49] op_sel:[1,0,0] op_sel_hi:[1,1,1]
	v_pk_fma_f32 v[50:51], v[200:201], v[82:83], v[50:51] op_sel:[1,0,0] op_sel_hi:[1,1,1]
	v_pk_fma_f32 v[52:53], v[200:201], v[84:85], v[52:53] op_sel:[1,0,0] op_sel_hi:[1,1,1]
	v_pk_fma_f32 v[54:55], v[200:201], v[86:87], v[54:55] op_sel:[1,0,0] op_sel_hi:[1,1,1]
	v_pk_fma_f32 v[56:57], v[200:201], v[88:89], v[56:57] op_sel:[1,0,0] op_sel_hi:[1,1,1]
	v_pk_fma_f32 v[58:59], v[200:201], v[90:91], v[58:59] op_sel:[1,0,0] op_sel_hi:[1,1,1]
	v_pk_fma_f32 v[60:61], v[200:201], v[92:93], v[60:61] op_sel:[1,0,0] op_sel_hi:[1,1,1]
	v_pk_fma_f32 v[62:63], v[200:201], v[94:95], v[62:63] op_sel:[1,0,0] op_sel_hi:[1,1,1]
	s_waitcnt vmcnt(17)
	v_cvt_scalef32_pk32_f32_fp6 v[64:95], v[120:125], 1.0
	v_pk_fma_f32 v[0:1], v[202:203], v[64:65], v[0:1] op_sel_hi:[0,1,1]
	v_pk_fma_f32 v[2:3], v[202:203], v[66:67], v[2:3] op_sel_hi:[0,1,1]
	v_pk_fma_f32 v[4:5], v[202:203], v[68:69], v[4:5] op_sel_hi:[0,1,1]
	v_pk_fma_f32 v[6:7], v[202:203], v[70:71], v[6:7] op_sel_hi:[0,1,1]
	v_pk_fma_f32 v[8:9], v[202:203], v[72:73], v[8:9] op_sel_hi:[0,1,1]
	v_pk_fma_f32 v[10:11], v[202:203], v[74:75], v[10:11] op_sel_hi:[0,1,1]
	v_pk_fma_f32 v[12:13], v[202:203], v[76:77], v[12:13] op_sel_hi:[0,1,1]
	v_pk_fma_f32 v[14:15], v[202:203], v[78:79], v[14:15] op_sel_hi:[0,1,1]
	v_pk_fma_f32 v[16:17], v[202:203], v[80:81], v[16:17] op_sel_hi:[0,1,1]
	v_pk_fma_f32 v[18:19], v[202:203], v[82:83], v[18:19] op_sel_hi:[0,1,1]
	v_pk_fma_f32 v[20:21], v[202:203], v[84:85], v[20:21] op_sel_hi:[0,1,1]
	v_pk_fma_f32 v[22:23], v[202:203], v[86:87], v[22:23] op_sel_hi:[0,1,1]
	v_pk_fma_f32 v[24:25], v[202:203], v[88:89], v[24:25] op_sel_hi:[0,1,1]
	v_pk_fma_f32 v[26:27], v[202:203], v[90:91], v[26:27] op_sel_hi:[0,1,1]
	v_pk_fma_f32 v[28:29], v[202:203], v[92:93], v[28:29] op_sel_hi:[0,1,1]
	v_pk_fma_f32 v[30:31], v[202:203], v[94:95], v[30:31] op_sel_hi:[0,1,1]
	v_cvt_scalef32_pk32_f32_fp6 v[64:95], v[126:131], 1.0
	v_pk_fma_f32 v[32:33], v[202:203], v[64:65], v[32:33] op_sel_hi:[0,1,1]
	v_pk_fma_f32 v[34:35], v[202:203], v[66:67], v[34:35] op_sel_hi:[0,1,1]
	v_pk_fma_f32 v[36:37], v[202:203], v[68:69], v[36:37] op_sel_hi:[0,1,1]
	v_pk_fma_f32 v[38:39], v[202:203], v[70:71], v[38:39] op_sel_hi:[0,1,1]
	v_pk_fma_f32 v[40:41], v[202:203], v[72:73], v[40:41] op_sel_hi:[0,1,1]
	v_pk_fma_f32 v[42:43], v[202:203], v[74:75], v[42:43] op_sel_hi:[0,1,1]
	v_pk_fma_f32 v[44:45], v[202:203], v[76:77], v[44:45] op_sel_hi:[0,1,1]
	v_pk_fma_f32 v[46:47], v[202:203], v[78:79], v[46:47] op_sel_hi:[0,1,1]
	v_pk_fma_f32 v[48:49], v[202:203], v[80:81], v[48:49] op_sel_hi:[0,1,1]
	v_pk_fma_f32 v[50:51], v[202:203], v[82:83], v[50:51] op_sel_hi:[0,1,1]
	v_pk_fma_f32 v[52:53], v[202:203], v[84:85], v[52:53] op_sel_hi:[0,1,1]
	v_pk_fma_f32 v[54:55], v[202:203], v[86:87], v[54:55] op_sel_hi:[0,1,1]
	v_pk_fma_f32 v[56:57], v[202:203], v[88:89], v[56:57] op_sel_hi:[0,1,1]
	v_pk_fma_f32 v[58:59], v[202:203], v[90:91], v[58:59] op_sel_hi:[0,1,1]
	v_pk_fma_f32 v[60:61], v[202:203], v[92:93], v[60:61] op_sel_hi:[0,1,1]
	v_pk_fma_f32 v[62:63], v[202:203], v[94:95], v[62:63] op_sel_hi:[0,1,1]
	s_waitcnt vmcnt(14)
	v_cvt_scalef32_pk32_f32_fp6 v[64:95], v[132:137], 1.0
	v_pk_fma_f32 v[0:1], v[202:203], v[64:65], v[0:1] op_sel:[1,0,0] op_sel_hi:[1,1,1]
	v_pk_fma_f32 v[2:3], v[202:203], v[66:67], v[2:3] op_sel:[1,0,0] op_sel_hi:[1,1,1]
	v_pk_fma_f32 v[4:5], v[202:203], v[68:69], v[4:5] op_sel:[1,0,0] op_sel_hi:[1,1,1]
	v_pk_fma_f32 v[6:7], v[202:203], v[70:71], v[6:7] op_sel:[1,0,0] op_sel_hi:[1,1,1]
	v_pk_fma_f32 v[8:9], v[202:203], v[72:73], v[8:9] op_sel:[1,0,0] op_sel_hi:[1,1,1]
	v_pk_fma_f32 v[10:11], v[202:203], v[74:75], v[10:11] op_sel:[1,0,0] op_sel_hi:[1,1,1]
	v_pk_fma_f32 v[12:13], v[202:203], v[76:77], v[12:13] op_sel:[1,0,0] op_sel_hi:[1,1,1]
	v_pk_fma_f32 v[14:15], v[202:203], v[78:79], v[14:15] op_sel:[1,0,0] op_sel_hi:[1,1,1]
	v_pk_fma_f32 v[16:17], v[202:203], v[80:81], v[16:17] op_sel:[1,0,0] op_sel_hi:[1,1,1]
	v_pk_fma_f32 v[18:19], v[202:203], v[82:83], v[18:19] op_sel:[1,0,0] op_sel_hi:[1,1,1]
	v_pk_fma_f32 v[20:21], v[202:203], v[84:85], v[20:21] op_sel:[1,0,0] op_sel_hi:[1,1,1]
	v_pk_fma_f32 v[22:23], v[202:203], v[86:87], v[22:23] op_sel:[1,0,0] op_sel_hi:[1,1,1]
	v_pk_fma_f32 v[24:25], v[202:203], v[88:89], v[24:25] op_sel:[1,0,0] op_sel_hi:[1,1,1]
	v_pk_fma_f32 v[26:27], v[202:203], v[90:91], v[26:27] op_sel:[1,0,0] op_sel_hi:[1,1,1]
	v_pk_fma_f32 v[28:29], v[202:203], v[92:93], v[28:29] op_sel:[1,0,0] op_sel_hi:[1,1,1]
	v_pk_fma_f32 v[30:31], v[202:203], v[94:95], v[30:31] op_sel:[1,0,0] op_sel_hi:[1,1,1]
	v_cvt_scalef32_pk32_f32_fp6 v[64:95], v[138:143], 1.0
	v_pk_fma_f32 v[32:33], v[202:203], v[64:65], v[32:33] op_sel:[1,0,0] op_sel_hi:[1,1,1]
	v_pk_fma_f32 v[34:35], v[202:203], v[66:67], v[34:35] op_sel:[1,0,0] op_sel_hi:[1,1,1]
	v_pk_fma_f32 v[36:37], v[202:203], v[68:69], v[36:37] op_sel:[1,0,0] op_sel_hi:[1,1,1]
	v_pk_fma_f32 v[38:39], v[202:203], v[70:71], v[38:39] op_sel:[1,0,0] op_sel_hi:[1,1,1]
	v_pk_fma_f32 v[40:41], v[202:203], v[72:73], v[40:41] op_sel:[1,0,0] op_sel_hi:[1,1,1]
	v_pk_fma_f32 v[42:43], v[202:203], v[74:75], v[42:43] op_sel:[1,0,0] op_sel_hi:[1,1,1]
	v_pk_fma_f32 v[44:45], v[202:203], v[76:77], v[44:45] op_sel:[1,0,0] op_sel_hi:[1,1,1]
	v_pk_fma_f32 v[46:47], v[202:203], v[78:79], v[46:47] op_sel:[1,0,0] op_sel_hi:[1,1,1]
	v_pk_fma_f32 v[48:49], v[202:203], v[80:81], v[48:49] op_sel:[1,0,0] op_sel_hi:[1,1,1]
	v_pk_fma_f32 v[50:51], v[202:203], v[82:83], v[50:51] op_sel:[1,0,0] op_sel_hi:[1,1,1]
	v_pk_fma_f32 v[52:53], v[202:203], v[84:85], v[52:53] op_sel:[1,0,0] op_sel_hi:[1,1,1]
	v_pk_fma_f32 v[54:55], v[202:203], v[86:87], v[54:55] op_sel:[1,0,0] op_sel_hi:[1,1,1]
	v_pk_fma_f32 v[56:57], v[202:203], v[88:89], v[56:57] op_sel:[1,0,0] op_sel_hi:[1,1,1]
	v_pk_fma_f32 v[58:59], v[202:203], v[90:91], v[58:59] op_sel:[1,0,0] op_sel_hi:[1,1,1]
	v_pk_fma_f32 v[60:61], v[202:203], v[92:93], v[60:61] op_sel:[1,0,0] op_sel_hi:[1,1,1]
	v_pk_fma_f32 v[62:63], v[202:203], v[94:95], v[62:63] op_sel:[1,0,0] op_sel_hi:[1,1,1]
	s_waitcnt lgkmcnt(0)
	v_mad_u32_u24 v192, v192, s100, v219
	v_mad_u32_u24 v193, v193, s100, v219
	v_mad_u32_u24 v194, v194, s100, v219
	v_mad_u32_u24 v195, v195, s100, v219
	global_load_dwordx4 v[96:99], v192, s[4:5]
	global_load_dwordx4 v[100:103], v192, s[4:5] offset:16
	global_load_dwordx4 v[104:107], v192, s[4:5] offset:32
	global_load_dwordx4 v[108:111], v193, s[4:5]
	global_load_dwordx4 v[112:115], v193, s[4:5] offset:16
	global_load_dwordx4 v[116:119], v193, s[4:5] offset:32
	global_load_dwordx4 v[120:123], v194, s[4:5]
	global_load_dwordx4 v[124:127], v194, s[4:5] offset:16
	global_load_dwordx4 v[128:131], v194, s[4:5] offset:32
	global_load_dwordx4 v[132:135], v195, s[4:5]
	global_load_dwordx4 v[136:139], v195, s[4:5] offset:16
	global_load_dwordx4 v[140:143], v195, s[4:5] offset:32
	ds_read2_b32 v[196:197], v221 offset0:64 offset1:80
	ds_read2_b32 v[198:199], v221 offset0:96 offset1:112
	ds_read2_b32 v[200:201], v223 offset0:0 offset1:16
	ds_read2_b32 v[202:203], v223 offset0:32 offset1:48
	s_waitcnt vmcnt(23)
	v_cvt_scalef32_pk32_f32_fp6 v[64:95], v[144:149], 1.0
	v_pk_fma_f32 v[0:1], v[208:209], v[64:65], v[0:1] op_sel_hi:[0,1,1]
	v_pk_fma_f32 v[2:3], v[208:209], v[66:67], v[2:3] op_sel_hi:[0,1,1]
	v_pk_fma_f32 v[4:5], v[208:209], v[68:69], v[4:5] op_sel_hi:[0,1,1]
	v_pk_fma_f32 v[6:7], v[208:209], v[70:71], v[6:7] op_sel_hi:[0,1,1]
	v_pk_fma_f32 v[8:9], v[208:209], v[72:73], v[8:9] op_sel_hi:[0,1,1]
	v_pk_fma_f32 v[10:11], v[208:209], v[74:75], v[10:11] op_sel_hi:[0,1,1]
	v_pk_fma_f32 v[12:13], v[208:209], v[76:77], v[12:13] op_sel_hi:[0,1,1]
	v_pk_fma_f32 v[14:15], v[208:209], v[78:79], v[14:15] op_sel_hi:[0,1,1]
	v_pk_fma_f32 v[16:17], v[208:209], v[80:81], v[16:17] op_sel_hi:[0,1,1]
	v_pk_fma_f32 v[18:19], v[208:209], v[82:83], v[18:19] op_sel_hi:[0,1,1]
	v_pk_fma_f32 v[20:21], v[208:209], v[84:85], v[20:21] op_sel_hi:[0,1,1]
	v_pk_fma_f32 v[22:23], v[208:209], v[86:87], v[22:23] op_sel_hi:[0,1,1]
	v_pk_fma_f32 v[24:25], v[208:209], v[88:89], v[24:25] op_sel_hi:[0,1,1]
	v_pk_fma_f32 v[26:27], v[208:209], v[90:91], v[26:27] op_sel_hi:[0,1,1]
	v_pk_fma_f32 v[28:29], v[208:209], v[92:93], v[28:29] op_sel_hi:[0,1,1]
	v_pk_fma_f32 v[30:31], v[208:209], v[94:95], v[30:31] op_sel_hi:[0,1,1]
	v_cvt_scalef32_pk32_f32_fp6 v[64:95], v[150:155], 1.0
	v_pk_fma_f32 v[32:33], v[208:209], v[64:65], v[32:33] op_sel_hi:[0,1,1]
	v_pk_fma_f32 v[34:35], v[208:209], v[66:67], v[34:35] op_sel_hi:[0,1,1]
	v_pk_fma_f32 v[36:37], v[208:209], v[68:69], v[36:37] op_sel_hi:[0,1,1]
	v_pk_fma_f32 v[38:39], v[208:209], v[70:71], v[38:39] op_sel_hi:[0,1,1]
	v_pk_fma_f32 v[40:41], v[208:209], v[72:73], v[40:41] op_sel_hi:[0,1,1]
	v_pk_fma_f32 v[42:43], v[208:209], v[74:75], v[42:43] op_sel_hi:[0,1,1]
	v_pk_fma_f32 v[44:45], v[208:209], v[76:77], v[44:45] op_sel_hi:[0,1,1]
	v_pk_fma_f32 v[46:47], v[208:209], v[78:79], v[46:47] op_sel_hi:[0,1,1]
	v_pk_fma_f32 v[48:49], v[208:209], v[80:81], v[48:49] op_sel_hi:[0,1,1]
	v_pk_fma_f32 v[50:51], v[208:209], v[82:83], v[50:51] op_sel_hi:[0,1,1]
	v_pk_fma_f32 v[52:53], v[208:209], v[84:85], v[52:53] op_sel_hi:[0,1,1]
	v_pk_fma_f32 v[54:55], v[208:209], v[86:87], v[54:55] op_sel_hi:[0,1,1]
	v_pk_fma_f32 v[56:57], v[208:209], v[88:89], v[56:57] op_sel_hi:[0,1,1]
	v_pk_fma_f32 v[58:59], v[208:209], v[90:91], v[58:59] op_sel_hi:[0,1,1]
	v_pk_fma_f32 v[60:61], v[208:209], v[92:93], v[60:61] op_sel_hi:[0,1,1]
	v_pk_fma_f32 v[62:63], v[208:209], v[94:95], v[62:63] op_sel_hi:[0,1,1]
	s_waitcnt vmcnt(20)
	v_cvt_scalef32_pk32_f32_fp6 v[64:95], v[156:161], 1.0
	v_pk_fma_f32 v[0:1], v[208:209], v[64:65], v[0:1] op_sel:[1,0,0] op_sel_hi:[1,1,1]
	v_pk_fma_f32 v[2:3], v[208:209], v[66:67], v[2:3] op_sel:[1,0,0] op_sel_hi:[1,1,1]
	v_pk_fma_f32 v[4:5], v[208:209], v[68:69], v[4:5] op_sel:[1,0,0] op_sel_hi:[1,1,1]
	v_pk_fma_f32 v[6:7], v[208:209], v[70:71], v[6:7] op_sel:[1,0,0] op_sel_hi:[1,1,1]
	v_pk_fma_f32 v[8:9], v[208:209], v[72:73], v[8:9] op_sel:[1,0,0] op_sel_hi:[1,1,1]
	v_pk_fma_f32 v[10:11], v[208:209], v[74:75], v[10:11] op_sel:[1,0,0] op_sel_hi:[1,1,1]
	v_pk_fma_f32 v[12:13], v[208:209], v[76:77], v[12:13] op_sel:[1,0,0] op_sel_hi:[1,1,1]
	v_pk_fma_f32 v[14:15], v[208:209], v[78:79], v[14:15] op_sel:[1,0,0] op_sel_hi:[1,1,1]
	v_pk_fma_f32 v[16:17], v[208:209], v[80:81], v[16:17] op_sel:[1,0,0] op_sel_hi:[1,1,1]
	v_pk_fma_f32 v[18:19], v[208:209], v[82:83], v[18:19] op_sel:[1,0,0] op_sel_hi:[1,1,1]
	v_pk_fma_f32 v[20:21], v[208:209], v[84:85], v[20:21] op_sel:[1,0,0] op_sel_hi:[1,1,1]
	v_pk_fma_f32 v[22:23], v[208:209], v[86:87], v[22:23] op_sel:[1,0,0] op_sel_hi:[1,1,1]
	v_pk_fma_f32 v[24:25], v[208:209], v[88:89], v[24:25] op_sel:[1,0,0] op_sel_hi:[1,1,1]
	v_pk_fma_f32 v[26:27], v[208:209], v[90:91], v[26:27] op_sel:[1,0,0] op_sel_hi:[1,1,1]
	v_pk_fma_f32 v[28:29], v[208:209], v[92:93], v[28:29] op_sel:[1,0,0] op_sel_hi:[1,1,1]
	v_pk_fma_f32 v[30:31], v[208:209], v[94:95], v[30:31] op_sel:[1,0,0] op_sel_hi:[1,1,1]
	v_cvt_scalef32_pk32_f32_fp6 v[64:95], v[162:167], 1.0
	v_pk_fma_f32 v[32:33], v[208:209], v[64:65], v[32:33] op_sel:[1,0,0] op_sel_hi:[1,1,1]
	v_pk_fma_f32 v[34:35], v[208:209], v[66:67], v[34:35] op_sel:[1,0,0] op_sel_hi:[1,1,1]
	v_pk_fma_f32 v[36:37], v[208:209], v[68:69], v[36:37] op_sel:[1,0,0] op_sel_hi:[1,1,1]
	v_pk_fma_f32 v[38:39], v[208:209], v[70:71], v[38:39] op_sel:[1,0,0] op_sel_hi:[1,1,1]
	v_pk_fma_f32 v[40:41], v[208:209], v[72:73], v[40:41] op_sel:[1,0,0] op_sel_hi:[1,1,1]
	v_pk_fma_f32 v[42:43], v[208:209], v[74:75], v[42:43] op_sel:[1,0,0] op_sel_hi:[1,1,1]
	v_pk_fma_f32 v[44:45], v[208:209], v[76:77], v[44:45] op_sel:[1,0,0] op_sel_hi:[1,1,1]
	v_pk_fma_f32 v[46:47], v[208:209], v[78:79], v[46:47] op_sel:[1,0,0] op_sel_hi:[1,1,1]
	v_pk_fma_f32 v[48:49], v[208:209], v[80:81], v[48:49] op_sel:[1,0,0] op_sel_hi:[1,1,1]
	v_pk_fma_f32 v[50:51], v[208:209], v[82:83], v[50:51] op_sel:[1,0,0] op_sel_hi:[1,1,1]
	v_pk_fma_f32 v[52:53], v[208:209], v[84:85], v[52:53] op_sel:[1,0,0] op_sel_hi:[1,1,1]
	v_pk_fma_f32 v[54:55], v[208:209], v[86:87], v[54:55] op_sel:[1,0,0] op_sel_hi:[1,1,1]
	v_pk_fma_f32 v[56:57], v[208:209], v[88:89], v[56:57] op_sel:[1,0,0] op_sel_hi:[1,1,1]
	v_pk_fma_f32 v[58:59], v[208:209], v[90:91], v[58:59] op_sel:[1,0,0] op_sel_hi:[1,1,1]
	v_pk_fma_f32 v[60:61], v[208:209], v[92:93], v[60:61] op_sel:[1,0,0] op_sel_hi:[1,1,1]
	v_pk_fma_f32 v[62:63], v[208:209], v[94:95], v[62:63] op_sel:[1,0,0] op_sel_hi:[1,1,1]
	s_waitcnt vmcnt(17)
	v_cvt_scalef32_pk32_f32_fp6 v[64:95], v[168:173], 1.0
	v_pk_fma_f32 v[0:1], v[210:211], v[64:65], v[0:1] op_sel_hi:[0,1,1]
	v_pk_fma_f32 v[2:3], v[210:211], v[66:67], v[2:3] op_sel_hi:[0,1,1]
	v_pk_fma_f32 v[4:5], v[210:211], v[68:69], v[4:5] op_sel_hi:[0,1,1]
	v_pk_fma_f32 v[6:7], v[210:211], v[70:71], v[6:7] op_sel_hi:[0,1,1]
	v_pk_fma_f32 v[8:9], v[210:211], v[72:73], v[8:9] op_sel_hi:[0,1,1]
	v_pk_fma_f32 v[10:11], v[210:211], v[74:75], v[10:11] op_sel_hi:[0,1,1]
	v_pk_fma_f32 v[12:13], v[210:211], v[76:77], v[12:13] op_sel_hi:[0,1,1]
	v_pk_fma_f32 v[14:15], v[210:211], v[78:79], v[14:15] op_sel_hi:[0,1,1]
	v_pk_fma_f32 v[16:17], v[210:211], v[80:81], v[16:17] op_sel_hi:[0,1,1]
	v_pk_fma_f32 v[18:19], v[210:211], v[82:83], v[18:19] op_sel_hi:[0,1,1]
	v_pk_fma_f32 v[20:21], v[210:211], v[84:85], v[20:21] op_sel_hi:[0,1,1]
	v_pk_fma_f32 v[22:23], v[210:211], v[86:87], v[22:23] op_sel_hi:[0,1,1]
	v_pk_fma_f32 v[24:25], v[210:211], v[88:89], v[24:25] op_sel_hi:[0,1,1]
	v_pk_fma_f32 v[26:27], v[210:211], v[90:91], v[26:27] op_sel_hi:[0,1,1]
	v_pk_fma_f32 v[28:29], v[210:211], v[92:93], v[28:29] op_sel_hi:[0,1,1]
	v_pk_fma_f32 v[30:31], v[210:211], v[94:95], v[30:31] op_sel_hi:[0,1,1]
	v_cvt_scalef32_pk32_f32_fp6 v[64:95], v[174:179], 1.0
	v_pk_fma_f32 v[32:33], v[210:211], v[64:65], v[32:33] op_sel_hi:[0,1,1]
	v_pk_fma_f32 v[34:35], v[210:211], v[66:67], v[34:35] op_sel_hi:[0,1,1]
	v_pk_fma_f32 v[36:37], v[210:211], v[68:69], v[36:37] op_sel_hi:[0,1,1]
	v_pk_fma_f32 v[38:39], v[210:211], v[70:71], v[38:39] op_sel_hi:[0,1,1]
	v_pk_fma_f32 v[40:41], v[210:211], v[72:73], v[40:41] op_sel_hi:[0,1,1]
	v_pk_fma_f32 v[42:43], v[210:211], v[74:75], v[42:43] op_sel_hi:[0,1,1]
	v_pk_fma_f32 v[44:45], v[210:211], v[76:77], v[44:45] op_sel_hi:[0,1,1]
	v_pk_fma_f32 v[46:47], v[210:211], v[78:79], v[46:47] op_sel_hi:[0,1,1]
	v_pk_fma_f32 v[48:49], v[210:211], v[80:81], v[48:49] op_sel_hi:[0,1,1]
	v_pk_fma_f32 v[50:51], v[210:211], v[82:83], v[50:51] op_sel_hi:[0,1,1]
	v_pk_fma_f32 v[52:53], v[210:211], v[84:85], v[52:53] op_sel_hi:[0,1,1]
	v_pk_fma_f32 v[54:55], v[210:211], v[86:87], v[54:55] op_sel_hi:[0,1,1]
	v_pk_fma_f32 v[56:57], v[210:211], v[88:89], v[56:57] op_sel_hi:[0,1,1]
	v_pk_fma_f32 v[58:59], v[210:211], v[90:91], v[58:59] op_sel_hi:[0,1,1]
	v_pk_fma_f32 v[60:61], v[210:211], v[92:93], v[60:61] op_sel_hi:[0,1,1]
	v_pk_fma_f32 v[62:63], v[210:211], v[94:95], v[62:63] op_sel_hi:[0,1,1]
	s_waitcnt vmcnt(14)
	v_cvt_scalef32_pk32_f32_fp6 v[64:95], v[180:185], 1.0
	v_pk_fma_f32 v[0:1], v[210:211], v[64:65], v[0:1] op_sel:[1,0,0] op_sel_hi:[1,1,1]
	v_pk_fma_f32 v[2:3], v[210:211], v[66:67], v[2:3] op_sel:[1,0,0] op_sel_hi:[1,1,1]
	v_pk_fma_f32 v[4:5], v[210:211], v[68:69], v[4:5] op_sel:[1,0,0] op_sel_hi:[1,1,1]
	v_pk_fma_f32 v[6:7], v[210:211], v[70:71], v[6:7] op_sel:[1,0,0] op_sel_hi:[1,1,1]
	v_pk_fma_f32 v[8:9], v[210:211], v[72:73], v[8:9] op_sel:[1,0,0] op_sel_hi:[1,1,1]
	v_pk_fma_f32 v[10:11], v[210:211], v[74:75], v[10:11] op_sel:[1,0,0] op_sel_hi:[1,1,1]
	v_pk_fma_f32 v[12:13], v[210:211], v[76:77], v[12:13] op_sel:[1,0,0] op_sel_hi:[1,1,1]
	v_pk_fma_f32 v[14:15], v[210:211], v[78:79], v[14:15] op_sel:[1,0,0] op_sel_hi:[1,1,1]
	v_pk_fma_f32 v[16:17], v[210:211], v[80:81], v[16:17] op_sel:[1,0,0] op_sel_hi:[1,1,1]
	v_pk_fma_f32 v[18:19], v[210:211], v[82:83], v[18:19] op_sel:[1,0,0] op_sel_hi:[1,1,1]
	v_pk_fma_f32 v[20:21], v[210:211], v[84:85], v[20:21] op_sel:[1,0,0] op_sel_hi:[1,1,1]
	v_pk_fma_f32 v[22:23], v[210:211], v[86:87], v[22:23] op_sel:[1,0,0] op_sel_hi:[1,1,1]
	v_pk_fma_f32 v[24:25], v[210:211], v[88:89], v[24:25] op_sel:[1,0,0] op_sel_hi:[1,1,1]
	v_pk_fma_f32 v[26:27], v[210:211], v[90:91], v[26:27] op_sel:[1,0,0] op_sel_hi:[1,1,1]
	v_pk_fma_f32 v[28:29], v[210:211], v[92:93], v[28:29] op_sel:[1,0,0] op_sel_hi:[1,1,1]
	v_pk_fma_f32 v[30:31], v[210:211], v[94:95], v[30:31] op_sel:[1,0,0] op_sel_hi:[1,1,1]
	v_cvt_scalef32_pk32_f32_fp6 v[64:95], v[186:191], 1.0
	v_pk_fma_f32 v[32:33], v[210:211], v[64:65], v[32:33] op_sel:[1,0,0] op_sel_hi:[1,1,1]
	v_pk_fma_f32 v[34:35], v[210:211], v[66:67], v[34:35] op_sel:[1,0,0] op_sel_hi:[1,1,1]
	v_pk_fma_f32 v[36:37], v[210:211], v[68:69], v[36:37] op_sel:[1,0,0] op_sel_hi:[1,1,1]
	v_pk_fma_f32 v[38:39], v[210:211], v[70:71], v[38:39] op_sel:[1,0,0] op_sel_hi:[1,1,1]
	v_pk_fma_f32 v[40:41], v[210:211], v[72:73], v[40:41] op_sel:[1,0,0] op_sel_hi:[1,1,1]
	v_pk_fma_f32 v[42:43], v[210:211], v[74:75], v[42:43] op_sel:[1,0,0] op_sel_hi:[1,1,1]
	v_pk_fma_f32 v[44:45], v[210:211], v[76:77], v[44:45] op_sel:[1,0,0] op_sel_hi:[1,1,1]
	v_pk_fma_f32 v[46:47], v[210:211], v[78:79], v[46:47] op_sel:[1,0,0] op_sel_hi:[1,1,1]
	v_pk_fma_f32 v[48:49], v[210:211], v[80:81], v[48:49] op_sel:[1,0,0] op_sel_hi:[1,1,1]
	v_pk_fma_f32 v[50:51], v[210:211], v[82:83], v[50:51] op_sel:[1,0,0] op_sel_hi:[1,1,1]
	v_pk_fma_f32 v[52:53], v[210:211], v[84:85], v[52:53] op_sel:[1,0,0] op_sel_hi:[1,1,1]
	v_pk_fma_f32 v[54:55], v[210:211], v[86:87], v[54:55] op_sel:[1,0,0] op_sel_hi:[1,1,1]
	v_pk_fma_f32 v[56:57], v[210:211], v[88:89], v[56:57] op_sel:[1,0,0] op_sel_hi:[1,1,1]
	v_pk_fma_f32 v[58:59], v[210:211], v[90:91], v[58:59] op_sel:[1,0,0] op_sel_hi:[1,1,1]
	v_pk_fma_f32 v[60:61], v[210:211], v[92:93], v[60:61] op_sel:[1,0,0] op_sel_hi:[1,1,1]
	v_pk_fma_f32 v[62:63], v[210:211], v[94:95], v[62:63] op_sel:[1,0,0] op_sel_hi:[1,1,1]
	s_waitcnt lgkmcnt(0)
	v_mad_u32_u24 v196, v196, s100, v219
	v_mad_u32_u24 v197, v197, s100, v219
	v_mad_u32_u24 v198, v198, s100, v219
	v_mad_u32_u24 v199, v199, s100, v219
	global_load_dwordx4 v[144:147], v196, s[4:5]
	global_load_dwordx4 v[148:151], v196, s[4:5] offset:16
	global_load_dwordx4 v[152:155], v196, s[4:5] offset:32
	global_load_dwordx4 v[156:159], v197, s[4:5]
	global_load_dwordx4 v[160:163], v197, s[4:5] offset:16
	global_load_dwordx4 v[164:167], v197, s[4:5] offset:32
	global_load_dwordx4 v[168:171], v198, s[4:5]
	global_load_dwordx4 v[172:175], v198, s[4:5] offset:16
	global_load_dwordx4 v[176:179], v198, s[4:5] offset:32
	global_load_dwordx4 v[180:183], v199, s[4:5]
	global_load_dwordx4 v[184:187], v199, s[4:5] offset:16
	global_load_dwordx4 v[188:191], v199, s[4:5] offset:32
	s_nop 1
	v_permlane32_swap_b32_e32 v0, v32
	v_permlane32_swap_b32_e32 v1, v33
	v_permlane32_swap_b32_e32 v2, v34
	v_permlane32_swap_b32_e32 v3, v35
	v_permlane32_swap_b32_e32 v4, v36
	v_permlane32_swap_b32_e32 v5, v37
	v_permlane32_swap_b32_e32 v6, v38
	v_permlane32_swap_b32_e32 v7, v39
	v_permlane32_swap_b32_e32 v8, v40
	v_permlane32_swap_b32_e32 v9, v41
	v_permlane32_swap_b32_e32 v10, v42
	v_permlane32_swap_b32_e32 v11, v43
	v_permlane32_swap_b32_e32 v12, v44
	v_permlane32_swap_b32_e32 v13, v45
	v_permlane32_swap_b32_e32 v14, v46
	v_permlane32_swap_b32_e32 v15, v47
	v_permlane32_swap_b32_e32 v16, v48
	v_permlane32_swap_b32_e32 v17, v49
	v_permlane32_swap_b32_e32 v18, v50
	v_permlane32_swap_b32_e32 v19, v51
	v_permlane32_swap_b32_e32 v20, v52
	v_permlane32_swap_b32_e32 v21, v53
	v_permlane32_swap_b32_e32 v22, v54
	v_permlane32_swap_b32_e32 v23, v55
	v_permlane32_swap_b32_e32 v24, v56
	v_permlane32_swap_b32_e32 v25, v57
	v_permlane32_swap_b32_e32 v26, v58
	v_permlane32_swap_b32_e32 v27, v59
	v_permlane32_swap_b32_e32 v28, v60
	v_permlane32_swap_b32_e32 v29, v61
	v_permlane32_swap_b32_e32 v30, v62
	v_permlane32_swap_b32_e32 v31, v63
	v_pk_add_f32 v[0:1], v[0:1], v[32:33]
	v_pk_add_f32 v[2:3], v[2:3], v[34:35]
	v_pk_add_f32 v[4:5], v[4:5], v[36:37]
	v_pk_add_f32 v[6:7], v[6:7], v[38:39]
	v_pk_add_f32 v[8:9], v[8:9], v[40:41]
	v_pk_add_f32 v[10:11], v[10:11], v[42:43]
	v_pk_add_f32 v[12:13], v[12:13], v[44:45]
	v_pk_add_f32 v[14:15], v[14:15], v[46:47]
	v_pk_add_f32 v[16:17], v[16:17], v[48:49]
	v_pk_add_f32 v[18:19], v[18:19], v[50:51]
	v_pk_add_f32 v[20:21], v[20:21], v[52:53]
	v_pk_add_f32 v[22:23], v[22:23], v[54:55]
	v_pk_add_f32 v[24:25], v[24:25], v[56:57]
	v_pk_add_f32 v[26:27], v[26:27], v[58:59]
	v_pk_add_f32 v[28:29], v[28:29], v[60:61]
	v_pk_add_f32 v[30:31], v[30:31], v[62:63]
	s_nop 1
	v_permlane16_swap_b32_e32 v0, v16
	v_permlane16_swap_b32_e32 v1, v17
	v_permlane16_swap_b32_e32 v2, v18
	v_permlane16_swap_b32_e32 v3, v19
	v_permlane16_swap_b32_e32 v4, v20
	v_permlane16_swap_b32_e32 v5, v21
	v_permlane16_swap_b32_e32 v6, v22
	v_permlane16_swap_b32_e32 v7, v23
	v_permlane16_swap_b32_e32 v8, v24
	v_permlane16_swap_b32_e32 v9, v25
	v_permlane16_swap_b32_e32 v10, v26
	v_permlane16_swap_b32_e32 v11, v27
	v_permlane16_swap_b32_e32 v12, v28
	v_permlane16_swap_b32_e32 v13, v29
	v_permlane16_swap_b32_e32 v14, v30
	v_permlane16_swap_b32_e32 v15, v31
	v_pk_add_f32 v[0:1], v[0:1], v[16:17]
	v_pk_add_f32 v[2:3], v[2:3], v[18:19]
	v_pk_add_f32 v[4:5], v[4:5], v[20:21]
	v_pk_add_f32 v[6:7], v[6:7], v[22:23]
	v_pk_add_f32 v[8:9], v[8:9], v[24:25]
	v_pk_add_f32 v[10:11], v[10:11], v[26:27]
	v_pk_add_f32 v[12:13], v[12:13], v[28:29]
	v_pk_add_f32 v[14:15], v[14:15], v[30:31]
	s_nop 1
	v_add_f32_dpp v0, v0, v0 row_ror:8 row_mask:0xf bank_mask:0x3
	v_add_f32_dpp v1, v1, v1 row_ror:8 row_mask:0xf bank_mask:0x3
	v_add_f32_dpp v2, v2, v2 row_ror:8 row_mask:0xf bank_mask:0x3
	v_add_f32_dpp v3, v3, v3 row_ror:8 row_mask:0xf bank_mask:0x3
	v_add_f32_dpp v4, v4, v4 row_ror:8 row_mask:0xf bank_mask:0x3
	v_add_f32_dpp v5, v5, v5 row_ror:8 row_mask:0xf bank_mask:0x3
	v_add_f32_dpp v6, v6, v6 row_ror:8 row_mask:0xf bank_mask:0x3
	v_add_f32_dpp v7, v7, v7 row_ror:8 row_mask:0xf bank_mask:0x3
	v_add_f32_dpp v0, v8, v8 row_ror:8 row_mask:0xf bank_mask:0xc
	v_add_f32_dpp v1, v9, v9 row_ror:8 row_mask:0xf bank_mask:0xc
	v_add_f32_dpp v2, v10, v10 row_ror:8 row_mask:0xf bank_mask:0xc
	v_add_f32_dpp v3, v11, v11 row_ror:8 row_mask:0xf bank_mask:0xc
	v_add_f32_dpp v4, v12, v12 row_ror:8 row_mask:0xf bank_mask:0xc
	v_add_f32_dpp v5, v13, v13 row_ror:8 row_mask:0xf bank_mask:0xc
	v_add_f32_dpp v6, v14, v14 row_ror:8 row_mask:0xf bank_mask:0xc
	v_add_f32_dpp v7, v15, v15 row_ror:8 row_mask:0xf bank_mask:0xc
	s_mov_b32 vcc_lo, 0xaaaaaaaa
	s_mov_b32 vcc_hi, 0xaaaaaaaa
	v_cndmask_b32_e32 v64, v0, v4, vcc
	v_cndmask_b32_e32 v65, v1, v5, vcc
	v_cndmask_b32_e32 v66, v2, v6, vcc
	v_cndmask_b32_e32 v67, v3, v7, vcc
	v_cndmask_b32_e32 v68, v4, v0, vcc
	v_cndmask_b32_e32 v69, v5, v1, vcc
	v_cndmask_b32_e32 v70, v6, v2, vcc
	v_cndmask_b32_e32 v71, v7, v3, vcc
	s_nop 1
	v_add_f32_dpp v0, v68, v64 quad_perm:[1,0,3,2] row_mask:0xf bank_mask:0xf
	v_add_f32_dpp v1, v69, v65 quad_perm:[1,0,3,2] row_mask:0xf bank_mask:0xf
	v_add_f32_dpp v2, v70, v66 quad_perm:[1,0,3,2] row_mask:0xf bank_mask:0xf
	v_add_f32_dpp v3, v71, v67 quad_perm:[1,0,3,2] row_mask:0xf bank_mask:0xf
	s_waitcnt vmcnt(24)
	v_pk_add_f32 v[212:213], v[212:213], v[0:1]
	v_pk_add_f32 v[214:215], v[214:215], v[2:3]
	global_store_dwordx4 v220, v[212:215], s[10:11]
	s_add_u32 s14, s14, 1
	s_and_b32 s14, s14, 63
	s_add_u32 s18, s14, 1
	s_and_b32 s98, s18, 63
	s_mov_b32 s100, s98
	s_and_b32 s19, s100, 15
	s_lshr_b32 s98, s100, 4
	s_lshl_b32 s99, s19, 9
	s_mul_i32 s15, s19, s16
	s_lshl_b32 s18, s98, 7
	s_add_u32 s15, s15, s18
	s_lshl_b32 s18, s101, 12
	s_add_u32 s15, s15, s18
	s_add_u32 s10, s24, s15
	s_addc_u32 s11, s25, 0
	s_mul_i32 s15, s98, 0x300000
	s_add_u32 s4, s26, 0x3800000
	s_addc_u32 s5, s27, 0
	s_add_u32 s4, s4, s15
	s_addc_u32 s5, s5, 0
	v_add_u32_e32 v222, s99, v217
	v_add_u32_e32 v224, s99, v218
	s_movk_i32 s100, 0xc0
	ds_read2_b32 v[192:193], v222 offset0:0 offset1:16
	ds_read2_b32 v[194:195], v222 offset0:32 offset1:48
	s_cmp_lg_u32 s14, 0
	s_cbranch_scc1 .Lgv0_loop
	s_waitcnt vmcnt(0) lgkmcnt(0)
	s_add_u32 s4, s40, 0x1000
	s_addc_u32 s5, s41, 0
	global_load_dwordx4 v[64:67], v229, s[4:5] offset:0
	global_load_dwordx4 v[68:71], v229, s[4:5] offset:1024
	global_load_dwordx4 v[72:75], v229, s[4:5] offset:2048
	global_load_dwordx4 v[76:79], v229, s[4:5] offset:3072
	s_lshl_b32 s15, s101, 12
	s_add_u32 s8, s24, s15
	s_addc_u32 s9, s25, 0
	s_lshl_b32 s15, s101, 11
	s_add_u32 s10, s34, s15
	s_addc_u32 s11, s35, 0
	s_lshl_b32 s18, s92, 13
	v_lshlrev_b32_e32 v146, 3, v228
	v_mov_b32_e32 v147, 0x358637bd
	s_mov_b32 s19, 0x800000
	v_mov_b32_e32 v148, v146
	global_load_dwordx4 v[80:83], v229, s[8:9] offset:0
	global_load_dwordx4 v[84:87], v229, s[8:9] offset:1024
	global_load_dwordx4 v[88:91], v229, s[8:9] offset:2048
	global_load_dwordx4 v[92:95], v229, s[8:9] offset:3072
	s_add_u32 s8, s8, s16
	s_addc_u32 s9, s9, 0
	global_load_dwordx4 v[96:99], v229, s[8:9] offset:0
	global_load_dwordx4 v[100:103], v229, s[8:9] offset:1024
	global_load_dwordx4 v[104:107], v229, s[8:9] offset:2048
	global_load_dwordx4 v[108:111], v229, s[8:9] offset:3072
	s_add_u32 s8, s8, s16
	s_addc_u32 s9, s9, 0
	global_load_dwordx4 v[112:115], v229, s[8:9] offset:0
	global_load_dwordx4 v[116:119], v229, s[8:9] offset:1024
	global_load_dwordx4 v[120:123], v229, s[8:9] offset:2048
	global_load_dwordx4 v[124:127], v229, s[8:9] offset:3072
	s_add_u32 s8, s8, s16
	s_addc_u32 s9, s9, 0
	global_load_dwordx4 v[128:131], v229, s[8:9] offset:0
	global_load_dwordx4 v[132:135], v229, s[8:9] offset:1024
	global_load_dwordx4 v[136:139], v229, s[8:9] offset:2048
	global_load_dwordx4 v[140:143], v229, s[8:9] offset:3072
	s_add_u32 s8, s8, s16
	s_addc_u32 s9, s9, 0
	s_waitcnt vmcnt(0)
	v_mul_f32_e32 v144, v80, v80
	v_fmac_f32_e32 v144, v81, v81
	v_fmac_f32_e32 v144, v82, v82
	v_fmac_f32_e32 v144, v83, v83
	v_fmac_f32_e32 v144, v84, v84
	v_fmac_f32_e32 v144, v85, v85
	v_fmac_f32_e32 v144, v86, v86
	v_fmac_f32_e32 v144, v87, v87
	v_fmac_f32_e32 v144, v88, v88
	v_fmac_f32_e32 v144, v89, v89
	v_fmac_f32_e32 v144, v90, v90
	v_fmac_f32_e32 v144, v91, v91
	v_fmac_f32_e32 v144, v92, v92
	v_fmac_f32_e32 v144, v93, v93
	v_fmac_f32_e32 v144, v94, v94
	v_fmac_f32_e32 v144, v95, v95
	s_nop 1
	v_add_f32_dpp v144, v144, v144 quad_perm:[1,0,3,2] row_mask:0xf bank_mask:0xf
	s_nop 1
	v_add_f32_dpp v144, v144, v144 quad_perm:[2,3,0,1] row_mask:0xf bank_mask:0xf
	s_nop 1
	v_add_f32_dpp v144, v144, v144 row_half_mirror row_mask:0xf bank_mask:0xf
	s_nop 1
	v_add_f32_dpp v144, v144, v144 row_mirror row_mask:0xf bank_mask:0xf
	v_mov_b32_e32 v145, v144
	s_nop 1
	v_permlane16_swap_b32_e32 v144, v145
	v_add_f32_e32 v144, v144, v145
	v_mov_b32_e32 v145, v144
	s_nop 1
	v_permlane32_swap_b32_e32 v144, v145
	v_add_f32_e32 v144, v144, v145
	v_fmamk_f32 v144, v144, 0x3a800000, v147
	v_mul_f32_e32 v145, 0x4b800000, v144
	v_cmp_gt_f32_e32 vcc, s19, v144
	s_nop 1
	v_cndmask_b32_e32 v144, v144, v145, vcc
	v_rsq_f32_e32 v144, v144
	s_nop 0
	v_mul_f32_e32 v145, 0x45800000, v144
	v_cndmask_b32_e32 v144, v144, v145, vcc
	v_mul_f32_e32 v80, v80, v144
	v_mul_f32_e32 v80, v64, v80
	v_mul_f32_e32 v81, v81, v144
	v_mul_f32_e32 v81, v65, v81
	v_mul_f32_e32 v82, v82, v144
	v_mul_f32_e32 v82, v66, v82
	v_mul_f32_e32 v83, v83, v144
	v_mul_f32_e32 v83, v67, v83
	v_cvt_pk_bf16_f32 v80, v80, v81
	v_cvt_pk_bf16_f32 v81, v82, v83
	global_store_dwordx2 v148, v[80:81], s[10:11] offset:0
	v_mul_f32_e32 v84, v84, v144
	v_mul_f32_e32 v84, v68, v84
	v_mul_f32_e32 v85, v85, v144
	v_mul_f32_e32 v85, v69, v85
	v_mul_f32_e32 v86, v86, v144
	v_mul_f32_e32 v86, v70, v86
	v_mul_f32_e32 v87, v87, v144
	v_mul_f32_e32 v87, v71, v87
	v_cvt_pk_bf16_f32 v84, v84, v85
	v_cvt_pk_bf16_f32 v85, v86, v87
	global_store_dwordx2 v148, v[84:85], s[10:11] offset:512
	v_mul_f32_e32 v88, v88, v144
	v_mul_f32_e32 v88, v72, v88
	v_mul_f32_e32 v89, v89, v144
	v_mul_f32_e32 v89, v73, v89
	v_mul_f32_e32 v90, v90, v144
	v_mul_f32_e32 v90, v74, v90
	v_mul_f32_e32 v91, v91, v144
	v_mul_f32_e32 v91, v75, v91
	v_cvt_pk_bf16_f32 v88, v88, v89
	v_cvt_pk_bf16_f32 v89, v90, v91
	global_store_dwordx2 v148, v[88:89], s[10:11] offset:1024
	v_mul_f32_e32 v92, v92, v144
	v_mul_f32_e32 v92, v76, v92
	v_mul_f32_e32 v93, v93, v144
	v_mul_f32_e32 v93, v77, v93
	v_mul_f32_e32 v94, v94, v144
	v_mul_f32_e32 v94, v78, v94
	v_mul_f32_e32 v95, v95, v144
	v_mul_f32_e32 v95, v79, v95
	v_cvt_pk_bf16_f32 v92, v92, v93
	v_cvt_pk_bf16_f32 v93, v94, v95
	global_store_dwordx2 v148, v[92:93], s[10:11] offset:1536
	s_add_u32 s10, s10, s18
	s_addc_u32 s11, s11, 0
	v_mul_f32_e32 v144, v96, v96
	v_fmac_f32_e32 v144, v97, v97
	v_fmac_f32_e32 v144, v98, v98
	v_fmac_f32_e32 v144, v99, v99
	v_fmac_f32_e32 v144, v100, v100
	v_fmac_f32_e32 v144, v101, v101
	v_fmac_f32_e32 v144, v102, v102
	v_fmac_f32_e32 v144, v103, v103
	v_fmac_f32_e32 v144, v104, v104
	v_fmac_f32_e32 v144, v105, v105
	v_fmac_f32_e32 v144, v106, v106
	v_fmac_f32_e32 v144, v107, v107
	v_fmac_f32_e32 v144, v108, v108
	v_fmac_f32_e32 v144, v109, v109
	v_fmac_f32_e32 v144, v110, v110
	v_fmac_f32_e32 v144, v111, v111
	s_nop 1
	v_add_f32_dpp v144, v144, v144 quad_perm:[1,0,3,2] row_mask:0xf bank_mask:0xf
	s_nop 1
	v_add_f32_dpp v144, v144, v144 quad_perm:[2,3,0,1] row_mask:0xf bank_mask:0xf
	s_nop 1
	v_add_f32_dpp v144, v144, v144 row_half_mirror row_mask:0xf bank_mask:0xf
	s_nop 1
	v_add_f32_dpp v144, v144, v144 row_mirror row_mask:0xf bank_mask:0xf
	v_mov_b32_e32 v145, v144
	s_nop 1
	v_permlane16_swap_b32_e32 v144, v145
	v_add_f32_e32 v144, v144, v145
	v_mov_b32_e32 v145, v144
	s_nop 1
	v_permlane32_swap_b32_e32 v144, v145
	v_add_f32_e32 v144, v144, v145
	v_fmamk_f32 v144, v144, 0x3a800000, v147
	v_mul_f32_e32 v145, 0x4b800000, v144
	v_cmp_gt_f32_e32 vcc, s19, v144
	s_nop 1
	v_cndmask_b32_e32 v144, v144, v145, vcc
	v_rsq_f32_e32 v144, v144
	s_nop 0
	v_mul_f32_e32 v145, 0x45800000, v144
	v_cndmask_b32_e32 v144, v144, v145, vcc
	v_mul_f32_e32 v96, v96, v144
	v_mul_f32_e32 v96, v64, v96
	v_mul_f32_e32 v97, v97, v144
	v_mul_f32_e32 v97, v65, v97
	v_mul_f32_e32 v98, v98, v144
	v_mul_f32_e32 v98, v66, v98
	v_mul_f32_e32 v99, v99, v144
	v_mul_f32_e32 v99, v67, v99
	v_cvt_pk_bf16_f32 v96, v96, v97
	v_cvt_pk_bf16_f32 v97, v98, v99
	global_store_dwordx2 v148, v[96:97], s[10:11] offset:0
	v_mul_f32_e32 v100, v100, v144
	v_mul_f32_e32 v100, v68, v100
	v_mul_f32_e32 v101, v101, v144
	v_mul_f32_e32 v101, v69, v101
	v_mul_f32_e32 v102, v102, v144
	v_mul_f32_e32 v102, v70, v102
	v_mul_f32_e32 v103, v103, v144
	v_mul_f32_e32 v103, v71, v103
	v_cvt_pk_bf16_f32 v100, v100, v101
	v_cvt_pk_bf16_f32 v101, v102, v103
	global_store_dwordx2 v148, v[100:101], s[10:11] offset:512
	v_mul_f32_e32 v104, v104, v144
	v_mul_f32_e32 v104, v72, v104
	v_mul_f32_e32 v105, v105, v144
	v_mul_f32_e32 v105, v73, v105
	v_mul_f32_e32 v106, v106, v144
	v_mul_f32_e32 v106, v74, v106
	v_mul_f32_e32 v107, v107, v144
	v_mul_f32_e32 v107, v75, v107
	v_cvt_pk_bf16_f32 v104, v104, v105
	v_cvt_pk_bf16_f32 v105, v106, v107
	global_store_dwordx2 v148, v[104:105], s[10:11] offset:1024
	v_mul_f32_e32 v108, v108, v144
	v_mul_f32_e32 v108, v76, v108
	v_mul_f32_e32 v109, v109, v144
	v_mul_f32_e32 v109, v77, v109
	v_mul_f32_e32 v110, v110, v144
	v_mul_f32_e32 v110, v78, v110
	v_mul_f32_e32 v111, v111, v144
	v_mul_f32_e32 v111, v79, v111
	v_cvt_pk_bf16_f32 v108, v108, v109
	v_cvt_pk_bf16_f32 v109, v110, v111
	global_store_dwordx2 v148, v[108:109], s[10:11] offset:1536
	s_add_u32 s10, s10, s18
	s_addc_u32 s11, s11, 0
	v_mul_f32_e32 v144, v112, v112
	v_fmac_f32_e32 v144, v113, v113
	v_fmac_f32_e32 v144, v114, v114
	v_fmac_f32_e32 v144, v115, v115
	v_fmac_f32_e32 v144, v116, v116
	v_fmac_f32_e32 v144, v117, v117
	v_fmac_f32_e32 v144, v118, v118
	v_fmac_f32_e32 v144, v119, v119
	v_fmac_f32_e32 v144, v120, v120
	v_fmac_f32_e32 v144, v121, v121
	v_fmac_f32_e32 v144, v122, v122
	v_fmac_f32_e32 v144, v123, v123
	v_fmac_f32_e32 v144, v124, v124
	v_fmac_f32_e32 v144, v125, v125
	v_fmac_f32_e32 v144, v126, v126
	v_fmac_f32_e32 v144, v127, v127
	s_nop 1
	v_add_f32_dpp v144, v144, v144 quad_perm:[1,0,3,2] row_mask:0xf bank_mask:0xf
	s_nop 1
	v_add_f32_dpp v144, v144, v144 quad_perm:[2,3,0,1] row_mask:0xf bank_mask:0xf
	s_nop 1
	v_add_f32_dpp v144, v144, v144 row_half_mirror row_mask:0xf bank_mask:0xf
	s_nop 1
	v_add_f32_dpp v144, v144, v144 row_mirror row_mask:0xf bank_mask:0xf
	v_mov_b32_e32 v145, v144
	s_nop 1
	v_permlane16_swap_b32_e32 v144, v145
	v_add_f32_e32 v144, v144, v145
	v_mov_b32_e32 v145, v144
	s_nop 1
	v_permlane32_swap_b32_e32 v144, v145
	v_add_f32_e32 v144, v144, v145
	v_fmamk_f32 v144, v144, 0x3a800000, v147
	v_mul_f32_e32 v145, 0x4b800000, v144
	v_cmp_gt_f32_e32 vcc, s19, v144
	s_nop 1
	v_cndmask_b32_e32 v144, v144, v145, vcc
	v_rsq_f32_e32 v144, v144
	s_nop 0
	v_mul_f32_e32 v145, 0x45800000, v144
	v_cndmask_b32_e32 v144, v144, v145, vcc
	v_mul_f32_e32 v112, v112, v144
	v_mul_f32_e32 v112, v64, v112
	v_mul_f32_e32 v113, v113, v144
	v_mul_f32_e32 v113, v65, v113
	v_mul_f32_e32 v114, v114, v144
	v_mul_f32_e32 v114, v66, v114
	v_mul_f32_e32 v115, v115, v144
	v_mul_f32_e32 v115, v67, v115
	v_cvt_pk_bf16_f32 v112, v112, v113
	v_cvt_pk_bf16_f32 v113, v114, v115
	global_store_dwordx2 v148, v[112:113], s[10:11] offset:0
	v_mul_f32_e32 v116, v116, v144
	v_mul_f32_e32 v116, v68, v116
	v_mul_f32_e32 v117, v117, v144
	v_mul_f32_e32 v117, v69, v117
	v_mul_f32_e32 v118, v118, v144
	v_mul_f32_e32 v118, v70, v118
	v_mul_f32_e32 v119, v119, v144
	v_mul_f32_e32 v119, v71, v119
	v_cvt_pk_bf16_f32 v116, v116, v117
	v_cvt_pk_bf16_f32 v117, v118, v119
	global_store_dwordx2 v148, v[116:117], s[10:11] offset:512
	v_mul_f32_e32 v120, v120, v144
	v_mul_f32_e32 v120, v72, v120
	v_mul_f32_e32 v121, v121, v144
	v_mul_f32_e32 v121, v73, v121
	v_mul_f32_e32 v122, v122, v144
	v_mul_f32_e32 v122, v74, v122
	v_mul_f32_e32 v123, v123, v144
	v_mul_f32_e32 v123, v75, v123
	v_cvt_pk_bf16_f32 v120, v120, v121
	v_cvt_pk_bf16_f32 v121, v122, v123
	global_store_dwordx2 v148, v[120:121], s[10:11] offset:1024
	v_mul_f32_e32 v124, v124, v144
	v_mul_f32_e32 v124, v76, v124
	v_mul_f32_e32 v125, v125, v144
	v_mul_f32_e32 v125, v77, v125
	v_mul_f32_e32 v126, v126, v144
	v_mul_f32_e32 v126, v78, v126
	v_mul_f32_e32 v127, v127, v144
	v_mul_f32_e32 v127, v79, v127
	v_cvt_pk_bf16_f32 v124, v124, v125
	v_cvt_pk_bf16_f32 v125, v126, v127
	global_store_dwordx2 v148, v[124:125], s[10:11] offset:1536
	s_add_u32 s10, s10, s18
	s_addc_u32 s11, s11, 0
	v_mul_f32_e32 v144, v128, v128
	v_fmac_f32_e32 v144, v129, v129
	v_fmac_f32_e32 v144, v130, v130
	v_fmac_f32_e32 v144, v131, v131
	v_fmac_f32_e32 v144, v132, v132
	v_fmac_f32_e32 v144, v133, v133
	v_fmac_f32_e32 v144, v134, v134
	v_fmac_f32_e32 v144, v135, v135
	v_fmac_f32_e32 v144, v136, v136
	v_fmac_f32_e32 v144, v137, v137
	v_fmac_f32_e32 v144, v138, v138
	v_fmac_f32_e32 v144, v139, v139
	v_fmac_f32_e32 v144, v140, v140
	v_fmac_f32_e32 v144, v141, v141
	v_fmac_f32_e32 v144, v142, v142
	v_fmac_f32_e32 v144, v143, v143
	s_nop 1
	v_add_f32_dpp v144, v144, v144 quad_perm:[1,0,3,2] row_mask:0xf bank_mask:0xf
	s_nop 1
	v_add_f32_dpp v144, v144, v144 quad_perm:[2,3,0,1] row_mask:0xf bank_mask:0xf
	s_nop 1
	v_add_f32_dpp v144, v144, v144 row_half_mirror row_mask:0xf bank_mask:0xf
	s_nop 1
	v_add_f32_dpp v144, v144, v144 row_mirror row_mask:0xf bank_mask:0xf
	v_mov_b32_e32 v145, v144
	s_nop 1
	v_permlane16_swap_b32_e32 v144, v145
	v_add_f32_e32 v144, v144, v145
	v_mov_b32_e32 v145, v144
	s_nop 1
	v_permlane32_swap_b32_e32 v144, v145
	v_add_f32_e32 v144, v144, v145
	v_fmamk_f32 v144, v144, 0x3a800000, v147
	v_mul_f32_e32 v145, 0x4b800000, v144
	v_cmp_gt_f32_e32 vcc, s19, v144
	s_nop 1
	v_cndmask_b32_e32 v144, v144, v145, vcc
	v_rsq_f32_e32 v144, v144
	s_nop 0
	v_mul_f32_e32 v145, 0x45800000, v144
	v_cndmask_b32_e32 v144, v144, v145, vcc
	v_mul_f32_e32 v128, v128, v144
	v_mul_f32_e32 v128, v64, v128
	v_mul_f32_e32 v129, v129, v144
	v_mul_f32_e32 v129, v65, v129
	v_mul_f32_e32 v130, v130, v144
	v_mul_f32_e32 v130, v66, v130
	v_mul_f32_e32 v131, v131, v144
	v_mul_f32_e32 v131, v67, v131
	v_cvt_pk_bf16_f32 v128, v128, v129
	v_cvt_pk_bf16_f32 v129, v130, v131
	global_store_dwordx2 v148, v[128:129], s[10:11] offset:0
	v_mul_f32_e32 v132, v132, v144
	v_mul_f32_e32 v132, v68, v132
	v_mul_f32_e32 v133, v133, v144
	v_mul_f32_e32 v133, v69, v133
	v_mul_f32_e32 v134, v134, v144
	v_mul_f32_e32 v134, v70, v134
	v_mul_f32_e32 v135, v135, v144
	v_mul_f32_e32 v135, v71, v135
	v_cvt_pk_bf16_f32 v132, v132, v133
	v_cvt_pk_bf16_f32 v133, v134, v135
	global_store_dwordx2 v148, v[132:133], s[10:11] offset:512
	v_mul_f32_e32 v136, v136, v144
	v_mul_f32_e32 v136, v72, v136
	v_mul_f32_e32 v137, v137, v144
	v_mul_f32_e32 v137, v73, v137
	v_mul_f32_e32 v138, v138, v144
	v_mul_f32_e32 v138, v74, v138
	v_mul_f32_e32 v139, v139, v144
	v_mul_f32_e32 v139, v75, v139
	v_cvt_pk_bf16_f32 v136, v136, v137
	v_cvt_pk_bf16_f32 v137, v138, v139
	global_store_dwordx2 v148, v[136:137], s[10:11] offset:1024
	v_mul_f32_e32 v140, v140, v144
	v_mul_f32_e32 v140, v76, v140
	v_mul_f32_e32 v141, v141, v144
	v_mul_f32_e32 v141, v77, v141
	v_mul_f32_e32 v142, v142, v144
	v_mul_f32_e32 v142, v78, v142
	v_mul_f32_e32 v143, v143, v144
	v_mul_f32_e32 v143, v79, v143
	v_cvt_pk_bf16_f32 v140, v140, v141
	v_cvt_pk_bf16_f32 v141, v142, v143
	global_store_dwordx2 v148, v[140:141], s[10:11] offset:1536
	s_add_u32 s10, s10, s18
	s_addc_u32 s11, s11, 0
	global_load_dwordx4 v[80:83], v229, s[8:9] offset:0
	global_load_dwordx4 v[84:87], v229, s[8:9] offset:1024
	global_load_dwordx4 v[88:91], v229, s[8:9] offset:2048
	global_load_dwordx4 v[92:95], v229, s[8:9] offset:3072
	s_add_u32 s8, s8, s16
	s_addc_u32 s9, s9, 0
	global_load_dwordx4 v[96:99], v229, s[8:9] offset:0
	global_load_dwordx4 v[100:103], v229, s[8:9] offset:1024
	global_load_dwordx4 v[104:107], v229, s[8:9] offset:2048
	global_load_dwordx4 v[108:111], v229, s[8:9] offset:3072
	s_add_u32 s8, s8, s16
	s_addc_u32 s9, s9, 0
	global_load_dwordx4 v[112:115], v229, s[8:9] offset:0
	global_load_dwordx4 v[116:119], v229, s[8:9] offset:1024
	global_load_dwordx4 v[120:123], v229, s[8:9] offset:2048
	global_load_dwordx4 v[124:127], v229, s[8:9] offset:3072
	s_add_u32 s8, s8, s16
	s_addc_u32 s9, s9, 0
	global_load_dwordx4 v[128:131], v229, s[8:9] offset:0
	global_load_dwordx4 v[132:135], v229, s[8:9] offset:1024
	global_load_dwordx4 v[136:139], v229, s[8:9] offset:2048
	global_load_dwordx4 v[140:143], v229, s[8:9] offset:3072
	s_add_u32 s8, s8, s16
	s_addc_u32 s9, s9, 0
	s_waitcnt vmcnt(0)
	v_mul_f32_e32 v144, v80, v80
	v_fmac_f32_e32 v144, v81, v81
	v_fmac_f32_e32 v144, v82, v82
	v_fmac_f32_e32 v144, v83, v83
	v_fmac_f32_e32 v144, v84, v84
	v_fmac_f32_e32 v144, v85, v85
	v_fmac_f32_e32 v144, v86, v86
	v_fmac_f32_e32 v144, v87, v87
	v_fmac_f32_e32 v144, v88, v88
	v_fmac_f32_e32 v144, v89, v89
	v_fmac_f32_e32 v144, v90, v90
	v_fmac_f32_e32 v144, v91, v91
	v_fmac_f32_e32 v144, v92, v92
	v_fmac_f32_e32 v144, v93, v93
	v_fmac_f32_e32 v144, v94, v94
	v_fmac_f32_e32 v144, v95, v95
	s_nop 1
	v_add_f32_dpp v144, v144, v144 quad_perm:[1,0,3,2] row_mask:0xf bank_mask:0xf
	s_nop 1
	v_add_f32_dpp v144, v144, v144 quad_perm:[2,3,0,1] row_mask:0xf bank_mask:0xf
	s_nop 1
	v_add_f32_dpp v144, v144, v144 row_half_mirror row_mask:0xf bank_mask:0xf
	s_nop 1
	v_add_f32_dpp v144, v144, v144 row_mirror row_mask:0xf bank_mask:0xf
	v_mov_b32_e32 v145, v144
	s_nop 1
	v_permlane16_swap_b32_e32 v144, v145
	v_add_f32_e32 v144, v144, v145
	v_mov_b32_e32 v145, v144
	s_nop 1
	v_permlane32_swap_b32_e32 v144, v145
	v_add_f32_e32 v144, v144, v145
	v_fmamk_f32 v144, v144, 0x3a800000, v147
	v_mul_f32_e32 v145, 0x4b800000, v144
	v_cmp_gt_f32_e32 vcc, s19, v144
	s_nop 1
	v_cndmask_b32_e32 v144, v144, v145, vcc
	v_rsq_f32_e32 v144, v144
	s_nop 0
	v_mul_f32_e32 v145, 0x45800000, v144
	v_cndmask_b32_e32 v144, v144, v145, vcc
	v_mul_f32_e32 v80, v80, v144
	v_mul_f32_e32 v80, v64, v80
	v_mul_f32_e32 v81, v81, v144
	v_mul_f32_e32 v81, v65, v81
	v_mul_f32_e32 v82, v82, v144
	v_mul_f32_e32 v82, v66, v82
	v_mul_f32_e32 v83, v83, v144
	v_mul_f32_e32 v83, v67, v83
	v_cvt_pk_bf16_f32 v80, v80, v81
	v_cvt_pk_bf16_f32 v81, v82, v83
	global_store_dwordx2 v148, v[80:81], s[10:11] offset:0
	v_mul_f32_e32 v84, v84, v144
	v_mul_f32_e32 v84, v68, v84
	v_mul_f32_e32 v85, v85, v144
	v_mul_f32_e32 v85, v69, v85
	v_mul_f32_e32 v86, v86, v144
	v_mul_f32_e32 v86, v70, v86
	v_mul_f32_e32 v87, v87, v144
	v_mul_f32_e32 v87, v71, v87
	v_cvt_pk_bf16_f32 v84, v84, v85
	v_cvt_pk_bf16_f32 v85, v86, v87
	global_store_dwordx2 v148, v[84:85], s[10:11] offset:512
	v_mul_f32_e32 v88, v88, v144
	v_mul_f32_e32 v88, v72, v88
	v_mul_f32_e32 v89, v89, v144
	v_mul_f32_e32 v89, v73, v89
	v_mul_f32_e32 v90, v90, v144
	v_mul_f32_e32 v90, v74, v90
	v_mul_f32_e32 v91, v91, v144
	v_mul_f32_e32 v91, v75, v91
	v_cvt_pk_bf16_f32 v88, v88, v89
	v_cvt_pk_bf16_f32 v89, v90, v91
	global_store_dwordx2 v148, v[88:89], s[10:11] offset:1024
	v_mul_f32_e32 v92, v92, v144
	v_mul_f32_e32 v92, v76, v92
	v_mul_f32_e32 v93, v93, v144
	v_mul_f32_e32 v93, v77, v93
	v_mul_f32_e32 v94, v94, v144
	v_mul_f32_e32 v94, v78, v94
	v_mul_f32_e32 v95, v95, v144
	v_mul_f32_e32 v95, v79, v95
	v_cvt_pk_bf16_f32 v92, v92, v93
	v_cvt_pk_bf16_f32 v93, v94, v95
	global_store_dwordx2 v148, v[92:93], s[10:11] offset:1536
	s_add_u32 s10, s10, s18
	s_addc_u32 s11, s11, 0
	v_mul_f32_e32 v144, v96, v96
	v_fmac_f32_e32 v144, v97, v97
	v_fmac_f32_e32 v144, v98, v98
	v_fmac_f32_e32 v144, v99, v99
	v_fmac_f32_e32 v144, v100, v100
	v_fmac_f32_e32 v144, v101, v101
	v_fmac_f32_e32 v144, v102, v102
	v_fmac_f32_e32 v144, v103, v103
	v_fmac_f32_e32 v144, v104, v104
	v_fmac_f32_e32 v144, v105, v105
	v_fmac_f32_e32 v144, v106, v106
	v_fmac_f32_e32 v144, v107, v107
	v_fmac_f32_e32 v144, v108, v108
	v_fmac_f32_e32 v144, v109, v109
	v_fmac_f32_e32 v144, v110, v110
	v_fmac_f32_e32 v144, v111, v111
	s_nop 1
	v_add_f32_dpp v144, v144, v144 quad_perm:[1,0,3,2] row_mask:0xf bank_mask:0xf
	s_nop 1
	v_add_f32_dpp v144, v144, v144 quad_perm:[2,3,0,1] row_mask:0xf bank_mask:0xf
	s_nop 1
	v_add_f32_dpp v144, v144, v144 row_half_mirror row_mask:0xf bank_mask:0xf
	s_nop 1
	v_add_f32_dpp v144, v144, v144 row_mirror row_mask:0xf bank_mask:0xf
	v_mov_b32_e32 v145, v144
	s_nop 1
	v_permlane16_swap_b32_e32 v144, v145
	v_add_f32_e32 v144, v144, v145
	v_mov_b32_e32 v145, v144
	s_nop 1
	v_permlane32_swap_b32_e32 v144, v145
	v_add_f32_e32 v144, v144, v145
	v_fmamk_f32 v144, v144, 0x3a800000, v147
	v_mul_f32_e32 v145, 0x4b800000, v144
	v_cmp_gt_f32_e32 vcc, s19, v144
	s_nop 1
	v_cndmask_b32_e32 v144, v144, v145, vcc
	v_rsq_f32_e32 v144, v144
	s_nop 0
	v_mul_f32_e32 v145, 0x45800000, v144
	v_cndmask_b32_e32 v144, v144, v145, vcc
	v_mul_f32_e32 v96, v96, v144
	v_mul_f32_e32 v96, v64, v96
	v_mul_f32_e32 v97, v97, v144
	v_mul_f32_e32 v97, v65, v97
	v_mul_f32_e32 v98, v98, v144
	v_mul_f32_e32 v98, v66, v98
	v_mul_f32_e32 v99, v99, v144
	v_mul_f32_e32 v99, v67, v99
	v_cvt_pk_bf16_f32 v96, v96, v97
	v_cvt_pk_bf16_f32 v97, v98, v99
	global_store_dwordx2 v148, v[96:97], s[10:11] offset:0
	v_mul_f32_e32 v100, v100, v144
	v_mul_f32_e32 v100, v68, v100
	v_mul_f32_e32 v101, v101, v144
	v_mul_f32_e32 v101, v69, v101
	v_mul_f32_e32 v102, v102, v144
	v_mul_f32_e32 v102, v70, v102
	v_mul_f32_e32 v103, v103, v144
	v_mul_f32_e32 v103, v71, v103
	v_cvt_pk_bf16_f32 v100, v100, v101
	v_cvt_pk_bf16_f32 v101, v102, v103
	global_store_dwordx2 v148, v[100:101], s[10:11] offset:512
	v_mul_f32_e32 v104, v104, v144
	v_mul_f32_e32 v104, v72, v104
	v_mul_f32_e32 v105, v105, v144
	v_mul_f32_e32 v105, v73, v105
	v_mul_f32_e32 v106, v106, v144
	v_mul_f32_e32 v106, v74, v106
	v_mul_f32_e32 v107, v107, v144
	v_mul_f32_e32 v107, v75, v107
	v_cvt_pk_bf16_f32 v104, v104, v105
	v_cvt_pk_bf16_f32 v105, v106, v107
	global_store_dwordx2 v148, v[104:105], s[10:11] offset:1024
	v_mul_f32_e32 v108, v108, v144
	v_mul_f32_e32 v108, v76, v108
	v_mul_f32_e32 v109, v109, v144
	v_mul_f32_e32 v109, v77, v109
	v_mul_f32_e32 v110, v110, v144
	v_mul_f32_e32 v110, v78, v110
	v_mul_f32_e32 v111, v111, v144
	v_mul_f32_e32 v111, v79, v111
	v_cvt_pk_bf16_f32 v108, v108, v109
	v_cvt_pk_bf16_f32 v109, v110, v111
	global_store_dwordx2 v148, v[108:109], s[10:11] offset:1536
	s_add_u32 s10, s10, s18
	s_addc_u32 s11, s11, 0
	v_mul_f32_e32 v144, v112, v112
	v_fmac_f32_e32 v144, v113, v113
	v_fmac_f32_e32 v144, v114, v114
	v_fmac_f32_e32 v144, v115, v115
	v_fmac_f32_e32 v144, v116, v116
	v_fmac_f32_e32 v144, v117, v117
	v_fmac_f32_e32 v144, v118, v118
	v_fmac_f32_e32 v144, v119, v119
	v_fmac_f32_e32 v144, v120, v120
	v_fmac_f32_e32 v144, v121, v121
	v_fmac_f32_e32 v144, v122, v122
	v_fmac_f32_e32 v144, v123, v123
	v_fmac_f32_e32 v144, v124, v124
	v_fmac_f32_e32 v144, v125, v125
	v_fmac_f32_e32 v144, v126, v126
	v_fmac_f32_e32 v144, v127, v127
	s_nop 1
	v_add_f32_dpp v144, v144, v144 quad_perm:[1,0,3,2] row_mask:0xf bank_mask:0xf
	s_nop 1
	v_add_f32_dpp v144, v144, v144 quad_perm:[2,3,0,1] row_mask:0xf bank_mask:0xf
	s_nop 1
	v_add_f32_dpp v144, v144, v144 row_half_mirror row_mask:0xf bank_mask:0xf
	s_nop 1
	v_add_f32_dpp v144, v144, v144 row_mirror row_mask:0xf bank_mask:0xf
	v_mov_b32_e32 v145, v144
	s_nop 1
	v_permlane16_swap_b32_e32 v144, v145
	v_add_f32_e32 v144, v144, v145
	v_mov_b32_e32 v145, v144
	s_nop 1
	v_permlane32_swap_b32_e32 v144, v145
	v_add_f32_e32 v144, v144, v145
	v_fmamk_f32 v144, v144, 0x3a800000, v147
	v_mul_f32_e32 v145, 0x4b800000, v144
	v_cmp_gt_f32_e32 vcc, s19, v144
	s_nop 1
	v_cndmask_b32_e32 v144, v144, v145, vcc
	v_rsq_f32_e32 v144, v144
	s_nop 0
	v_mul_f32_e32 v145, 0x45800000, v144
	v_cndmask_b32_e32 v144, v144, v145, vcc
	v_mul_f32_e32 v112, v112, v144
	v_mul_f32_e32 v112, v64, v112
	v_mul_f32_e32 v113, v113, v144
	v_mul_f32_e32 v113, v65, v113
	v_mul_f32_e32 v114, v114, v144
	v_mul_f32_e32 v114, v66, v114
	v_mul_f32_e32 v115, v115, v144
	v_mul_f32_e32 v115, v67, v115
	v_cvt_pk_bf16_f32 v112, v112, v113
	v_cvt_pk_bf16_f32 v113, v114, v115
	global_store_dwordx2 v148, v[112:113], s[10:11] offset:0
	v_mul_f32_e32 v116, v116, v144
	v_mul_f32_e32 v116, v68, v116
	v_mul_f32_e32 v117, v117, v144
	v_mul_f32_e32 v117, v69, v117
	v_mul_f32_e32 v118, v118, v144
	v_mul_f32_e32 v118, v70, v118
	v_mul_f32_e32 v119, v119, v144
	v_mul_f32_e32 v119, v71, v119
	v_cvt_pk_bf16_f32 v116, v116, v117
	v_cvt_pk_bf16_f32 v117, v118, v119
	global_store_dwordx2 v148, v[116:117], s[10:11] offset:512
	v_mul_f32_e32 v120, v120, v144
	v_mul_f32_e32 v120, v72, v120
	v_mul_f32_e32 v121, v121, v144
	v_mul_f32_e32 v121, v73, v121
	v_mul_f32_e32 v122, v122, v144
	v_mul_f32_e32 v122, v74, v122
	v_mul_f32_e32 v123, v123, v144
	v_mul_f32_e32 v123, v75, v123
	v_cvt_pk_bf16_f32 v120, v120, v121
	v_cvt_pk_bf16_f32 v121, v122, v123
	global_store_dwordx2 v148, v[120:121], s[10:11] offset:1024
	v_mul_f32_e32 v124, v124, v144
	v_mul_f32_e32 v124, v76, v124
	v_mul_f32_e32 v125, v125, v144
	v_mul_f32_e32 v125, v77, v125
	v_mul_f32_e32 v126, v126, v144
	v_mul_f32_e32 v126, v78, v126
	v_mul_f32_e32 v127, v127, v144
	v_mul_f32_e32 v127, v79, v127
	v_cvt_pk_bf16_f32 v124, v124, v125
	v_cvt_pk_bf16_f32 v125, v126, v127
	global_store_dwordx2 v148, v[124:125], s[10:11] offset:1536
	s_add_u32 s10, s10, s18
	s_addc_u32 s11, s11, 0
	v_mul_f32_e32 v144, v128, v128
	v_fmac_f32_e32 v144, v129, v129
	v_fmac_f32_e32 v144, v130, v130
	v_fmac_f32_e32 v144, v131, v131
	v_fmac_f32_e32 v144, v132, v132
	v_fmac_f32_e32 v144, v133, v133
	v_fmac_f32_e32 v144, v134, v134
	v_fmac_f32_e32 v144, v135, v135
	v_fmac_f32_e32 v144, v136, v136
	v_fmac_f32_e32 v144, v137, v137
	v_fmac_f32_e32 v144, v138, v138
	v_fmac_f32_e32 v144, v139, v139
	v_fmac_f32_e32 v144, v140, v140
	v_fmac_f32_e32 v144, v141, v141
	v_fmac_f32_e32 v144, v142, v142
	v_fmac_f32_e32 v144, v143, v143
	s_nop 1
	v_add_f32_dpp v144, v144, v144 quad_perm:[1,0,3,2] row_mask:0xf bank_mask:0xf
	s_nop 1
	v_add_f32_dpp v144, v144, v144 quad_perm:[2,3,0,1] row_mask:0xf bank_mask:0xf
	s_nop 1
	v_add_f32_dpp v144, v144, v144 row_half_mirror row_mask:0xf bank_mask:0xf
	s_nop 1
	v_add_f32_dpp v144, v144, v144 row_mirror row_mask:0xf bank_mask:0xf
	v_mov_b32_e32 v145, v144
	s_nop 1
	v_permlane16_swap_b32_e32 v144, v145
	v_add_f32_e32 v144, v144, v145
	v_mov_b32_e32 v145, v144
	s_nop 1
	v_permlane32_swap_b32_e32 v144, v145
	v_add_f32_e32 v144, v144, v145
	v_fmamk_f32 v144, v144, 0x3a800000, v147
	v_mul_f32_e32 v145, 0x4b800000, v144
	v_cmp_gt_f32_e32 vcc, s19, v144
	s_nop 1
	v_cndmask_b32_e32 v144, v144, v145, vcc
	v_rsq_f32_e32 v144, v144
	s_nop 0
	v_mul_f32_e32 v145, 0x45800000, v144
	v_cndmask_b32_e32 v144, v144, v145, vcc
	v_mul_f32_e32 v128, v128, v144
	v_mul_f32_e32 v128, v64, v128
	v_mul_f32_e32 v129, v129, v144
	v_mul_f32_e32 v129, v65, v129
	v_mul_f32_e32 v130, v130, v144
	v_mul_f32_e32 v130, v66, v130
	v_mul_f32_e32 v131, v131, v144
	v_mul_f32_e32 v131, v67, v131
	v_cvt_pk_bf16_f32 v128, v128, v129
	v_cvt_pk_bf16_f32 v129, v130, v131
	global_store_dwordx2 v148, v[128:129], s[10:11] offset:0
	v_mul_f32_e32 v132, v132, v144
	v_mul_f32_e32 v132, v68, v132
	v_mul_f32_e32 v133, v133, v144
	v_mul_f32_e32 v133, v69, v133
	v_mul_f32_e32 v134, v134, v144
	v_mul_f32_e32 v134, v70, v134
	v_mul_f32_e32 v135, v135, v144
	v_mul_f32_e32 v135, v71, v135
	v_cvt_pk_bf16_f32 v132, v132, v133
	v_cvt_pk_bf16_f32 v133, v134, v135
	global_store_dwordx2 v148, v[132:133], s[10:11] offset:512
	v_mul_f32_e32 v136, v136, v144
	v_mul_f32_e32 v136, v72, v136
	v_mul_f32_e32 v137, v137, v144
	v_mul_f32_e32 v137, v73, v137
	v_mul_f32_e32 v138, v138, v144
	v_mul_f32_e32 v138, v74, v138
	v_mul_f32_e32 v139, v139, v144
	v_mul_f32_e32 v139, v75, v139
	v_cvt_pk_bf16_f32 v136, v136, v137
	v_cvt_pk_bf16_f32 v137, v138, v139
	global_store_dwordx2 v148, v[136:137], s[10:11] offset:1024
	v_mul_f32_e32 v140, v140, v144
	v_mul_f32_e32 v140, v76, v140
	v_mul_f32_e32 v141, v141, v144
	v_mul_f32_e32 v141, v77, v141
	v_mul_f32_e32 v142, v142, v144
	v_mul_f32_e32 v142, v78, v142
	v_mul_f32_e32 v143, v143, v144
	v_mul_f32_e32 v143, v79, v143
	v_cvt_pk_bf16_f32 v140, v140, v141
	v_cvt_pk_bf16_f32 v141, v142, v143
	global_store_dwordx2 v148, v[140:141], s[10:11] offset:1536
	s_add_u32 s10, s10, s18
	s_addc_u32 s11, s11, 0
	global_load_dwordx4 v[80:83], v229, s[8:9] offset:0
	global_load_dwordx4 v[84:87], v229, s[8:9] offset:1024
	global_load_dwordx4 v[88:91], v229, s[8:9] offset:2048
	global_load_dwordx4 v[92:95], v229, s[8:9] offset:3072
	s_add_u32 s8, s8, s16
	s_addc_u32 s9, s9, 0
	global_load_dwordx4 v[96:99], v229, s[8:9] offset:0
	global_load_dwordx4 v[100:103], v229, s[8:9] offset:1024
	global_load_dwordx4 v[104:107], v229, s[8:9] offset:2048
	global_load_dwordx4 v[108:111], v229, s[8:9] offset:3072
	s_add_u32 s8, s8, s16
	s_addc_u32 s9, s9, 0
	global_load_dwordx4 v[112:115], v229, s[8:9] offset:0
	global_load_dwordx4 v[116:119], v229, s[8:9] offset:1024
	global_load_dwordx4 v[120:123], v229, s[8:9] offset:2048
	global_load_dwordx4 v[124:127], v229, s[8:9] offset:3072
	s_add_u32 s8, s8, s16
	s_addc_u32 s9, s9, 0
	global_load_dwordx4 v[128:131], v229, s[8:9] offset:0
	global_load_dwordx4 v[132:135], v229, s[8:9] offset:1024
	global_load_dwordx4 v[136:139], v229, s[8:9] offset:2048
	global_load_dwordx4 v[140:143], v229, s[8:9] offset:3072
	s_add_u32 s8, s8, s16
	s_addc_u32 s9, s9, 0
	s_waitcnt vmcnt(0)
	v_mul_f32_e32 v144, v80, v80
	v_fmac_f32_e32 v144, v81, v81
	v_fmac_f32_e32 v144, v82, v82
	v_fmac_f32_e32 v144, v83, v83
	v_fmac_f32_e32 v144, v84, v84
	v_fmac_f32_e32 v144, v85, v85
	v_fmac_f32_e32 v144, v86, v86
	v_fmac_f32_e32 v144, v87, v87
	v_fmac_f32_e32 v144, v88, v88
	v_fmac_f32_e32 v144, v89, v89
	v_fmac_f32_e32 v144, v90, v90
	v_fmac_f32_e32 v144, v91, v91
	v_fmac_f32_e32 v144, v92, v92
	v_fmac_f32_e32 v144, v93, v93
	v_fmac_f32_e32 v144, v94, v94
	v_fmac_f32_e32 v144, v95, v95
	s_nop 1
	v_add_f32_dpp v144, v144, v144 quad_perm:[1,0,3,2] row_mask:0xf bank_mask:0xf
	s_nop 1
	v_add_f32_dpp v144, v144, v144 quad_perm:[2,3,0,1] row_mask:0xf bank_mask:0xf
	s_nop 1
	v_add_f32_dpp v144, v144, v144 row_half_mirror row_mask:0xf bank_mask:0xf
	s_nop 1
	v_add_f32_dpp v144, v144, v144 row_mirror row_mask:0xf bank_mask:0xf
	v_mov_b32_e32 v145, v144
	s_nop 1
	v_permlane16_swap_b32_e32 v144, v145
	v_add_f32_e32 v144, v144, v145
	v_mov_b32_e32 v145, v144
	s_nop 1
	v_permlane32_swap_b32_e32 v144, v145
	v_add_f32_e32 v144, v144, v145
	v_fmamk_f32 v144, v144, 0x3a800000, v147
	v_mul_f32_e32 v145, 0x4b800000, v144
	v_cmp_gt_f32_e32 vcc, s19, v144
	s_nop 1
	v_cndmask_b32_e32 v144, v144, v145, vcc
	v_rsq_f32_e32 v144, v144
	s_nop 0
	v_mul_f32_e32 v145, 0x45800000, v144
	v_cndmask_b32_e32 v144, v144, v145, vcc
	v_mul_f32_e32 v80, v80, v144
	v_mul_f32_e32 v80, v64, v80
	v_mul_f32_e32 v81, v81, v144
	v_mul_f32_e32 v81, v65, v81
	v_mul_f32_e32 v82, v82, v144
	v_mul_f32_e32 v82, v66, v82
	v_mul_f32_e32 v83, v83, v144
	v_mul_f32_e32 v83, v67, v83
	v_cvt_pk_bf16_f32 v80, v80, v81
	v_cvt_pk_bf16_f32 v81, v82, v83
	global_store_dwordx2 v148, v[80:81], s[10:11] offset:0
	v_mul_f32_e32 v84, v84, v144
	v_mul_f32_e32 v84, v68, v84
	v_mul_f32_e32 v85, v85, v144
	v_mul_f32_e32 v85, v69, v85
	v_mul_f32_e32 v86, v86, v144
	v_mul_f32_e32 v86, v70, v86
	v_mul_f32_e32 v87, v87, v144
	v_mul_f32_e32 v87, v71, v87
	v_cvt_pk_bf16_f32 v84, v84, v85
	v_cvt_pk_bf16_f32 v85, v86, v87
	global_store_dwordx2 v148, v[84:85], s[10:11] offset:512
	v_mul_f32_e32 v88, v88, v144
	v_mul_f32_e32 v88, v72, v88
	v_mul_f32_e32 v89, v89, v144
	v_mul_f32_e32 v89, v73, v89
	v_mul_f32_e32 v90, v90, v144
	v_mul_f32_e32 v90, v74, v90
	v_mul_f32_e32 v91, v91, v144
	v_mul_f32_e32 v91, v75, v91
	v_cvt_pk_bf16_f32 v88, v88, v89
	v_cvt_pk_bf16_f32 v89, v90, v91
	global_store_dwordx2 v148, v[88:89], s[10:11] offset:1024
	v_mul_f32_e32 v92, v92, v144
	v_mul_f32_e32 v92, v76, v92
	v_mul_f32_e32 v93, v93, v144
	v_mul_f32_e32 v93, v77, v93
	v_mul_f32_e32 v94, v94, v144
	v_mul_f32_e32 v94, v78, v94
	v_mul_f32_e32 v95, v95, v144
	v_mul_f32_e32 v95, v79, v95
	v_cvt_pk_bf16_f32 v92, v92, v93
	v_cvt_pk_bf16_f32 v93, v94, v95
	global_store_dwordx2 v148, v[92:93], s[10:11] offset:1536
	s_add_u32 s10, s10, s18
	s_addc_u32 s11, s11, 0
	v_mul_f32_e32 v144, v96, v96
	v_fmac_f32_e32 v144, v97, v97
	v_fmac_f32_e32 v144, v98, v98
	v_fmac_f32_e32 v144, v99, v99
	v_fmac_f32_e32 v144, v100, v100
	v_fmac_f32_e32 v144, v101, v101
	v_fmac_f32_e32 v144, v102, v102
	v_fmac_f32_e32 v144, v103, v103
	v_fmac_f32_e32 v144, v104, v104
	v_fmac_f32_e32 v144, v105, v105
	v_fmac_f32_e32 v144, v106, v106
	v_fmac_f32_e32 v144, v107, v107
	v_fmac_f32_e32 v144, v108, v108
	v_fmac_f32_e32 v144, v109, v109
	v_fmac_f32_e32 v144, v110, v110
	v_fmac_f32_e32 v144, v111, v111
	s_nop 1
	v_add_f32_dpp v144, v144, v144 quad_perm:[1,0,3,2] row_mask:0xf bank_mask:0xf
	s_nop 1
	v_add_f32_dpp v144, v144, v144 quad_perm:[2,3,0,1] row_mask:0xf bank_mask:0xf
	s_nop 1
	v_add_f32_dpp v144, v144, v144 row_half_mirror row_mask:0xf bank_mask:0xf
	s_nop 1
	v_add_f32_dpp v144, v144, v144 row_mirror row_mask:0xf bank_mask:0xf
	v_mov_b32_e32 v145, v144
	s_nop 1
	v_permlane16_swap_b32_e32 v144, v145
	v_add_f32_e32 v144, v144, v145
	v_mov_b32_e32 v145, v144
	s_nop 1
	v_permlane32_swap_b32_e32 v144, v145
	v_add_f32_e32 v144, v144, v145
	v_fmamk_f32 v144, v144, 0x3a800000, v147
	v_mul_f32_e32 v145, 0x4b800000, v144
	v_cmp_gt_f32_e32 vcc, s19, v144
	s_nop 1
	v_cndmask_b32_e32 v144, v144, v145, vcc
	v_rsq_f32_e32 v144, v144
	s_nop 0
	v_mul_f32_e32 v145, 0x45800000, v144
	v_cndmask_b32_e32 v144, v144, v145, vcc
	v_mul_f32_e32 v96, v96, v144
	v_mul_f32_e32 v96, v64, v96
	v_mul_f32_e32 v97, v97, v144
	v_mul_f32_e32 v97, v65, v97
	v_mul_f32_e32 v98, v98, v144
	v_mul_f32_e32 v98, v66, v98
	v_mul_f32_e32 v99, v99, v144
	v_mul_f32_e32 v99, v67, v99
	v_cvt_pk_bf16_f32 v96, v96, v97
	v_cvt_pk_bf16_f32 v97, v98, v99
	global_store_dwordx2 v148, v[96:97], s[10:11] offset:0
	v_mul_f32_e32 v100, v100, v144
	v_mul_f32_e32 v100, v68, v100
	v_mul_f32_e32 v101, v101, v144
	v_mul_f32_e32 v101, v69, v101
	v_mul_f32_e32 v102, v102, v144
	v_mul_f32_e32 v102, v70, v102
	v_mul_f32_e32 v103, v103, v144
	v_mul_f32_e32 v103, v71, v103
	v_cvt_pk_bf16_f32 v100, v100, v101
	v_cvt_pk_bf16_f32 v101, v102, v103
	global_store_dwordx2 v148, v[100:101], s[10:11] offset:512
	v_mul_f32_e32 v104, v104, v144
	v_mul_f32_e32 v104, v72, v104
	v_mul_f32_e32 v105, v105, v144
	v_mul_f32_e32 v105, v73, v105
	v_mul_f32_e32 v106, v106, v144
	v_mul_f32_e32 v106, v74, v106
	v_mul_f32_e32 v107, v107, v144
	v_mul_f32_e32 v107, v75, v107
	v_cvt_pk_bf16_f32 v104, v104, v105
	v_cvt_pk_bf16_f32 v105, v106, v107
	global_store_dwordx2 v148, v[104:105], s[10:11] offset:1024
	v_mul_f32_e32 v108, v108, v144
	v_mul_f32_e32 v108, v76, v108
	v_mul_f32_e32 v109, v109, v144
	v_mul_f32_e32 v109, v77, v109
	v_mul_f32_e32 v110, v110, v144
	v_mul_f32_e32 v110, v78, v110
	v_mul_f32_e32 v111, v111, v144
	v_mul_f32_e32 v111, v79, v111
	v_cvt_pk_bf16_f32 v108, v108, v109
	v_cvt_pk_bf16_f32 v109, v110, v111
	global_store_dwordx2 v148, v[108:109], s[10:11] offset:1536
	s_add_u32 s10, s10, s18
	s_addc_u32 s11, s11, 0
	v_mul_f32_e32 v144, v112, v112
	v_fmac_f32_e32 v144, v113, v113
	v_fmac_f32_e32 v144, v114, v114
	v_fmac_f32_e32 v144, v115, v115
	v_fmac_f32_e32 v144, v116, v116
	v_fmac_f32_e32 v144, v117, v117
	v_fmac_f32_e32 v144, v118, v118
	v_fmac_f32_e32 v144, v119, v119
	v_fmac_f32_e32 v144, v120, v120
	v_fmac_f32_e32 v144, v121, v121
	v_fmac_f32_e32 v144, v122, v122
	v_fmac_f32_e32 v144, v123, v123
	v_fmac_f32_e32 v144, v124, v124
	v_fmac_f32_e32 v144, v125, v125
	v_fmac_f32_e32 v144, v126, v126
	v_fmac_f32_e32 v144, v127, v127
	s_nop 1
	v_add_f32_dpp v144, v144, v144 quad_perm:[1,0,3,2] row_mask:0xf bank_mask:0xf
	s_nop 1
	v_add_f32_dpp v144, v144, v144 quad_perm:[2,3,0,1] row_mask:0xf bank_mask:0xf
	s_nop 1
	v_add_f32_dpp v144, v144, v144 row_half_mirror row_mask:0xf bank_mask:0xf
	s_nop 1
	v_add_f32_dpp v144, v144, v144 row_mirror row_mask:0xf bank_mask:0xf
	v_mov_b32_e32 v145, v144
	s_nop 1
	v_permlane16_swap_b32_e32 v144, v145
	v_add_f32_e32 v144, v144, v145
	v_mov_b32_e32 v145, v144
	s_nop 1
	v_permlane32_swap_b32_e32 v144, v145
	v_add_f32_e32 v144, v144, v145
	v_fmamk_f32 v144, v144, 0x3a800000, v147
	v_mul_f32_e32 v145, 0x4b800000, v144
	v_cmp_gt_f32_e32 vcc, s19, v144
	s_nop 1
	v_cndmask_b32_e32 v144, v144, v145, vcc
	v_rsq_f32_e32 v144, v144
	s_nop 0
	v_mul_f32_e32 v145, 0x45800000, v144
	v_cndmask_b32_e32 v144, v144, v145, vcc
	v_mul_f32_e32 v112, v112, v144
	v_mul_f32_e32 v112, v64, v112
	v_mul_f32_e32 v113, v113, v144
	v_mul_f32_e32 v113, v65, v113
	v_mul_f32_e32 v114, v114, v144
	v_mul_f32_e32 v114, v66, v114
	v_mul_f32_e32 v115, v115, v144
	v_mul_f32_e32 v115, v67, v115
	v_cvt_pk_bf16_f32 v112, v112, v113
	v_cvt_pk_bf16_f32 v113, v114, v115
	global_store_dwordx2 v148, v[112:113], s[10:11] offset:0
	v_mul_f32_e32 v116, v116, v144
	v_mul_f32_e32 v116, v68, v116
	v_mul_f32_e32 v117, v117, v144
	v_mul_f32_e32 v117, v69, v117
	v_mul_f32_e32 v118, v118, v144
	v_mul_f32_e32 v118, v70, v118
	v_mul_f32_e32 v119, v119, v144
	v_mul_f32_e32 v119, v71, v119
	v_cvt_pk_bf16_f32 v116, v116, v117
	v_cvt_pk_bf16_f32 v117, v118, v119
	global_store_dwordx2 v148, v[116:117], s[10:11] offset:512
	v_mul_f32_e32 v120, v120, v144
	v_mul_f32_e32 v120, v72, v120
	v_mul_f32_e32 v121, v121, v144
	v_mul_f32_e32 v121, v73, v121
	v_mul_f32_e32 v122, v122, v144
	v_mul_f32_e32 v122, v74, v122
	v_mul_f32_e32 v123, v123, v144
	v_mul_f32_e32 v123, v75, v123
	v_cvt_pk_bf16_f32 v120, v120, v121
	v_cvt_pk_bf16_f32 v121, v122, v123
	global_store_dwordx2 v148, v[120:121], s[10:11] offset:1024
	v_mul_f32_e32 v124, v124, v144
	v_mul_f32_e32 v124, v76, v124
	v_mul_f32_e32 v125, v125, v144
	v_mul_f32_e32 v125, v77, v125
	v_mul_f32_e32 v126, v126, v144
	v_mul_f32_e32 v126, v78, v126
	v_mul_f32_e32 v127, v127, v144
	v_mul_f32_e32 v127, v79, v127
	v_cvt_pk_bf16_f32 v124, v124, v125
	v_cvt_pk_bf16_f32 v125, v126, v127
	global_store_dwordx2 v148, v[124:125], s[10:11] offset:1536
	s_add_u32 s10, s10, s18
	s_addc_u32 s11, s11, 0
	v_mul_f32_e32 v144, v128, v128
	v_fmac_f32_e32 v144, v129, v129
	v_fmac_f32_e32 v144, v130, v130
	v_fmac_f32_e32 v144, v131, v131
	v_fmac_f32_e32 v144, v132, v132
	v_fmac_f32_e32 v144, v133, v133
	v_fmac_f32_e32 v144, v134, v134
	v_fmac_f32_e32 v144, v135, v135
	v_fmac_f32_e32 v144, v136, v136
	v_fmac_f32_e32 v144, v137, v137
	v_fmac_f32_e32 v144, v138, v138
	v_fmac_f32_e32 v144, v139, v139
	v_fmac_f32_e32 v144, v140, v140
	v_fmac_f32_e32 v144, v141, v141
	v_fmac_f32_e32 v144, v142, v142
	v_fmac_f32_e32 v144, v143, v143
	s_nop 1
	v_add_f32_dpp v144, v144, v144 quad_perm:[1,0,3,2] row_mask:0xf bank_mask:0xf
	s_nop 1
	v_add_f32_dpp v144, v144, v144 quad_perm:[2,3,0,1] row_mask:0xf bank_mask:0xf
	s_nop 1
	v_add_f32_dpp v144, v144, v144 row_half_mirror row_mask:0xf bank_mask:0xf
	s_nop 1
	v_add_f32_dpp v144, v144, v144 row_mirror row_mask:0xf bank_mask:0xf
	v_mov_b32_e32 v145, v144
	s_nop 1
	v_permlane16_swap_b32_e32 v144, v145
	v_add_f32_e32 v144, v144, v145
	v_mov_b32_e32 v145, v144
	s_nop 1
	v_permlane32_swap_b32_e32 v144, v145
	v_add_f32_e32 v144, v144, v145
	v_fmamk_f32 v144, v144, 0x3a800000, v147
	v_mul_f32_e32 v145, 0x4b800000, v144
	v_cmp_gt_f32_e32 vcc, s19, v144
	s_nop 1
	v_cndmask_b32_e32 v144, v144, v145, vcc
	v_rsq_f32_e32 v144, v144
	s_nop 0
	v_mul_f32_e32 v145, 0x45800000, v144
	v_cndmask_b32_e32 v144, v144, v145, vcc
	v_mul_f32_e32 v128, v128, v144
	v_mul_f32_e32 v128, v64, v128
	v_mul_f32_e32 v129, v129, v144
	v_mul_f32_e32 v129, v65, v129
	v_mul_f32_e32 v130, v130, v144
	v_mul_f32_e32 v130, v66, v130
	v_mul_f32_e32 v131, v131, v144
	v_mul_f32_e32 v131, v67, v131
	v_cvt_pk_bf16_f32 v128, v128, v129
	v_cvt_pk_bf16_f32 v129, v130, v131
	global_store_dwordx2 v148, v[128:129], s[10:11] offset:0
	v_mul_f32_e32 v132, v132, v144
	v_mul_f32_e32 v132, v68, v132
	v_mul_f32_e32 v133, v133, v144
	v_mul_f32_e32 v133, v69, v133
	v_mul_f32_e32 v134, v134, v144
	v_mul_f32_e32 v134, v70, v134
	v_mul_f32_e32 v135, v135, v144
	v_mul_f32_e32 v135, v71, v135
	v_cvt_pk_bf16_f32 v132, v132, v133
	v_cvt_pk_bf16_f32 v133, v134, v135
	global_store_dwordx2 v148, v[132:133], s[10:11] offset:512
	v_mul_f32_e32 v136, v136, v144
	v_mul_f32_e32 v136, v72, v136
	v_mul_f32_e32 v137, v137, v144
	v_mul_f32_e32 v137, v73, v137
	v_mul_f32_e32 v138, v138, v144
	v_mul_f32_e32 v138, v74, v138
	v_mul_f32_e32 v139, v139, v144
	v_mul_f32_e32 v139, v75, v139
	v_cvt_pk_bf16_f32 v136, v136, v137
	v_cvt_pk_bf16_f32 v137, v138, v139
	global_store_dwordx2 v148, v[136:137], s[10:11] offset:1024
	v_mul_f32_e32 v140, v140, v144
	v_mul_f32_e32 v140, v76, v140
	v_mul_f32_e32 v141, v141, v144
	v_mul_f32_e32 v141, v77, v141
	v_mul_f32_e32 v142, v142, v144
	v_mul_f32_e32 v142, v78, v142
	v_mul_f32_e32 v143, v143, v144
	v_mul_f32_e32 v143, v79, v143
	v_cvt_pk_bf16_f32 v140, v140, v141
	v_cvt_pk_bf16_f32 v141, v142, v143
	global_store_dwordx2 v148, v[140:141], s[10:11] offset:1536
	s_add_u32 s10, s10, s18
	s_addc_u32 s11, s11, 0
	global_load_dwordx4 v[80:83], v229, s[8:9] offset:0
	global_load_dwordx4 v[84:87], v229, s[8:9] offset:1024
	global_load_dwordx4 v[88:91], v229, s[8:9] offset:2048
	global_load_dwordx4 v[92:95], v229, s[8:9] offset:3072
	s_add_u32 s8, s8, s16
	s_addc_u32 s9, s9, 0
	global_load_dwordx4 v[96:99], v229, s[8:9] offset:0
	global_load_dwordx4 v[100:103], v229, s[8:9] offset:1024
	global_load_dwordx4 v[104:107], v229, s[8:9] offset:2048
	global_load_dwordx4 v[108:111], v229, s[8:9] offset:3072
	s_add_u32 s8, s8, s16
	s_addc_u32 s9, s9, 0
	global_load_dwordx4 v[112:115], v229, s[8:9] offset:0
	global_load_dwordx4 v[116:119], v229, s[8:9] offset:1024
	global_load_dwordx4 v[120:123], v229, s[8:9] offset:2048
	global_load_dwordx4 v[124:127], v229, s[8:9] offset:3072
	s_add_u32 s8, s8, s16
	s_addc_u32 s9, s9, 0
	global_load_dwordx4 v[128:131], v229, s[8:9] offset:0
	global_load_dwordx4 v[132:135], v229, s[8:9] offset:1024
	global_load_dwordx4 v[136:139], v229, s[8:9] offset:2048
	global_load_dwordx4 v[140:143], v229, s[8:9] offset:3072
	s_add_u32 s8, s8, s16
	s_addc_u32 s9, s9, 0
	s_waitcnt vmcnt(0)
	v_mul_f32_e32 v144, v80, v80
	v_fmac_f32_e32 v144, v81, v81
	v_fmac_f32_e32 v144, v82, v82
	v_fmac_f32_e32 v144, v83, v83
	v_fmac_f32_e32 v144, v84, v84
	v_fmac_f32_e32 v144, v85, v85
	v_fmac_f32_e32 v144, v86, v86
	v_fmac_f32_e32 v144, v87, v87
	v_fmac_f32_e32 v144, v88, v88
	v_fmac_f32_e32 v144, v89, v89
	v_fmac_f32_e32 v144, v90, v90
	v_fmac_f32_e32 v144, v91, v91
	v_fmac_f32_e32 v144, v92, v92
	v_fmac_f32_e32 v144, v93, v93
	v_fmac_f32_e32 v144, v94, v94
	v_fmac_f32_e32 v144, v95, v95
	s_nop 1
	v_add_f32_dpp v144, v144, v144 quad_perm:[1,0,3,2] row_mask:0xf bank_mask:0xf
	s_nop 1
	v_add_f32_dpp v144, v144, v144 quad_perm:[2,3,0,1] row_mask:0xf bank_mask:0xf
	s_nop 1
	v_add_f32_dpp v144, v144, v144 row_half_mirror row_mask:0xf bank_mask:0xf
	s_nop 1
	v_add_f32_dpp v144, v144, v144 row_mirror row_mask:0xf bank_mask:0xf
	v_mov_b32_e32 v145, v144
	s_nop 1
	v_permlane16_swap_b32_e32 v144, v145
	v_add_f32_e32 v144, v144, v145
	v_mov_b32_e32 v145, v144
	s_nop 1
	v_permlane32_swap_b32_e32 v144, v145
	v_add_f32_e32 v144, v144, v145
	v_fmamk_f32 v144, v144, 0x3a800000, v147
	v_mul_f32_e32 v145, 0x4b800000, v144
	v_cmp_gt_f32_e32 vcc, s19, v144
	s_nop 1
	v_cndmask_b32_e32 v144, v144, v145, vcc
	v_rsq_f32_e32 v144, v144
	s_nop 0
	v_mul_f32_e32 v145, 0x45800000, v144
	v_cndmask_b32_e32 v144, v144, v145, vcc
	v_mul_f32_e32 v80, v80, v144
	v_mul_f32_e32 v80, v64, v80
	v_mul_f32_e32 v81, v81, v144
	v_mul_f32_e32 v81, v65, v81
	v_mul_f32_e32 v82, v82, v144
	v_mul_f32_e32 v82, v66, v82
	v_mul_f32_e32 v83, v83, v144
	v_mul_f32_e32 v83, v67, v83
	v_cvt_pk_bf16_f32 v80, v80, v81
	v_cvt_pk_bf16_f32 v81, v82, v83
	global_store_dwordx2 v148, v[80:81], s[10:11] offset:0
	v_mul_f32_e32 v84, v84, v144
	v_mul_f32_e32 v84, v68, v84
	v_mul_f32_e32 v85, v85, v144
	v_mul_f32_e32 v85, v69, v85
	v_mul_f32_e32 v86, v86, v144
	v_mul_f32_e32 v86, v70, v86
	v_mul_f32_e32 v87, v87, v144
	v_mul_f32_e32 v87, v71, v87
	v_cvt_pk_bf16_f32 v84, v84, v85
	v_cvt_pk_bf16_f32 v85, v86, v87
	global_store_dwordx2 v148, v[84:85], s[10:11] offset:512
	v_mul_f32_e32 v88, v88, v144
	v_mul_f32_e32 v88, v72, v88
	v_mul_f32_e32 v89, v89, v144
	v_mul_f32_e32 v89, v73, v89
	v_mul_f32_e32 v90, v90, v144
	v_mul_f32_e32 v90, v74, v90
	v_mul_f32_e32 v91, v91, v144
	v_mul_f32_e32 v91, v75, v91
	v_cvt_pk_bf16_f32 v88, v88, v89
	v_cvt_pk_bf16_f32 v89, v90, v91
	global_store_dwordx2 v148, v[88:89], s[10:11] offset:1024
	v_mul_f32_e32 v92, v92, v144
	v_mul_f32_e32 v92, v76, v92
	v_mul_f32_e32 v93, v93, v144
	v_mul_f32_e32 v93, v77, v93
	v_mul_f32_e32 v94, v94, v144
	v_mul_f32_e32 v94, v78, v94
	v_mul_f32_e32 v95, v95, v144
	v_mul_f32_e32 v95, v79, v95
	v_cvt_pk_bf16_f32 v92, v92, v93
	v_cvt_pk_bf16_f32 v93, v94, v95
	global_store_dwordx2 v148, v[92:93], s[10:11] offset:1536
	s_add_u32 s10, s10, s18
	s_addc_u32 s11, s11, 0
	v_mul_f32_e32 v144, v96, v96
	v_fmac_f32_e32 v144, v97, v97
	v_fmac_f32_e32 v144, v98, v98
	v_fmac_f32_e32 v144, v99, v99
	v_fmac_f32_e32 v144, v100, v100
	v_fmac_f32_e32 v144, v101, v101
	v_fmac_f32_e32 v144, v102, v102
	v_fmac_f32_e32 v144, v103, v103
	v_fmac_f32_e32 v144, v104, v104
	v_fmac_f32_e32 v144, v105, v105
	v_fmac_f32_e32 v144, v106, v106
	v_fmac_f32_e32 v144, v107, v107
	v_fmac_f32_e32 v144, v108, v108
	v_fmac_f32_e32 v144, v109, v109
	v_fmac_f32_e32 v144, v110, v110
	v_fmac_f32_e32 v144, v111, v111
	s_nop 1
	v_add_f32_dpp v144, v144, v144 quad_perm:[1,0,3,2] row_mask:0xf bank_mask:0xf
	s_nop 1
	v_add_f32_dpp v144, v144, v144 quad_perm:[2,3,0,1] row_mask:0xf bank_mask:0xf
	s_nop 1
	v_add_f32_dpp v144, v144, v144 row_half_mirror row_mask:0xf bank_mask:0xf
	s_nop 1
	v_add_f32_dpp v144, v144, v144 row_mirror row_mask:0xf bank_mask:0xf
	v_mov_b32_e32 v145, v144
	s_nop 1
	v_permlane16_swap_b32_e32 v144, v145
	v_add_f32_e32 v144, v144, v145
	v_mov_b32_e32 v145, v144
	s_nop 1
	v_permlane32_swap_b32_e32 v144, v145
	v_add_f32_e32 v144, v144, v145
	v_fmamk_f32 v144, v144, 0x3a800000, v147
	v_mul_f32_e32 v145, 0x4b800000, v144
	v_cmp_gt_f32_e32 vcc, s19, v144
	s_nop 1
	v_cndmask_b32_e32 v144, v144, v145, vcc
	v_rsq_f32_e32 v144, v144
	s_nop 0
	v_mul_f32_e32 v145, 0x45800000, v144
	v_cndmask_b32_e32 v144, v144, v145, vcc
	v_mul_f32_e32 v96, v96, v144
	v_mul_f32_e32 v96, v64, v96
	v_mul_f32_e32 v97, v97, v144
	v_mul_f32_e32 v97, v65, v97
	v_mul_f32_e32 v98, v98, v144
	v_mul_f32_e32 v98, v66, v98
	v_mul_f32_e32 v99, v99, v144
	v_mul_f32_e32 v99, v67, v99
	v_cvt_pk_bf16_f32 v96, v96, v97
	v_cvt_pk_bf16_f32 v97, v98, v99
	global_store_dwordx2 v148, v[96:97], s[10:11] offset:0
	v_mul_f32_e32 v100, v100, v144
	v_mul_f32_e32 v100, v68, v100
	v_mul_f32_e32 v101, v101, v144
	v_mul_f32_e32 v101, v69, v101
	v_mul_f32_e32 v102, v102, v144
	v_mul_f32_e32 v102, v70, v102
	v_mul_f32_e32 v103, v103, v144
	v_mul_f32_e32 v103, v71, v103
	v_cvt_pk_bf16_f32 v100, v100, v101
	v_cvt_pk_bf16_f32 v101, v102, v103
	global_store_dwordx2 v148, v[100:101], s[10:11] offset:512
	v_mul_f32_e32 v104, v104, v144
	v_mul_f32_e32 v104, v72, v104
	v_mul_f32_e32 v105, v105, v144
	v_mul_f32_e32 v105, v73, v105
	v_mul_f32_e32 v106, v106, v144
	v_mul_f32_e32 v106, v74, v106
	v_mul_f32_e32 v107, v107, v144
	v_mul_f32_e32 v107, v75, v107
	v_cvt_pk_bf16_f32 v104, v104, v105
	v_cvt_pk_bf16_f32 v105, v106, v107
	global_store_dwordx2 v148, v[104:105], s[10:11] offset:1024
	v_mul_f32_e32 v108, v108, v144
	v_mul_f32_e32 v108, v76, v108
	v_mul_f32_e32 v109, v109, v144
	v_mul_f32_e32 v109, v77, v109
	v_mul_f32_e32 v110, v110, v144
	v_mul_f32_e32 v110, v78, v110
	v_mul_f32_e32 v111, v111, v144
	v_mul_f32_e32 v111, v79, v111
	v_cvt_pk_bf16_f32 v108, v108, v109
	v_cvt_pk_bf16_f32 v109, v110, v111
	global_store_dwordx2 v148, v[108:109], s[10:11] offset:1536
	s_add_u32 s10, s10, s18
	s_addc_u32 s11, s11, 0
	v_mul_f32_e32 v144, v112, v112
	v_fmac_f32_e32 v144, v113, v113
	v_fmac_f32_e32 v144, v114, v114
	v_fmac_f32_e32 v144, v115, v115
	v_fmac_f32_e32 v144, v116, v116
	v_fmac_f32_e32 v144, v117, v117
	v_fmac_f32_e32 v144, v118, v118
	v_fmac_f32_e32 v144, v119, v119
	v_fmac_f32_e32 v144, v120, v120
	v_fmac_f32_e32 v144, v121, v121
	v_fmac_f32_e32 v144, v122, v122
	v_fmac_f32_e32 v144, v123, v123
	v_fmac_f32_e32 v144, v124, v124
	v_fmac_f32_e32 v144, v125, v125
	v_fmac_f32_e32 v144, v126, v126
	v_fmac_f32_e32 v144, v127, v127
	s_nop 1
	v_add_f32_dpp v144, v144, v144 quad_perm:[1,0,3,2] row_mask:0xf bank_mask:0xf
	s_nop 1
	v_add_f32_dpp v144, v144, v144 quad_perm:[2,3,0,1] row_mask:0xf bank_mask:0xf
	s_nop 1
	v_add_f32_dpp v144, v144, v144 row_half_mirror row_mask:0xf bank_mask:0xf
	s_nop 1
	v_add_f32_dpp v144, v144, v144 row_mirror row_mask:0xf bank_mask:0xf
	v_mov_b32_e32 v145, v144
	s_nop 1
	v_permlane16_swap_b32_e32 v144, v145
	v_add_f32_e32 v144, v144, v145
	v_mov_b32_e32 v145, v144
	s_nop 1
	v_permlane32_swap_b32_e32 v144, v145
	v_add_f32_e32 v144, v144, v145
	v_fmamk_f32 v144, v144, 0x3a800000, v147
	v_mul_f32_e32 v145, 0x4b800000, v144
	v_cmp_gt_f32_e32 vcc, s19, v144
	s_nop 1
	v_cndmask_b32_e32 v144, v144, v145, vcc
	v_rsq_f32_e32 v144, v144
	s_nop 0
	v_mul_f32_e32 v145, 0x45800000, v144
	v_cndmask_b32_e32 v144, v144, v145, vcc
	v_mul_f32_e32 v112, v112, v144
	v_mul_f32_e32 v112, v64, v112
	v_mul_f32_e32 v113, v113, v144
	v_mul_f32_e32 v113, v65, v113
	v_mul_f32_e32 v114, v114, v144
	v_mul_f32_e32 v114, v66, v114
	v_mul_f32_e32 v115, v115, v144
	v_mul_f32_e32 v115, v67, v115
	v_cvt_pk_bf16_f32 v112, v112, v113
	v_cvt_pk_bf16_f32 v113, v114, v115
	global_store_dwordx2 v148, v[112:113], s[10:11] offset:0
	v_mul_f32_e32 v116, v116, v144
	v_mul_f32_e32 v116, v68, v116
	v_mul_f32_e32 v117, v117, v144
	v_mul_f32_e32 v117, v69, v117
	v_mul_f32_e32 v118, v118, v144
	v_mul_f32_e32 v118, v70, v118
	v_mul_f32_e32 v119, v119, v144
	v_mul_f32_e32 v119, v71, v119
	v_cvt_pk_bf16_f32 v116, v116, v117
	v_cvt_pk_bf16_f32 v117, v118, v119
	global_store_dwordx2 v148, v[116:117], s[10:11] offset:512
	v_mul_f32_e32 v120, v120, v144
	v_mul_f32_e32 v120, v72, v120
	v_mul_f32_e32 v121, v121, v144
	v_mul_f32_e32 v121, v73, v121
	v_mul_f32_e32 v122, v122, v144
	v_mul_f32_e32 v122, v74, v122
	v_mul_f32_e32 v123, v123, v144
	v_mul_f32_e32 v123, v75, v123
	v_cvt_pk_bf16_f32 v120, v120, v121
	v_cvt_pk_bf16_f32 v121, v122, v123
	global_store_dwordx2 v148, v[120:121], s[10:11] offset:1024
	v_mul_f32_e32 v124, v124, v144
	v_mul_f32_e32 v124, v76, v124
	v_mul_f32_e32 v125, v125, v144
	v_mul_f32_e32 v125, v77, v125
	v_mul_f32_e32 v126, v126, v144
	v_mul_f32_e32 v126, v78, v126
	v_mul_f32_e32 v127, v127, v144
	v_mul_f32_e32 v127, v79, v127
	v_cvt_pk_bf16_f32 v124, v124, v125
	v_cvt_pk_bf16_f32 v125, v126, v127
	global_store_dwordx2 v148, v[124:125], s[10:11] offset:1536
	s_add_u32 s10, s10, s18
	s_addc_u32 s11, s11, 0
	v_mul_f32_e32 v144, v128, v128
	v_fmac_f32_e32 v144, v129, v129
	v_fmac_f32_e32 v144, v130, v130
	v_fmac_f32_e32 v144, v131, v131
	v_fmac_f32_e32 v144, v132, v132
	v_fmac_f32_e32 v144, v133, v133
	v_fmac_f32_e32 v144, v134, v134
	v_fmac_f32_e32 v144, v135, v135
	v_fmac_f32_e32 v144, v136, v136
	v_fmac_f32_e32 v144, v137, v137
	v_fmac_f32_e32 v144, v138, v138
	v_fmac_f32_e32 v144, v139, v139
	v_fmac_f32_e32 v144, v140, v140
	v_fmac_f32_e32 v144, v141, v141
	v_fmac_f32_e32 v144, v142, v142
	v_fmac_f32_e32 v144, v143, v143
	s_nop 1
	v_add_f32_dpp v144, v144, v144 quad_perm:[1,0,3,2] row_mask:0xf bank_mask:0xf
	s_nop 1
	v_add_f32_dpp v144, v144, v144 quad_perm:[2,3,0,1] row_mask:0xf bank_mask:0xf
	s_nop 1
	v_add_f32_dpp v144, v144, v144 row_half_mirror row_mask:0xf bank_mask:0xf
	s_nop 1
	v_add_f32_dpp v144, v144, v144 row_mirror row_mask:0xf bank_mask:0xf
	v_mov_b32_e32 v145, v144
	s_nop 1
	v_permlane16_swap_b32_e32 v144, v145
	v_add_f32_e32 v144, v144, v145
	v_mov_b32_e32 v145, v144
	s_nop 1
	v_permlane32_swap_b32_e32 v144, v145
	v_add_f32_e32 v144, v144, v145
	v_fmamk_f32 v144, v144, 0x3a800000, v147
	v_mul_f32_e32 v145, 0x4b800000, v144
	v_cmp_gt_f32_e32 vcc, s19, v144
	s_nop 1
	v_cndmask_b32_e32 v144, v144, v145, vcc
	v_rsq_f32_e32 v144, v144
	s_nop 0
	v_mul_f32_e32 v145, 0x45800000, v144
	v_cndmask_b32_e32 v144, v144, v145, vcc
	v_mul_f32_e32 v128, v128, v144
	v_mul_f32_e32 v128, v64, v128
	v_mul_f32_e32 v129, v129, v144
	v_mul_f32_e32 v129, v65, v129
	v_mul_f32_e32 v130, v130, v144
	v_mul_f32_e32 v130, v66, v130
	v_mul_f32_e32 v131, v131, v144
	v_mul_f32_e32 v131, v67, v131
	v_cvt_pk_bf16_f32 v128, v128, v129
	v_cvt_pk_bf16_f32 v129, v130, v131
	global_store_dwordx2 v148, v[128:129], s[10:11] offset:0
	v_mul_f32_e32 v132, v132, v144
	v_mul_f32_e32 v132, v68, v132
	v_mul_f32_e32 v133, v133, v144
	v_mul_f32_e32 v133, v69, v133
	v_mul_f32_e32 v134, v134, v144
	v_mul_f32_e32 v134, v70, v134
	v_mul_f32_e32 v135, v135, v144
	v_mul_f32_e32 v135, v71, v135
	v_cvt_pk_bf16_f32 v132, v132, v133
	v_cvt_pk_bf16_f32 v133, v134, v135
	global_store_dwordx2 v148, v[132:133], s[10:11] offset:512
	v_mul_f32_e32 v136, v136, v144
	v_mul_f32_e32 v136, v72, v136
	v_mul_f32_e32 v137, v137, v144
	v_mul_f32_e32 v137, v73, v137
	v_mul_f32_e32 v138, v138, v144
	v_mul_f32_e32 v138, v74, v138
	v_mul_f32_e32 v139, v139, v144
	v_mul_f32_e32 v139, v75, v139
	v_cvt_pk_bf16_f32 v136, v136, v137
	v_cvt_pk_bf16_f32 v137, v138, v139
	global_store_dwordx2 v148, v[136:137], s[10:11] offset:1024
	v_mul_f32_e32 v140, v140, v144
	v_mul_f32_e32 v140, v76, v140
	v_mul_f32_e32 v141, v141, v144
	v_mul_f32_e32 v141, v77, v141
	v_mul_f32_e32 v142, v142, v144
	v_mul_f32_e32 v142, v78, v142
	v_mul_f32_e32 v143, v143, v144
	v_mul_f32_e32 v143, v79, v143
	v_cvt_pk_bf16_f32 v140, v140, v141
	v_cvt_pk_bf16_f32 v141, v142, v143
	global_store_dwordx2 v148, v[140:141], s[10:11] offset:1536
	s_add_u32 s10, s10, s18
	s_addc_u32 s11, s11, 0
	s_waitcnt vmcnt(0)
	s_lshl_b32 s15, s92, 6
	s_add_u32 s101, s101, s15
	s_cmpk_lt_u32 s101, 0x8000
	s_cbranch_scc1 .Lgv0_chunk
	s_branch .LBB0_637

.Lgv1_chunk:
	s_movk_i32 s100, 0xc0
	s_lshl_b32 s16, s92, 14
	s_add_u32 s12, s26, 0xd800000
	s_addc_u32 s13, s27, 0
	s_lshl_b32 s15, s101, 9
	s_add_u32 s12, s12, s15
	s_addc_u32 s13, s13, 0
	s_lshl_b32 s18, s92, 11
	global_load_dword v96, v216, s[12:13]
	global_load_dword v97, v216, s[12:13] offset:256
	s_add_u32 s12, s12, s18
	s_addc_u32 s13, s13, 0
	global_load_dword v98, v216, s[12:13]
	global_load_dword v99, v216, s[12:13] offset:256
	s_add_u32 s12, s12, s18
	s_addc_u32 s13, s13, 0
	global_load_dword v100, v216, s[12:13]
	global_load_dword v101, v216, s[12:13] offset:256
	s_add_u32 s12, s12, s18
	s_addc_u32 s13, s13, 0
	global_load_dword v102, v216, s[12:13]
	global_load_dword v103, v216, s[12:13] offset:256
	s_add_u32 s12, s12, s18
	s_addc_u32 s13, s13, 0
	global_load_dword v104, v216, s[12:13]
	global_load_dword v105, v216, s[12:13] offset:256
	s_add_u32 s12, s12, s18
	s_addc_u32 s13, s13, 0
	global_load_dword v106, v216, s[12:13]
	global_load_dword v107, v216, s[12:13] offset:256
	s_add_u32 s12, s12, s18
	s_addc_u32 s13, s13, 0
	global_load_dword v108, v216, s[12:13]
	global_load_dword v109, v216, s[12:13] offset:256
	s_add_u32 s12, s12, s18
	s_addc_u32 s13, s13, 0
	global_load_dword v110, v216, s[12:13]
	global_load_dword v111, v216, s[12:13] offset:256
	s_add_u32 s12, s12, s18
	s_addc_u32 s13, s13, 0
	global_load_dword v112, v216, s[12:13]
	global_load_dword v113, v216, s[12:13] offset:256
	s_add_u32 s12, s12, s18
	s_addc_u32 s13, s13, 0
	global_load_dword v114, v216, s[12:13]
	global_load_dword v115, v216, s[12:13] offset:256
	s_add_u32 s12, s12, s18
	s_addc_u32 s13, s13, 0
	global_load_dword v116, v216, s[12:13]
	global_load_dword v117, v216, s[12:13] offset:256
	s_add_u32 s12, s12, s18
	s_addc_u32 s13, s13, 0
	global_load_dword v118, v216, s[12:13]
	global_load_dword v119, v216, s[12:13] offset:256
	s_add_u32 s12, s12, s18
	s_addc_u32 s13, s13, 0
	global_load_dword v120, v216, s[12:13]
	global_load_dword v121, v216, s[12:13] offset:256
	s_add_u32 s12, s12, s18
	s_addc_u32 s13, s13, 0
	global_load_dword v122, v216, s[12:13]
	global_load_dword v123, v216, s[12:13] offset:256
	s_add_u32 s12, s12, s18
	s_addc_u32 s13, s13, 0
	global_load_dword v124, v216, s[12:13]
	global_load_dword v125, v216, s[12:13] offset:256
	s_add_u32 s12, s12, s18
	s_addc_u32 s13, s13, 0
	global_load_dword v126, v216, s[12:13]
	global_load_dword v127, v216, s[12:13] offset:256
	s_add_u32 s12, s12, s18
	s_addc_u32 s13, s13, 0
	s_waitcnt vmcnt(0)
	ds_write2st64_b32 v225, v96, v97 offset0:0 offset1:1
	ds_write2st64_b32 v225, v98, v99 offset0:2 offset1:3
	ds_write2st64_b32 v225, v100, v101 offset0:4 offset1:5
	ds_write2st64_b32 v225, v102, v103 offset0:6 offset1:7
	ds_write2st64_b32 v225, v104, v105 offset0:8 offset1:9
	ds_write2st64_b32 v225, v106, v107 offset0:10 offset1:11
	ds_write2st64_b32 v225, v108, v109 offset0:12 offset1:13
	ds_write2st64_b32 v225, v110, v111 offset0:14 offset1:15
	ds_write2st64_b32 v225, v112, v113 offset0:16 offset1:17
	ds_write2st64_b32 v225, v114, v115 offset0:18 offset1:19
	ds_write2st64_b32 v225, v116, v117 offset0:20 offset1:21
	ds_write2st64_b32 v225, v118, v119 offset0:22 offset1:23
	ds_write2st64_b32 v225, v120, v121 offset0:24 offset1:25
	ds_write2st64_b32 v225, v122, v123 offset0:26 offset1:27
	ds_write2st64_b32 v225, v124, v125 offset0:28 offset1:29
	ds_write2st64_b32 v225, v126, v127 offset0:30 offset1:31
	s_add_u32 s12, s26, 0xf800000
	s_addc_u32 s13, s27, 0
	s_lshl_b32 s15, s101, 9
	s_add_u32 s12, s12, s15
	s_addc_u32 s13, s13, 0
	s_lshl_b32 s18, s92, 11
	global_load_dword v96, v216, s[12:13]
	global_load_dword v97, v216, s[12:13] offset:256
	s_add_u32 s12, s12, s18
	s_addc_u32 s13, s13, 0
	global_load_dword v98, v216, s[12:13]
	global_load_dword v99, v216, s[12:13] offset:256
	s_add_u32 s12, s12, s18
	s_addc_u32 s13, s13, 0
	global_load_dword v100, v216, s[12:13]
	global_load_dword v101, v216, s[12:13] offset:256
	s_add_u32 s12, s12, s18
	s_addc_u32 s13, s13, 0
	global_load_dword v102, v216, s[12:13]
	global_load_dword v103, v216, s[12:13] offset:256
	s_add_u32 s12, s12, s18
	s_addc_u32 s13, s13, 0
	global_load_dword v104, v216, s[12:13]
	global_load_dword v105, v216, s[12:13] offset:256
	s_add_u32 s12, s12, s18
	s_addc_u32 s13, s13, 0
	global_load_dword v106, v216, s[12:13]
	global_load_dword v107, v216, s[12:13] offset:256
	s_add_u32 s12, s12, s18
	s_addc_u32 s13, s13, 0
	global_load_dword v108, v216, s[12:13]
	global_load_dword v109, v216, s[12:13] offset:256
	s_add_u32 s12, s12, s18
	s_addc_u32 s13, s13, 0
	global_load_dword v110, v216, s[12:13]
	global_load_dword v111, v216, s[12:13] offset:256
	s_add_u32 s12, s12, s18
	s_addc_u32 s13, s13, 0
	global_load_dword v112, v216, s[12:13]
	global_load_dword v113, v216, s[12:13] offset:256
	s_add_u32 s12, s12, s18
	s_addc_u32 s13, s13, 0
	global_load_dword v114, v216, s[12:13]
	global_load_dword v115, v216, s[12:13] offset:256
	s_add_u32 s12, s12, s18
	s_addc_u32 s13, s13, 0
	global_load_dword v116, v216, s[12:13]
	global_load_dword v117, v216, s[12:13] offset:256
	s_add_u32 s12, s12, s18
	s_addc_u32 s13, s13, 0
	global_load_dword v118, v216, s[12:13]
	global_load_dword v119, v216, s[12:13] offset:256
	s_add_u32 s12, s12, s18
	s_addc_u32 s13, s13, 0
	global_load_dword v120, v216, s[12:13]
	global_load_dword v121, v216, s[12:13] offset:256
	s_add_u32 s12, s12, s18
	s_addc_u32 s13, s13, 0
	global_load_dword v122, v216, s[12:13]
	global_load_dword v123, v216, s[12:13] offset:256
	s_add_u32 s12, s12, s18
	s_addc_u32 s13, s13, 0
	global_load_dword v124, v216, s[12:13]
	global_load_dword v125, v216, s[12:13] offset:256
	s_add_u32 s12, s12, s18
	s_addc_u32 s13, s13, 0
	global_load_dword v126, v216, s[12:13]
	global_load_dword v127, v216, s[12:13] offset:256
	s_add_u32 s12, s12, s18
	s_addc_u32 s13, s13, 0
	s_waitcnt vmcnt(0)
	ds_write2st64_b32 v226, v96, v97 offset0:0 offset1:1
	ds_write2st64_b32 v226, v98, v99 offset0:2 offset1:3
	ds_write2st64_b32 v226, v100, v101 offset0:4 offset1:5
	ds_write2st64_b32 v226, v102, v103 offset0:6 offset1:7
	ds_write2st64_b32 v226, v104, v105 offset0:8 offset1:9
	ds_write2st64_b32 v226, v106, v107 offset0:10 offset1:11
	ds_write2st64_b32 v226, v108, v109 offset0:12 offset1:13
	ds_write2st64_b32 v226, v110, v111 offset0:14 offset1:15
	ds_write2st64_b32 v226, v112, v113 offset0:16 offset1:17
	ds_write2st64_b32 v226, v114, v115 offset0:18 offset1:19
	ds_write2st64_b32 v226, v116, v117 offset0:20 offset1:21
	ds_write2st64_b32 v226, v118, v119 offset0:22 offset1:23
	ds_write2st64_b32 v226, v120, v121 offset0:24 offset1:25
	ds_write2st64_b32 v226, v122, v123 offset0:26 offset1:27
	ds_write2st64_b32 v226, v124, v125 offset0:28 offset1:29
	ds_write2st64_b32 v226, v126, v127 offset0:30 offset1:31
	s_waitcnt lgkmcnt(0)
	s_mov_b32 s14, 0
	s_mov_b32 s18, 0
	s_and_b32 s19, s18, 15
	s_lshr_b32 s98, s18, 4
	s_lshl_b32 s99, s19, 9
	s_mul_i32 s15, s19, s16
	s_lshl_b32 s18, s98, 7
	s_add_u32 s15, s15, s18
	s_lshl_b32 s18, s101, 12
	s_add_u32 s15, s15, s18
	s_add_u32 s8, s24, s15
	s_addc_u32 s9, s25, 0
	s_mul_i32 s15, s98, 0x300000
	s_add_u32 s4, s26, 0x4800000
	s_addc_u32 s5, s27, 0
	s_add_u32 s4, s4, s15
	s_addc_u32 s5, s5, 0
	v_add_u32_e32 v221, s99, v217
	v_add_u32_e32 v223, s99, v218
	ds_read2_b32 v[192:193], v221 offset0:0 offset1:16
	ds_read2_b32 v[194:195], v221 offset0:32 offset1:48
	s_waitcnt lgkmcnt(0)
	v_mad_u32_u24 v192, v192, s100, v219
	v_mad_u32_u24 v193, v193, s100, v219
	v_mad_u32_u24 v194, v194, s100, v219
	v_mad_u32_u24 v195, v195, s100, v219
	global_load_dwordx4 v[96:99], v192, s[4:5]
	global_load_dwordx4 v[100:103], v192, s[4:5] offset:16
	global_load_dwordx4 v[104:107], v192, s[4:5] offset:32
	global_load_dwordx4 v[108:111], v193, s[4:5]
	global_load_dwordx4 v[112:115], v193, s[4:5] offset:16
	global_load_dwordx4 v[116:119], v193, s[4:5] offset:32
	global_load_dwordx4 v[120:123], v194, s[4:5]
	global_load_dwordx4 v[124:127], v194, s[4:5] offset:16
	global_load_dwordx4 v[128:131], v194, s[4:5] offset:32
	global_load_dwordx4 v[132:135], v195, s[4:5]
	global_load_dwordx4 v[136:139], v195, s[4:5] offset:16
	global_load_dwordx4 v[140:143], v195, s[4:5] offset:32
	ds_read2_b32 v[196:197], v221 offset0:64 offset1:80
	ds_read2_b32 v[198:199], v221 offset0:96 offset1:112
	s_waitcnt lgkmcnt(0)
	v_mad_u32_u24 v196, v196, s100, v219
	v_mad_u32_u24 v197, v197, s100, v219
	v_mad_u32_u24 v198, v198, s100, v219
	v_mad_u32_u24 v199, v199, s100, v219
	global_load_dwordx4 v[144:147], v196, s[4:5]
	global_load_dwordx4 v[148:151], v196, s[4:5] offset:16
	global_load_dwordx4 v[152:155], v196, s[4:5] offset:32
	global_load_dwordx4 v[156:159], v197, s[4:5]
	global_load_dwordx4 v[160:163], v197, s[4:5] offset:16
	global_load_dwordx4 v[164:167], v197, s[4:5] offset:32
	global_load_dwordx4 v[168:171], v198, s[4:5]
	global_load_dwordx4 v[172:175], v198, s[4:5] offset:16
	global_load_dwordx4 v[176:179], v198, s[4:5] offset:32
	global_load_dwordx4 v[180:183], v199, s[4:5]
	global_load_dwordx4 v[184:187], v199, s[4:5] offset:16
	global_load_dwordx4 v[188:191], v199, s[4:5] offset:32
	global_load_dword v227, v220, s[8:9]
	ds_read2_b32 v[200:201], v223 offset0:0 offset1:16
	ds_read2_b32 v[202:203], v223 offset0:32 offset1:48
	s_mov_b32 s18, 1
	s_and_b32 s19, s18, 15
	s_lshr_b32 s98, s18, 4
	s_lshl_b32 s99, s19, 9
	s_mul_i32 s15, s19, s16
	s_lshl_b32 s18, s98, 7
	s_add_u32 s15, s15, s18
	s_lshl_b32 s18, s101, 12
	s_add_u32 s15, s15, s18
	s_add_u32 s10, s24, s15
	s_addc_u32 s11, s25, 0
	s_mul_i32 s15, s98, 0x300000
	s_add_u32 s4, s26, 0x4800000
	s_addc_u32 s5, s27, 0
	s_add_u32 s4, s4, s15
	s_addc_u32 s5, s5, 0
	v_add_u32_e32 v222, s99, v217
	v_add_u32_e32 v224, s99, v218
	ds_read2_b32 v[192:193], v222 offset0:0 offset1:16
	ds_read2_b32 v[194:195], v222 offset0:32 offset1:48
	s_waitcnt lgkmcnt(0)
.Lgv1_loop:
	global_load_dwordx4 v[212:215], v220, s[8:9]
	ds_read2_b32 v[208:209], v223 offset0:64 offset1:80
	ds_read2_b32 v[210:211], v223 offset0:96 offset1:112
	s_waitcnt vmcnt(23)
	v_cvt_scalef32_pk32_f32_fp6 v[64:95], v[96:101], 1.0
	v_pk_mul_f32 v[0:1], v[200:201], v[64:65] op_sel_hi:[0,1]
	v_pk_mul_f32 v[2:3], v[200:201], v[66:67] op_sel_hi:[0,1]
	v_pk_mul_f32 v[4:5], v[200:201], v[68:69] op_sel_hi:[0,1]
	v_pk_mul_f32 v[6:7], v[200:201], v[70:71] op_sel_hi:[0,1]
	v_pk_mul_f32 v[8:9], v[200:201], v[72:73] op_sel_hi:[0,1]
	v_pk_mul_f32 v[10:11], v[200:201], v[74:75] op_sel_hi:[0,1]
	v_pk_mul_f32 v[12:13], v[200:201], v[76:77] op_sel_hi:[0,1]
	v_pk_mul_f32 v[14:15], v[200:201], v[78:79] op_sel_hi:[0,1]
	v_pk_mul_f32 v[16:17], v[200:201], v[80:81] op_sel_hi:[0,1]
	v_pk_mul_f32 v[18:19], v[200:201], v[82:83] op_sel_hi:[0,1]
	v_pk_mul_f32 v[20:21], v[200:201], v[84:85] op_sel_hi:[0,1]
	v_pk_mul_f32 v[22:23], v[200:201], v[86:87] op_sel_hi:[0,1]
	v_pk_mul_f32 v[24:25], v[200:201], v[88:89] op_sel_hi:[0,1]
	v_pk_mul_f32 v[26:27], v[200:201], v[90:91] op_sel_hi:[0,1]
	v_pk_mul_f32 v[28:29], v[200:201], v[92:93] op_sel_hi:[0,1]
	v_pk_mul_f32 v[30:31], v[200:201], v[94:95] op_sel_hi:[0,1]
	v_cvt_scalef32_pk32_f32_fp6 v[64:95], v[102:107], 1.0
	v_pk_mul_f32 v[32:33], v[200:201], v[64:65] op_sel_hi:[0,1]
	v_pk_mul_f32 v[34:35], v[200:201], v[66:67] op_sel_hi:[0,1]
	v_pk_mul_f32 v[36:37], v[200:201], v[68:69] op_sel_hi:[0,1]
	v_pk_mul_f32 v[38:39], v[200:201], v[70:71] op_sel_hi:[0,1]
	v_pk_mul_f32 v[40:41], v[200:201], v[72:73] op_sel_hi:[0,1]
	v_pk_mul_f32 v[42:43], v[200:201], v[74:75] op_sel_hi:[0,1]
	v_pk_mul_f32 v[44:45], v[200:201], v[76:77] op_sel_hi:[0,1]
	v_pk_mul_f32 v[46:47], v[200:201], v[78:79] op_sel_hi:[0,1]
	v_pk_mul_f32 v[48:49], v[200:201], v[80:81] op_sel_hi:[0,1]
	v_pk_mul_f32 v[50:51], v[200:201], v[82:83] op_sel_hi:[0,1]
	v_pk_mul_f32 v[52:53], v[200:201], v[84:85] op_sel_hi:[0,1]
	v_pk_mul_f32 v[54:55], v[200:201], v[86:87] op_sel_hi:[0,1]
	v_pk_mul_f32 v[56:57], v[200:201], v[88:89] op_sel_hi:[0,1]
	v_pk_mul_f32 v[58:59], v[200:201], v[90:91] op_sel_hi:[0,1]
	v_pk_mul_f32 v[60:61], v[200:201], v[92:93] op_sel_hi:[0,1]
	v_pk_mul_f32 v[62:63], v[200:201], v[94:95] op_sel_hi:[0,1]
	s_waitcnt vmcnt(20)
	v_cvt_scalef32_pk32_f32_fp6 v[64:95], v[108:113], 1.0
	v_pk_fma_f32 v[0:1], v[200:201], v[64:65], v[0:1] op_sel:[1,0,0] op_sel_hi:[1,1,1]
	v_pk_fma_f32 v[2:3], v[200:201], v[66:67], v[2:3] op_sel:[1,0,0] op_sel_hi:[1,1,1]
	v_pk_fma_f32 v[4:5], v[200:201], v[68:69], v[4:5] op_sel:[1,0,0] op_sel_hi:[1,1,1]
	v_pk_fma_f32 v[6:7], v[200:201], v[70:71], v[6:7] op_sel:[1,0,0] op_sel_hi:[1,1,1]
	v_pk_fma_f32 v[8:9], v[200:201], v[72:73], v[8:9] op_sel:[1,0,0] op_sel_hi:[1,1,1]
	v_pk_fma_f32 v[10:11], v[200:201], v[74:75], v[10:11] op_sel:[1,0,0] op_sel_hi:[1,1,1]
	v_pk_fma_f32 v[12:13], v[200:201], v[76:77], v[12:13] op_sel:[1,0,0] op_sel_hi:[1,1,1]
	v_pk_fma_f32 v[14:15], v[200:201], v[78:79], v[14:15] op_sel:[1,0,0] op_sel_hi:[1,1,1]
	v_pk_fma_f32 v[16:17], v[200:201], v[80:81], v[16:17] op_sel:[1,0,0] op_sel_hi:[1,1,1]
	v_pk_fma_f32 v[18:19], v[200:201], v[82:83], v[18:19] op_sel:[1,0,0] op_sel_hi:[1,1,1]
	v_pk_fma_f32 v[20:21], v[200:201], v[84:85], v[20:21] op_sel:[1,0,0] op_sel_hi:[1,1,1]
	v_pk_fma_f32 v[22:23], v[200:201], v[86:87], v[22:23] op_sel:[1,0,0] op_sel_hi:[1,1,1]
	v_pk_fma_f32 v[24:25], v[200:201], v[88:89], v[24:25] op_sel:[1,0,0] op_sel_hi:[1,1,1]
	v_pk_fma_f32 v[26:27], v[200:201], v[90:91], v[26:27] op_sel:[1,0,0] op_sel_hi:[1,1,1]
	v_pk_fma_f32 v[28:29], v[200:201], v[92:93], v[28:29] op_sel:[1,0,0] op_sel_hi:[1,1,1]
	v_pk_fma_f32 v[30:31], v[200:201], v[94:95], v[30:31] op_sel:[1,0,0] op_sel_hi:[1,1,1]
	v_cvt_scalef32_pk32_f32_fp6 v[64:95], v[114:119], 1.0
	v_pk_fma_f32 v[32:33], v[200:201], v[64:65], v[32:33] op_sel:[1,0,0] op_sel_hi:[1,1,1]
	v_pk_fma_f32 v[34:35], v[200:201], v[66:67], v[34:35] op_sel:[1,0,0] op_sel_hi:[1,1,1]
	v_pk_fma_f32 v[36:37], v[200:201], v[68:69], v[36:37] op_sel:[1,0,0] op_sel_hi:[1,1,1]
	v_pk_fma_f32 v[38:39], v[200:201], v[70:71], v[38:39] op_sel:[1,0,0] op_sel_hi:[1,1,1]
	v_pk_fma_f32 v[40:41], v[200:201], v[72:73], v[40:41] op_sel:[1,0,0] op_sel_hi:[1,1,1]
	v_pk_fma_f32 v[42:43], v[200:201], v[74:75], v[42:43] op_sel:[1,0,0] op_sel_hi:[1,1,1]
	v_pk_fma_f32 v[44:45], v[200:201], v[76:77], v[44:45] op_sel:[1,0,0] op_sel_hi:[1,1,1]
	v_pk_fma_f32 v[46:47], v[200:201], v[78:79], v[46:47] op_sel:[1,0,0] op_sel_hi:[1,1,1]
	v_pk_fma_f32 v[48:49], v[200:201], v[80:81], v[48:49] op_sel:[1,0,0] op_sel_hi:[1,1,1]
	v_pk_fma_f32 v[50:51], v[200:201], v[82:83], v[50:51] op_sel:[1,0,0] op_sel_hi:[1,1,1]
	v_pk_fma_f32 v[52:53], v[200:201], v[84:85], v[52:53] op_sel:[1,0,0] op_sel_hi:[1,1,1]
	v_pk_fma_f32 v[54:55], v[200:201], v[86:87], v[54:55] op_sel:[1,0,0] op_sel_hi:[1,1,1]
	v_pk_fma_f32 v[56:57], v[200:201], v[88:89], v[56:57] op_sel:[1,0,0] op_sel_hi:[1,1,1]
	v_pk_fma_f32 v[58:59], v[200:201], v[90:91], v[58:59] op_sel:[1,0,0] op_sel_hi:[1,1,1]
	v_pk_fma_f32 v[60:61], v[200:201], v[92:93], v[60:61] op_sel:[1,0,0] op_sel_hi:[1,1,1]
	v_pk_fma_f32 v[62:63], v[200:201], v[94:95], v[62:63] op_sel:[1,0,0] op_sel_hi:[1,1,1]
	s_waitcnt vmcnt(17)
	v_cvt_scalef32_pk32_f32_fp6 v[64:95], v[120:125], 1.0
	v_pk_fma_f32 v[0:1], v[202:203], v[64:65], v[0:1] op_sel_hi:[0,1,1]
	v_pk_fma_f32 v[2:3], v[202:203], v[66:67], v[2:3] op_sel_hi:[0,1,1]
	v_pk_fma_f32 v[4:5], v[202:203], v[68:69], v[4:5] op_sel_hi:[0,1,1]
	v_pk_fma_f32 v[6:7], v[202:203], v[70:71], v[6:7] op_sel_hi:[0,1,1]
	v_pk_fma_f32 v[8:9], v[202:203], v[72:73], v[8:9] op_sel_hi:[0,1,1]
	v_pk_fma_f32 v[10:11], v[202:203], v[74:75], v[10:11] op_sel_hi:[0,1,1]
	v_pk_fma_f32 v[12:13], v[202:203], v[76:77], v[12:13] op_sel_hi:[0,1,1]
	v_pk_fma_f32 v[14:15], v[202:203], v[78:79], v[14:15] op_sel_hi:[0,1,1]
	v_pk_fma_f32 v[16:17], v[202:203], v[80:81], v[16:17] op_sel_hi:[0,1,1]
	v_pk_fma_f32 v[18:19], v[202:203], v[82:83], v[18:19] op_sel_hi:[0,1,1]
	v_pk_fma_f32 v[20:21], v[202:203], v[84:85], v[20:21] op_sel_hi:[0,1,1]
	v_pk_fma_f32 v[22:23], v[202:203], v[86:87], v[22:23] op_sel_hi:[0,1,1]
	v_pk_fma_f32 v[24:25], v[202:203], v[88:89], v[24:25] op_sel_hi:[0,1,1]
	v_pk_fma_f32 v[26:27], v[202:203], v[90:91], v[26:27] op_sel_hi:[0,1,1]
	v_pk_fma_f32 v[28:29], v[202:203], v[92:93], v[28:29] op_sel_hi:[0,1,1]
	v_pk_fma_f32 v[30:31], v[202:203], v[94:95], v[30:31] op_sel_hi:[0,1,1]
	v_cvt_scalef32_pk32_f32_fp6 v[64:95], v[126:131], 1.0
	v_pk_fma_f32 v[32:33], v[202:203], v[64:65], v[32:33] op_sel_hi:[0,1,1]
	v_pk_fma_f32 v[34:35], v[202:203], v[66:67], v[34:35] op_sel_hi:[0,1,1]
	v_pk_fma_f32 v[36:37], v[202:203], v[68:69], v[36:37] op_sel_hi:[0,1,1]
	v_pk_fma_f32 v[38:39], v[202:203], v[70:71], v[38:39] op_sel_hi:[0,1,1]
	v_pk_fma_f32 v[40:41], v[202:203], v[72:73], v[40:41] op_sel_hi:[0,1,1]
	v_pk_fma_f32 v[42:43], v[202:203], v[74:75], v[42:43] op_sel_hi:[0,1,1]
	v_pk_fma_f32 v[44:45], v[202:203], v[76:77], v[44:45] op_sel_hi:[0,1,1]
	v_pk_fma_f32 v[46:47], v[202:203], v[78:79], v[46:47] op_sel_hi:[0,1,1]
	v_pk_fma_f32 v[48:49], v[202:203], v[80:81], v[48:49] op_sel_hi:[0,1,1]
	v_pk_fma_f32 v[50:51], v[202:203], v[82:83], v[50:51] op_sel_hi:[0,1,1]
	v_pk_fma_f32 v[52:53], v[202:203], v[84:85], v[52:53] op_sel_hi:[0,1,1]
	v_pk_fma_f32 v[54:55], v[202:203], v[86:87], v[54:55] op_sel_hi:[0,1,1]
	v_pk_fma_f32 v[56:57], v[202:203], v[88:89], v[56:57] op_sel_hi:[0,1,1]
	v_pk_fma_f32 v[58:59], v[202:203], v[90:91], v[58:59] op_sel_hi:[0,1,1]
	v_pk_fma_f32 v[60:61], v[202:203], v[92:93], v[60:61] op_sel_hi:[0,1,1]
	v_pk_fma_f32 v[62:63], v[202:203], v[94:95], v[62:63] op_sel_hi:[0,1,1]
	s_waitcnt vmcnt(14)
	v_cvt_scalef32_pk32_f32_fp6 v[64:95], v[132:137], 1.0
	v_pk_fma_f32 v[0:1], v[202:203], v[64:65], v[0:1] op_sel:[1,0,0] op_sel_hi:[1,1,1]
	v_pk_fma_f32 v[2:3], v[202:203], v[66:67], v[2:3] op_sel:[1,0,0] op_sel_hi:[1,1,1]
	v_pk_fma_f32 v[4:5], v[202:203], v[68:69], v[4:5] op_sel:[1,0,0] op_sel_hi:[1,1,1]
	v_pk_fma_f32 v[6:7], v[202:203], v[70:71], v[6:7] op_sel:[1,0,0] op_sel_hi:[1,1,1]
	v_pk_fma_f32 v[8:9], v[202:203], v[72:73], v[8:9] op_sel:[1,0,0] op_sel_hi:[1,1,1]
	v_pk_fma_f32 v[10:11], v[202:203], v[74:75], v[10:11] op_sel:[1,0,0] op_sel_hi:[1,1,1]
	v_pk_fma_f32 v[12:13], v[202:203], v[76:77], v[12:13] op_sel:[1,0,0] op_sel_hi:[1,1,1]
	v_pk_fma_f32 v[14:15], v[202:203], v[78:79], v[14:15] op_sel:[1,0,0] op_sel_hi:[1,1,1]
	v_pk_fma_f32 v[16:17], v[202:203], v[80:81], v[16:17] op_sel:[1,0,0] op_sel_hi:[1,1,1]
	v_pk_fma_f32 v[18:19], v[202:203], v[82:83], v[18:19] op_sel:[1,0,0] op_sel_hi:[1,1,1]
	v_pk_fma_f32 v[20:21], v[202:203], v[84:85], v[20:21] op_sel:[1,0,0] op_sel_hi:[1,1,1]
	v_pk_fma_f32 v[22:23], v[202:203], v[86:87], v[22:23] op_sel:[1,0,0] op_sel_hi:[1,1,1]
	v_pk_fma_f32 v[24:25], v[202:203], v[88:89], v[24:25] op_sel:[1,0,0] op_sel_hi:[1,1,1]
	v_pk_fma_f32 v[26:27], v[202:203], v[90:91], v[26:27] op_sel:[1,0,0] op_sel_hi:[1,1,1]
	v_pk_fma_f32 v[28:29], v[202:203], v[92:93], v[28:29] op_sel:[1,0,0] op_sel_hi:[1,1,1]
	v_pk_fma_f32 v[30:31], v[202:203], v[94:95], v[30:31] op_sel:[1,0,0] op_sel_hi:[1,1,1]
	v_cvt_scalef32_pk32_f32_fp6 v[64:95], v[138:143], 1.0
	v_pk_fma_f32 v[32:33], v[202:203], v[64:65], v[32:33] op_sel:[1,0,0] op_sel_hi:[1,1,1]
	v_pk_fma_f32 v[34:35], v[202:203], v[66:67], v[34:35] op_sel:[1,0,0] op_sel_hi:[1,1,1]
	v_pk_fma_f32 v[36:37], v[202:203], v[68:69], v[36:37] op_sel:[1,0,0] op_sel_hi:[1,1,1]
	v_pk_fma_f32 v[38:39], v[202:203], v[70:71], v[38:39] op_sel:[1,0,0] op_sel_hi:[1,1,1]
	v_pk_fma_f32 v[40:41], v[202:203], v[72:73], v[40:41] op_sel:[1,0,0] op_sel_hi:[1,1,1]
	v_pk_fma_f32 v[42:43], v[202:203], v[74:75], v[42:43] op_sel:[1,0,0] op_sel_hi:[1,1,1]
	v_pk_fma_f32 v[44:45], v[202:203], v[76:77], v[44:45] op_sel:[1,0,0] op_sel_hi:[1,1,1]
	v_pk_fma_f32 v[46:47], v[202:203], v[78:79], v[46:47] op_sel:[1,0,0] op_sel_hi:[1,1,1]
	v_pk_fma_f32 v[48:49], v[202:203], v[80:81], v[48:49] op_sel:[1,0,0] op_sel_hi:[1,1,1]
	v_pk_fma_f32 v[50:51], v[202:203], v[82:83], v[50:51] op_sel:[1,0,0] op_sel_hi:[1,1,1]
	v_pk_fma_f32 v[52:53], v[202:203], v[84:85], v[52:53] op_sel:[1,0,0] op_sel_hi:[1,1,1]
	v_pk_fma_f32 v[54:55], v[202:203], v[86:87], v[54:55] op_sel:[1,0,0] op_sel_hi:[1,1,1]
	v_pk_fma_f32 v[56:57], v[202:203], v[88:89], v[56:57] op_sel:[1,0,0] op_sel_hi:[1,1,1]
	v_pk_fma_f32 v[58:59], v[202:203], v[90:91], v[58:59] op_sel:[1,0,0] op_sel_hi:[1,1,1]
	v_pk_fma_f32 v[60:61], v[202:203], v[92:93], v[60:61] op_sel:[1,0,0] op_sel_hi:[1,1,1]
	v_pk_fma_f32 v[62:63], v[202:203], v[94:95], v[62:63] op_sel:[1,0,0] op_sel_hi:[1,1,1]
	s_waitcnt lgkmcnt(0)
	v_mad_u32_u24 v192, v192, s100, v219
	v_mad_u32_u24 v193, v193, s100, v219
	v_mad_u32_u24 v194, v194, s100, v219
	v_mad_u32_u24 v195, v195, s100, v219
	global_load_dwordx4 v[96:99], v192, s[4:5]
	global_load_dwordx4 v[100:103], v192, s[4:5] offset:16
	global_load_dwordx4 v[104:107], v192, s[4:5] offset:32
	global_load_dwordx4 v[108:111], v193, s[4:5]
	global_load_dwordx4 v[112:115], v193, s[4:5] offset:16
	global_load_dwordx4 v[116:119], v193, s[4:5] offset:32
	global_load_dwordx4 v[120:123], v194, s[4:5]
	global_load_dwordx4 v[124:127], v194, s[4:5] offset:16
	global_load_dwordx4 v[128:131], v194, s[4:5] offset:32
	global_load_dwordx4 v[132:135], v195, s[4:5]
	global_load_dwordx4 v[136:139], v195, s[4:5] offset:16
	global_load_dwordx4 v[140:143], v195, s[4:5] offset:32
	ds_read2_b32 v[196:197], v222 offset0:64 offset1:80
	ds_read2_b32 v[198:199], v222 offset0:96 offset1:112
	ds_read2_b32 v[200:201], v224 offset0:0 offset1:16
	ds_read2_b32 v[202:203], v224 offset0:32 offset1:48
	s_waitcnt vmcnt(23)
	v_cvt_scalef32_pk32_f32_fp6 v[64:95], v[144:149], 1.0
	v_pk_fma_f32 v[0:1], v[208:209], v[64:65], v[0:1] op_sel_hi:[0,1,1]
	v_pk_fma_f32 v[2:3], v[208:209], v[66:67], v[2:3] op_sel_hi:[0,1,1]
	v_pk_fma_f32 v[4:5], v[208:209], v[68:69], v[4:5] op_sel_hi:[0,1,1]
	v_pk_fma_f32 v[6:7], v[208:209], v[70:71], v[6:7] op_sel_hi:[0,1,1]
	v_pk_fma_f32 v[8:9], v[208:209], v[72:73], v[8:9] op_sel_hi:[0,1,1]
	v_pk_fma_f32 v[10:11], v[208:209], v[74:75], v[10:11] op_sel_hi:[0,1,1]
	v_pk_fma_f32 v[12:13], v[208:209], v[76:77], v[12:13] op_sel_hi:[0,1,1]
	v_pk_fma_f32 v[14:15], v[208:209], v[78:79], v[14:15] op_sel_hi:[0,1,1]
	v_pk_fma_f32 v[16:17], v[208:209], v[80:81], v[16:17] op_sel_hi:[0,1,1]
	v_pk_fma_f32 v[18:19], v[208:209], v[82:83], v[18:19] op_sel_hi:[0,1,1]
	v_pk_fma_f32 v[20:21], v[208:209], v[84:85], v[20:21] op_sel_hi:[0,1,1]
	v_pk_fma_f32 v[22:23], v[208:209], v[86:87], v[22:23] op_sel_hi:[0,1,1]
	v_pk_fma_f32 v[24:25], v[208:209], v[88:89], v[24:25] op_sel_hi:[0,1,1]
	v_pk_fma_f32 v[26:27], v[208:209], v[90:91], v[26:27] op_sel_hi:[0,1,1]
	v_pk_fma_f32 v[28:29], v[208:209], v[92:93], v[28:29] op_sel_hi:[0,1,1]
	v_pk_fma_f32 v[30:31], v[208:209], v[94:95], v[30:31] op_sel_hi:[0,1,1]
	v_cvt_scalef32_pk32_f32_fp6 v[64:95], v[150:155], 1.0
	v_pk_fma_f32 v[32:33], v[208:209], v[64:65], v[32:33] op_sel_hi:[0,1,1]
	v_pk_fma_f32 v[34:35], v[208:209], v[66:67], v[34:35] op_sel_hi:[0,1,1]
	v_pk_fma_f32 v[36:37], v[208:209], v[68:69], v[36:37] op_sel_hi:[0,1,1]
	v_pk_fma_f32 v[38:39], v[208:209], v[70:71], v[38:39] op_sel_hi:[0,1,1]
	v_pk_fma_f32 v[40:41], v[208:209], v[72:73], v[40:41] op_sel_hi:[0,1,1]
	v_pk_fma_f32 v[42:43], v[208:209], v[74:75], v[42:43] op_sel_hi:[0,1,1]
	v_pk_fma_f32 v[44:45], v[208:209], v[76:77], v[44:45] op_sel_hi:[0,1,1]
	v_pk_fma_f32 v[46:47], v[208:209], v[78:79], v[46:47] op_sel_hi:[0,1,1]
	v_pk_fma_f32 v[48:49], v[208:209], v[80:81], v[48:49] op_sel_hi:[0,1,1]
	v_pk_fma_f32 v[50:51], v[208:209], v[82:83], v[50:51] op_sel_hi:[0,1,1]
	v_pk_fma_f32 v[52:53], v[208:209], v[84:85], v[52:53] op_sel_hi:[0,1,1]
	v_pk_fma_f32 v[54:55], v[208:209], v[86:87], v[54:55] op_sel_hi:[0,1,1]
	v_pk_fma_f32 v[56:57], v[208:209], v[88:89], v[56:57] op_sel_hi:[0,1,1]
	v_pk_fma_f32 v[58:59], v[208:209], v[90:91], v[58:59] op_sel_hi:[0,1,1]
	v_pk_fma_f32 v[60:61], v[208:209], v[92:93], v[60:61] op_sel_hi:[0,1,1]
	v_pk_fma_f32 v[62:63], v[208:209], v[94:95], v[62:63] op_sel_hi:[0,1,1]
	s_waitcnt vmcnt(20)
	v_cvt_scalef32_pk32_f32_fp6 v[64:95], v[156:161], 1.0
	v_pk_fma_f32 v[0:1], v[208:209], v[64:65], v[0:1] op_sel:[1,0,0] op_sel_hi:[1,1,1]
	v_pk_fma_f32 v[2:3], v[208:209], v[66:67], v[2:3] op_sel:[1,0,0] op_sel_hi:[1,1,1]
	v_pk_fma_f32 v[4:5], v[208:209], v[68:69], v[4:5] op_sel:[1,0,0] op_sel_hi:[1,1,1]
	v_pk_fma_f32 v[6:7], v[208:209], v[70:71], v[6:7] op_sel:[1,0,0] op_sel_hi:[1,1,1]
	v_pk_fma_f32 v[8:9], v[208:209], v[72:73], v[8:9] op_sel:[1,0,0] op_sel_hi:[1,1,1]
	v_pk_fma_f32 v[10:11], v[208:209], v[74:75], v[10:11] op_sel:[1,0,0] op_sel_hi:[1,1,1]
	v_pk_fma_f32 v[12:13], v[208:209], v[76:77], v[12:13] op_sel:[1,0,0] op_sel_hi:[1,1,1]
	v_pk_fma_f32 v[14:15], v[208:209], v[78:79], v[14:15] op_sel:[1,0,0] op_sel_hi:[1,1,1]
	v_pk_fma_f32 v[16:17], v[208:209], v[80:81], v[16:17] op_sel:[1,0,0] op_sel_hi:[1,1,1]
	v_pk_fma_f32 v[18:19], v[208:209], v[82:83], v[18:19] op_sel:[1,0,0] op_sel_hi:[1,1,1]
	v_pk_fma_f32 v[20:21], v[208:209], v[84:85], v[20:21] op_sel:[1,0,0] op_sel_hi:[1,1,1]
	v_pk_fma_f32 v[22:23], v[208:209], v[86:87], v[22:23] op_sel:[1,0,0] op_sel_hi:[1,1,1]
	v_pk_fma_f32 v[24:25], v[208:209], v[88:89], v[24:25] op_sel:[1,0,0] op_sel_hi:[1,1,1]
	v_pk_fma_f32 v[26:27], v[208:209], v[90:91], v[26:27] op_sel:[1,0,0] op_sel_hi:[1,1,1]
	v_pk_fma_f32 v[28:29], v[208:209], v[92:93], v[28:29] op_sel:[1,0,0] op_sel_hi:[1,1,1]
	v_pk_fma_f32 v[30:31], v[208:209], v[94:95], v[30:31] op_sel:[1,0,0] op_sel_hi:[1,1,1]
	v_cvt_scalef32_pk32_f32_fp6 v[64:95], v[162:167], 1.0
	v_pk_fma_f32 v[32:33], v[208:209], v[64:65], v[32:33] op_sel:[1,0,0] op_sel_hi:[1,1,1]
	v_pk_fma_f32 v[34:35], v[208:209], v[66:67], v[34:35] op_sel:[1,0,0] op_sel_hi:[1,1,1]
	v_pk_fma_f32 v[36:37], v[208:209], v[68:69], v[36:37] op_sel:[1,0,0] op_sel_hi:[1,1,1]
	v_pk_fma_f32 v[38:39], v[208:209], v[70:71], v[38:39] op_sel:[1,0,0] op_sel_hi:[1,1,1]
	v_pk_fma_f32 v[40:41], v[208:209], v[72:73], v[40:41] op_sel:[1,0,0] op_sel_hi:[1,1,1]
	v_pk_fma_f32 v[42:43], v[208:209], v[74:75], v[42:43] op_sel:[1,0,0] op_sel_hi:[1,1,1]
	v_pk_fma_f32 v[44:45], v[208:209], v[76:77], v[44:45] op_sel:[1,0,0] op_sel_hi:[1,1,1]
	v_pk_fma_f32 v[46:47], v[208:209], v[78:79], v[46:47] op_sel:[1,0,0] op_sel_hi:[1,1,1]
	v_pk_fma_f32 v[48:49], v[208:209], v[80:81], v[48:49] op_sel:[1,0,0] op_sel_hi:[1,1,1]
	v_pk_fma_f32 v[50:51], v[208:209], v[82:83], v[50:51] op_sel:[1,0,0] op_sel_hi:[1,1,1]
	v_pk_fma_f32 v[52:53], v[208:209], v[84:85], v[52:53] op_sel:[1,0,0] op_sel_hi:[1,1,1]
	v_pk_fma_f32 v[54:55], v[208:209], v[86:87], v[54:55] op_sel:[1,0,0] op_sel_hi:[1,1,1]
	v_pk_fma_f32 v[56:57], v[208:209], v[88:89], v[56:57] op_sel:[1,0,0] op_sel_hi:[1,1,1]
	v_pk_fma_f32 v[58:59], v[208:209], v[90:91], v[58:59] op_sel:[1,0,0] op_sel_hi:[1,1,1]
	v_pk_fma_f32 v[60:61], v[208:209], v[92:93], v[60:61] op_sel:[1,0,0] op_sel_hi:[1,1,1]
	v_pk_fma_f32 v[62:63], v[208:209], v[94:95], v[62:63] op_sel:[1,0,0] op_sel_hi:[1,1,1]
	s_waitcnt vmcnt(17)
	v_cvt_scalef32_pk32_f32_fp6 v[64:95], v[168:173], 1.0
	v_pk_fma_f32 v[0:1], v[210:211], v[64:65], v[0:1] op_sel_hi:[0,1,1]
	v_pk_fma_f32 v[2:3], v[210:211], v[66:67], v[2:3] op_sel_hi:[0,1,1]
	v_pk_fma_f32 v[4:5], v[210:211], v[68:69], v[4:5] op_sel_hi:[0,1,1]
	v_pk_fma_f32 v[6:7], v[210:211], v[70:71], v[6:7] op_sel_hi:[0,1,1]
	v_pk_fma_f32 v[8:9], v[210:211], v[72:73], v[8:9] op_sel_hi:[0,1,1]
	v_pk_fma_f32 v[10:11], v[210:211], v[74:75], v[10:11] op_sel_hi:[0,1,1]
	v_pk_fma_f32 v[12:13], v[210:211], v[76:77], v[12:13] op_sel_hi:[0,1,1]
	v_pk_fma_f32 v[14:15], v[210:211], v[78:79], v[14:15] op_sel_hi:[0,1,1]
	v_pk_fma_f32 v[16:17], v[210:211], v[80:81], v[16:17] op_sel_hi:[0,1,1]
	v_pk_fma_f32 v[18:19], v[210:211], v[82:83], v[18:19] op_sel_hi:[0,1,1]
	v_pk_fma_f32 v[20:21], v[210:211], v[84:85], v[20:21] op_sel_hi:[0,1,1]
	v_pk_fma_f32 v[22:23], v[210:211], v[86:87], v[22:23] op_sel_hi:[0,1,1]
	v_pk_fma_f32 v[24:25], v[210:211], v[88:89], v[24:25] op_sel_hi:[0,1,1]
	v_pk_fma_f32 v[26:27], v[210:211], v[90:91], v[26:27] op_sel_hi:[0,1,1]
	v_pk_fma_f32 v[28:29], v[210:211], v[92:93], v[28:29] op_sel_hi:[0,1,1]
	v_pk_fma_f32 v[30:31], v[210:211], v[94:95], v[30:31] op_sel_hi:[0,1,1]
	v_cvt_scalef32_pk32_f32_fp6 v[64:95], v[174:179], 1.0
	v_pk_fma_f32 v[32:33], v[210:211], v[64:65], v[32:33] op_sel_hi:[0,1,1]
	v_pk_fma_f32 v[34:35], v[210:211], v[66:67], v[34:35] op_sel_hi:[0,1,1]
	v_pk_fma_f32 v[36:37], v[210:211], v[68:69], v[36:37] op_sel_hi:[0,1,1]
	v_pk_fma_f32 v[38:39], v[210:211], v[70:71], v[38:39] op_sel_hi:[0,1,1]
	v_pk_fma_f32 v[40:41], v[210:211], v[72:73], v[40:41] op_sel_hi:[0,1,1]
	v_pk_fma_f32 v[42:43], v[210:211], v[74:75], v[42:43] op_sel_hi:[0,1,1]
	v_pk_fma_f32 v[44:45], v[210:211], v[76:77], v[44:45] op_sel_hi:[0,1,1]
	v_pk_fma_f32 v[46:47], v[210:211], v[78:79], v[46:47] op_sel_hi:[0,1,1]
	v_pk_fma_f32 v[48:49], v[210:211], v[80:81], v[48:49] op_sel_hi:[0,1,1]
	v_pk_fma_f32 v[50:51], v[210:211], v[82:83], v[50:51] op_sel_hi:[0,1,1]
	v_pk_fma_f32 v[52:53], v[210:211], v[84:85], v[52:53] op_sel_hi:[0,1,1]
	v_pk_fma_f32 v[54:55], v[210:211], v[86:87], v[54:55] op_sel_hi:[0,1,1]
	v_pk_fma_f32 v[56:57], v[210:211], v[88:89], v[56:57] op_sel_hi:[0,1,1]
	v_pk_fma_f32 v[58:59], v[210:211], v[90:91], v[58:59] op_sel_hi:[0,1,1]
	v_pk_fma_f32 v[60:61], v[210:211], v[92:93], v[60:61] op_sel_hi:[0,1,1]
	v_pk_fma_f32 v[62:63], v[210:211], v[94:95], v[62:63] op_sel_hi:[0,1,1]
	s_waitcnt vmcnt(14)
	v_cvt_scalef32_pk32_f32_fp6 v[64:95], v[180:185], 1.0
	v_pk_fma_f32 v[0:1], v[210:211], v[64:65], v[0:1] op_sel:[1,0,0] op_sel_hi:[1,1,1]
	v_pk_fma_f32 v[2:3], v[210:211], v[66:67], v[2:3] op_sel:[1,0,0] op_sel_hi:[1,1,1]
	v_pk_fma_f32 v[4:5], v[210:211], v[68:69], v[4:5] op_sel:[1,0,0] op_sel_hi:[1,1,1]
	v_pk_fma_f32 v[6:7], v[210:211], v[70:71], v[6:7] op_sel:[1,0,0] op_sel_hi:[1,1,1]
	v_pk_fma_f32 v[8:9], v[210:211], v[72:73], v[8:9] op_sel:[1,0,0] op_sel_hi:[1,1,1]
	v_pk_fma_f32 v[10:11], v[210:211], v[74:75], v[10:11] op_sel:[1,0,0] op_sel_hi:[1,1,1]
	v_pk_fma_f32 v[12:13], v[210:211], v[76:77], v[12:13] op_sel:[1,0,0] op_sel_hi:[1,1,1]
	v_pk_fma_f32 v[14:15], v[210:211], v[78:79], v[14:15] op_sel:[1,0,0] op_sel_hi:[1,1,1]
	v_pk_fma_f32 v[16:17], v[210:211], v[80:81], v[16:17] op_sel:[1,0,0] op_sel_hi:[1,1,1]
	v_pk_fma_f32 v[18:19], v[210:211], v[82:83], v[18:19] op_sel:[1,0,0] op_sel_hi:[1,1,1]
	v_pk_fma_f32 v[20:21], v[210:211], v[84:85], v[20:21] op_sel:[1,0,0] op_sel_hi:[1,1,1]
	v_pk_fma_f32 v[22:23], v[210:211], v[86:87], v[22:23] op_sel:[1,0,0] op_sel_hi:[1,1,1]
	v_pk_fma_f32 v[24:25], v[210:211], v[88:89], v[24:25] op_sel:[1,0,0] op_sel_hi:[1,1,1]
	v_pk_fma_f32 v[26:27], v[210:211], v[90:91], v[26:27] op_sel:[1,0,0] op_sel_hi:[1,1,1]
	v_pk_fma_f32 v[28:29], v[210:211], v[92:93], v[28:29] op_sel:[1,0,0] op_sel_hi:[1,1,1]
	v_pk_fma_f32 v[30:31], v[210:211], v[94:95], v[30:31] op_sel:[1,0,0] op_sel_hi:[1,1,1]
	v_cvt_scalef32_pk32_f32_fp6 v[64:95], v[186:191], 1.0
	v_pk_fma_f32 v[32:33], v[210:211], v[64:65], v[32:33] op_sel:[1,0,0] op_sel_hi:[1,1,1]
	v_pk_fma_f32 v[34:35], v[210:211], v[66:67], v[34:35] op_sel:[1,0,0] op_sel_hi:[1,1,1]
	v_pk_fma_f32 v[36:37], v[210:211], v[68:69], v[36:37] op_sel:[1,0,0] op_sel_hi:[1,1,1]
	v_pk_fma_f32 v[38:39], v[210:211], v[70:71], v[38:39] op_sel:[1,0,0] op_sel_hi:[1,1,1]
	v_pk_fma_f32 v[40:41], v[210:211], v[72:73], v[40:41] op_sel:[1,0,0] op_sel_hi:[1,1,1]
	v_pk_fma_f32 v[42:43], v[210:211], v[74:75], v[42:43] op_sel:[1,0,0] op_sel_hi:[1,1,1]
	v_pk_fma_f32 v[44:45], v[210:211], v[76:77], v[44:45] op_sel:[1,0,0] op_sel_hi:[1,1,1]
	v_pk_fma_f32 v[46:47], v[210:211], v[78:79], v[46:47] op_sel:[1,0,0] op_sel_hi:[1,1,1]
	v_pk_fma_f32 v[48:49], v[210:211], v[80:81], v[48:49] op_sel:[1,0,0] op_sel_hi:[1,1,1]
	v_pk_fma_f32 v[50:51], v[210:211], v[82:83], v[50:51] op_sel:[1,0,0] op_sel_hi:[1,1,1]
	v_pk_fma_f32 v[52:53], v[210:211], v[84:85], v[52:53] op_sel:[1,0,0] op_sel_hi:[1,1,1]
	v_pk_fma_f32 v[54:55], v[210:211], v[86:87], v[54:55] op_sel:[1,0,0] op_sel_hi:[1,1,1]
	v_pk_fma_f32 v[56:57], v[210:211], v[88:89], v[56:57] op_sel:[1,0,0] op_sel_hi:[1,1,1]
	v_pk_fma_f32 v[58:59], v[210:211], v[90:91], v[58:59] op_sel:[1,0,0] op_sel_hi:[1,1,1]
	v_pk_fma_f32 v[60:61], v[210:211], v[92:93], v[60:61] op_sel:[1,0,0] op_sel_hi:[1,1,1]
	v_pk_fma_f32 v[62:63], v[210:211], v[94:95], v[62:63] op_sel:[1,0,0] op_sel_hi:[1,1,1]
	s_waitcnt lgkmcnt(0)
	v_mad_u32_u24 v196, v196, s100, v219
	v_mad_u32_u24 v197, v197, s100, v219
	v_mad_u32_u24 v198, v198, s100, v219
	v_mad_u32_u24 v199, v199, s100, v219
	global_load_dwordx4 v[144:147], v196, s[4:5]
	global_load_dwordx4 v[148:151], v196, s[4:5] offset:16
	global_load_dwordx4 v[152:155], v196, s[4:5] offset:32
	global_load_dwordx4 v[156:159], v197, s[4:5]
	global_load_dwordx4 v[160:163], v197, s[4:5] offset:16
	global_load_dwordx4 v[164:167], v197, s[4:5] offset:32
	global_load_dwordx4 v[168:171], v198, s[4:5]
	global_load_dwordx4 v[172:175], v198, s[4:5] offset:16
	global_load_dwordx4 v[176:179], v198, s[4:5] offset:32
	global_load_dwordx4 v[180:183], v199, s[4:5]
	global_load_dwordx4 v[184:187], v199, s[4:5] offset:16
	global_load_dwordx4 v[188:191], v199, s[4:5] offset:32
	s_nop 1
	v_permlane32_swap_b32_e32 v0, v32
	v_permlane32_swap_b32_e32 v1, v33
	v_permlane32_swap_b32_e32 v2, v34
	v_permlane32_swap_b32_e32 v3, v35
	v_permlane32_swap_b32_e32 v4, v36
	v_permlane32_swap_b32_e32 v5, v37
	v_permlane32_swap_b32_e32 v6, v38
	v_permlane32_swap_b32_e32 v7, v39
	v_permlane32_swap_b32_e32 v8, v40
	v_permlane32_swap_b32_e32 v9, v41
	v_permlane32_swap_b32_e32 v10, v42
	v_permlane32_swap_b32_e32 v11, v43
	v_permlane32_swap_b32_e32 v12, v44
	v_permlane32_swap_b32_e32 v13, v45
	v_permlane32_swap_b32_e32 v14, v46
	v_permlane32_swap_b32_e32 v15, v47
	v_permlane32_swap_b32_e32 v16, v48
	v_permlane32_swap_b32_e32 v17, v49
	v_permlane32_swap_b32_e32 v18, v50
	v_permlane32_swap_b32_e32 v19, v51
	v_permlane32_swap_b32_e32 v20, v52
	v_permlane32_swap_b32_e32 v21, v53
	v_permlane32_swap_b32_e32 v22, v54
	v_permlane32_swap_b32_e32 v23, v55
	v_permlane32_swap_b32_e32 v24, v56
	v_permlane32_swap_b32_e32 v25, v57
	v_permlane32_swap_b32_e32 v26, v58
	v_permlane32_swap_b32_e32 v27, v59
	v_permlane32_swap_b32_e32 v28, v60
	v_permlane32_swap_b32_e32 v29, v61
	v_permlane32_swap_b32_e32 v30, v62
	v_permlane32_swap_b32_e32 v31, v63
	v_pk_add_f32 v[0:1], v[0:1], v[32:33]
	v_pk_add_f32 v[2:3], v[2:3], v[34:35]
	v_pk_add_f32 v[4:5], v[4:5], v[36:37]
	v_pk_add_f32 v[6:7], v[6:7], v[38:39]
	v_pk_add_f32 v[8:9], v[8:9], v[40:41]
	v_pk_add_f32 v[10:11], v[10:11], v[42:43]
	v_pk_add_f32 v[12:13], v[12:13], v[44:45]
	v_pk_add_f32 v[14:15], v[14:15], v[46:47]
	v_pk_add_f32 v[16:17], v[16:17], v[48:49]
	v_pk_add_f32 v[18:19], v[18:19], v[50:51]
	v_pk_add_f32 v[20:21], v[20:21], v[52:53]
	v_pk_add_f32 v[22:23], v[22:23], v[54:55]
	v_pk_add_f32 v[24:25], v[24:25], v[56:57]
	v_pk_add_f32 v[26:27], v[26:27], v[58:59]
	v_pk_add_f32 v[28:29], v[28:29], v[60:61]
	v_pk_add_f32 v[30:31], v[30:31], v[62:63]
	s_nop 1
	v_permlane16_swap_b32_e32 v0, v16
	v_permlane16_swap_b32_e32 v1, v17
	v_permlane16_swap_b32_e32 v2, v18
	v_permlane16_swap_b32_e32 v3, v19
	v_permlane16_swap_b32_e32 v4, v20
	v_permlane16_swap_b32_e32 v5, v21
	v_permlane16_swap_b32_e32 v6, v22
	v_permlane16_swap_b32_e32 v7, v23
	v_permlane16_swap_b32_e32 v8, v24
	v_permlane16_swap_b32_e32 v9, v25
	v_permlane16_swap_b32_e32 v10, v26
	v_permlane16_swap_b32_e32 v11, v27
	v_permlane16_swap_b32_e32 v12, v28
	v_permlane16_swap_b32_e32 v13, v29
	v_permlane16_swap_b32_e32 v14, v30
	v_permlane16_swap_b32_e32 v15, v31
	v_pk_add_f32 v[0:1], v[0:1], v[16:17]
	v_pk_add_f32 v[2:3], v[2:3], v[18:19]
	v_pk_add_f32 v[4:5], v[4:5], v[20:21]
	v_pk_add_f32 v[6:7], v[6:7], v[22:23]
	v_pk_add_f32 v[8:9], v[8:9], v[24:25]
	v_pk_add_f32 v[10:11], v[10:11], v[26:27]
	v_pk_add_f32 v[12:13], v[12:13], v[28:29]
	v_pk_add_f32 v[14:15], v[14:15], v[30:31]
	s_nop 1
	v_add_f32_dpp v0, v0, v0 row_ror:8 row_mask:0xf bank_mask:0x3
	v_add_f32_dpp v1, v1, v1 row_ror:8 row_mask:0xf bank_mask:0x3
	v_add_f32_dpp v2, v2, v2 row_ror:8 row_mask:0xf bank_mask:0x3
	v_add_f32_dpp v3, v3, v3 row_ror:8 row_mask:0xf bank_mask:0x3
	v_add_f32_dpp v4, v4, v4 row_ror:8 row_mask:0xf bank_mask:0x3
	v_add_f32_dpp v5, v5, v5 row_ror:8 row_mask:0xf bank_mask:0x3
	v_add_f32_dpp v6, v6, v6 row_ror:8 row_mask:0xf bank_mask:0x3
	v_add_f32_dpp v7, v7, v7 row_ror:8 row_mask:0xf bank_mask:0x3
	v_add_f32_dpp v0, v8, v8 row_ror:8 row_mask:0xf bank_mask:0xc
	v_add_f32_dpp v1, v9, v9 row_ror:8 row_mask:0xf bank_mask:0xc
	v_add_f32_dpp v2, v10, v10 row_ror:8 row_mask:0xf bank_mask:0xc
	v_add_f32_dpp v3, v11, v11 row_ror:8 row_mask:0xf bank_mask:0xc
	v_add_f32_dpp v4, v12, v12 row_ror:8 row_mask:0xf bank_mask:0xc
	v_add_f32_dpp v5, v13, v13 row_ror:8 row_mask:0xf bank_mask:0xc
	v_add_f32_dpp v6, v14, v14 row_ror:8 row_mask:0xf bank_mask:0xc
	v_add_f32_dpp v7, v15, v15 row_ror:8 row_mask:0xf bank_mask:0xc
	s_mov_b32 vcc_lo, 0xaaaaaaaa
	s_mov_b32 vcc_hi, 0xaaaaaaaa
	v_cndmask_b32_e32 v64, v0, v4, vcc
	v_cndmask_b32_e32 v65, v1, v5, vcc
	v_cndmask_b32_e32 v66, v2, v6, vcc
	v_cndmask_b32_e32 v67, v3, v7, vcc
	v_cndmask_b32_e32 v68, v4, v0, vcc
	v_cndmask_b32_e32 v69, v5, v1, vcc
	v_cndmask_b32_e32 v70, v6, v2, vcc
	v_cndmask_b32_e32 v71, v7, v3, vcc
	s_nop 1
	v_add_f32_dpp v0, v68, v64 quad_perm:[1,0,3,2] row_mask:0xf bank_mask:0xf
	v_add_f32_dpp v1, v69, v65 quad_perm:[1,0,3,2] row_mask:0xf bank_mask:0xf
	v_add_f32_dpp v2, v70, v66 quad_perm:[1,0,3,2] row_mask:0xf bank_mask:0xf
	v_add_f32_dpp v3, v71, v67 quad_perm:[1,0,3,2] row_mask:0xf bank_mask:0xf
	s_waitcnt vmcnt(24)
	v_pk_add_f32 v[212:213], v[212:213], v[0:1]
	v_pk_add_f32 v[214:215], v[214:215], v[2:3]
	global_store_dwordx4 v220, v[212:215], s[8:9]
	s_add_u32 s14, s14, 1
	s_and_b32 s14, s14, 63
	s_add_u32 s18, s14, 1
	s_and_b32 s98, s18, 63
	s_mov_b32 s100, s98
	s_and_b32 s19, s100, 15
	s_lshr_b32 s98, s100, 4
	s_lshl_b32 s99, s19, 9
	s_mul_i32 s15, s19, s16
	s_lshl_b32 s18, s98, 7
	s_add_u32 s15, s15, s18
	s_lshl_b32 s18, s101, 12
	s_add_u32 s15, s15, s18
	s_add_u32 s8, s24, s15
	s_addc_u32 s9, s25, 0
	s_mul_i32 s15, s98, 0x300000
	s_add_u32 s4, s26, 0x4800000
	s_addc_u32 s5, s27, 0
	s_add_u32 s4, s4, s15
	s_addc_u32 s5, s5, 0
	v_add_u32_e32 v221, s99, v217
	v_add_u32_e32 v223, s99, v218
	s_movk_i32 s100, 0xc0
	ds_read2_b32 v[192:193], v221 offset0:0 offset1:16
	ds_read2_b32 v[194:195], v221 offset0:32 offset1:48
	global_load_dwordx4 v[212:215], v220, s[10:11]
	ds_read2_b32 v[208:209], v224 offset0:64 offset1:80
	ds_read2_b32 v[210:211], v224 offset0:96 offset1:112
	s_waitcnt vmcnt(23)
	v_cvt_scalef32_pk32_f32_fp6 v[64:95], v[96:101], 1.0
	v_pk_mul_f32 v[0:1], v[200:201], v[64:65] op_sel_hi:[0,1]
	v_pk_mul_f32 v[2:3], v[200:201], v[66:67] op_sel_hi:[0,1]
	v_pk_mul_f32 v[4:5], v[200:201], v[68:69] op_sel_hi:[0,1]
	v_pk_mul_f32 v[6:7], v[200:201], v[70:71] op_sel_hi:[0,1]
	v_pk_mul_f32 v[8:9], v[200:201], v[72:73] op_sel_hi:[0,1]
	v_pk_mul_f32 v[10:11], v[200:201], v[74:75] op_sel_hi:[0,1]
	v_pk_mul_f32 v[12:13], v[200:201], v[76:77] op_sel_hi:[0,1]
	v_pk_mul_f32 v[14:15], v[200:201], v[78:79] op_sel_hi:[0,1]
	v_pk_mul_f32 v[16:17], v[200:201], v[80:81] op_sel_hi:[0,1]
	v_pk_mul_f32 v[18:19], v[200:201], v[82:83] op_sel_hi:[0,1]
	v_pk_mul_f32 v[20:21], v[200:201], v[84:85] op_sel_hi:[0,1]
	v_pk_mul_f32 v[22:23], v[200:201], v[86:87] op_sel_hi:[0,1]
	v_pk_mul_f32 v[24:25], v[200:201], v[88:89] op_sel_hi:[0,1]
	v_pk_mul_f32 v[26:27], v[200:201], v[90:91] op_sel_hi:[0,1]
	v_pk_mul_f32 v[28:29], v[200:201], v[92:93] op_sel_hi:[0,1]
	v_pk_mul_f32 v[30:31], v[200:201], v[94:95] op_sel_hi:[0,1]
	v_cvt_scalef32_pk32_f32_fp6 v[64:95], v[102:107], 1.0
	v_pk_mul_f32 v[32:33], v[200:201], v[64:65] op_sel_hi:[0,1]
	v_pk_mul_f32 v[34:35], v[200:201], v[66:67] op_sel_hi:[0,1]
	v_pk_mul_f32 v[36:37], v[200:201], v[68:69] op_sel_hi:[0,1]
	v_pk_mul_f32 v[38:39], v[200:201], v[70:71] op_sel_hi:[0,1]
	v_pk_mul_f32 v[40:41], v[200:201], v[72:73] op_sel_hi:[0,1]
	v_pk_mul_f32 v[42:43], v[200:201], v[74:75] op_sel_hi:[0,1]
	v_pk_mul_f32 v[44:45], v[200:201], v[76:77] op_sel_hi:[0,1]
	v_pk_mul_f32 v[46:47], v[200:201], v[78:79] op_sel_hi:[0,1]
	v_pk_mul_f32 v[48:49], v[200:201], v[80:81] op_sel_hi:[0,1]
	v_pk_mul_f32 v[50:51], v[200:201], v[82:83] op_sel_hi:[0,1]
	v_pk_mul_f32 v[52:53], v[200:201], v[84:85] op_sel_hi:[0,1]
	v_pk_mul_f32 v[54:55], v[200:201], v[86:87] op_sel_hi:[0,1]
	v_pk_mul_f32 v[56:57], v[200:201], v[88:89] op_sel_hi:[0,1]
	v_pk_mul_f32 v[58:59], v[200:201], v[90:91] op_sel_hi:[0,1]
	v_pk_mul_f32 v[60:61], v[200:201], v[92:93] op_sel_hi:[0,1]
	v_pk_mul_f32 v[62:63], v[200:201], v[94:95] op_sel_hi:[0,1]
	s_waitcnt vmcnt(20)
	v_cvt_scalef32_pk32_f32_fp6 v[64:95], v[108:113], 1.0
	v_pk_fma_f32 v[0:1], v[200:201], v[64:65], v[0:1] op_sel:[1,0,0] op_sel_hi:[1,1,1]
	v_pk_fma_f32 v[2:3], v[200:201], v[66:67], v[2:3] op_sel:[1,0,0] op_sel_hi:[1,1,1]
	v_pk_fma_f32 v[4:5], v[200:201], v[68:69], v[4:5] op_sel:[1,0,0] op_sel_hi:[1,1,1]
	v_pk_fma_f32 v[6:7], v[200:201], v[70:71], v[6:7] op_sel:[1,0,0] op_sel_hi:[1,1,1]
	v_pk_fma_f32 v[8:9], v[200:201], v[72:73], v[8:9] op_sel:[1,0,0] op_sel_hi:[1,1,1]
	v_pk_fma_f32 v[10:11], v[200:201], v[74:75], v[10:11] op_sel:[1,0,0] op_sel_hi:[1,1,1]
	v_pk_fma_f32 v[12:13], v[200:201], v[76:77], v[12:13] op_sel:[1,0,0] op_sel_hi:[1,1,1]
	v_pk_fma_f32 v[14:15], v[200:201], v[78:79], v[14:15] op_sel:[1,0,0] op_sel_hi:[1,1,1]
	v_pk_fma_f32 v[16:17], v[200:201], v[80:81], v[16:17] op_sel:[1,0,0] op_sel_hi:[1,1,1]
	v_pk_fma_f32 v[18:19], v[200:201], v[82:83], v[18:19] op_sel:[1,0,0] op_sel_hi:[1,1,1]
	v_pk_fma_f32 v[20:21], v[200:201], v[84:85], v[20:21] op_sel:[1,0,0] op_sel_hi:[1,1,1]
	v_pk_fma_f32 v[22:23], v[200:201], v[86:87], v[22:23] op_sel:[1,0,0] op_sel_hi:[1,1,1]
	v_pk_fma_f32 v[24:25], v[200:201], v[88:89], v[24:25] op_sel:[1,0,0] op_sel_hi:[1,1,1]
	v_pk_fma_f32 v[26:27], v[200:201], v[90:91], v[26:27] op_sel:[1,0,0] op_sel_hi:[1,1,1]
	v_pk_fma_f32 v[28:29], v[200:201], v[92:93], v[28:29] op_sel:[1,0,0] op_sel_hi:[1,1,1]
	v_pk_fma_f32 v[30:31], v[200:201], v[94:95], v[30:31] op_sel:[1,0,0] op_sel_hi:[1,1,1]
	v_cvt_scalef32_pk32_f32_fp6 v[64:95], v[114:119], 1.0
	v_pk_fma_f32 v[32:33], v[200:201], v[64:65], v[32:33] op_sel:[1,0,0] op_sel_hi:[1,1,1]
	v_pk_fma_f32 v[34:35], v[200:201], v[66:67], v[34:35] op_sel:[1,0,0] op_sel_hi:[1,1,1]
	v_pk_fma_f32 v[36:37], v[200:201], v[68:69], v[36:37] op_sel:[1,0,0] op_sel_hi:[1,1,1]
	v_pk_fma_f32 v[38:39], v[200:201], v[70:71], v[38:39] op_sel:[1,0,0] op_sel_hi:[1,1,1]
	v_pk_fma_f32 v[40:41], v[200:201], v[72:73], v[40:41] op_sel:[1,0,0] op_sel_hi:[1,1,1]
	v_pk_fma_f32 v[42:43], v[200:201], v[74:75], v[42:43] op_sel:[1,0,0] op_sel_hi:[1,1,1]
	v_pk_fma_f32 v[44:45], v[200:201], v[76:77], v[44:45] op_sel:[1,0,0] op_sel_hi:[1,1,1]
	v_pk_fma_f32 v[46:47], v[200:201], v[78:79], v[46:47] op_sel:[1,0,0] op_sel_hi:[1,1,1]
	v_pk_fma_f32 v[48:49], v[200:201], v[80:81], v[48:49] op_sel:[1,0,0] op_sel_hi:[1,1,1]
	v_pk_fma_f32 v[50:51], v[200:201], v[82:83], v[50:51] op_sel:[1,0,0] op_sel_hi:[1,1,1]
	v_pk_fma_f32 v[52:53], v[200:201], v[84:85], v[52:53] op_sel:[1,0,0] op_sel_hi:[1,1,1]
	v_pk_fma_f32 v[54:55], v[200:201], v[86:87], v[54:55] op_sel:[1,0,0] op_sel_hi:[1,1,1]
	v_pk_fma_f32 v[56:57], v[200:201], v[88:89], v[56:57] op_sel:[1,0,0] op_sel_hi:[1,1,1]
	v_pk_fma_f32 v[58:59], v[200:201], v[90:91], v[58:59] op_sel:[1,0,0] op_sel_hi:[1,1,1]
	v_pk_fma_f32 v[60:61], v[200:201], v[92:93], v[60:61] op_sel:[1,0,0] op_sel_hi:[1,1,1]
	v_pk_fma_f32 v[62:63], v[200:201], v[94:95], v[62:63] op_sel:[1,0,0] op_sel_hi:[1,1,1]
	s_waitcnt vmcnt(17)
	v_cvt_scalef32_pk32_f32_fp6 v[64:95], v[120:125], 1.0
	v_pk_fma_f32 v[0:1], v[202:203], v[64:65], v[0:1] op_sel_hi:[0,1,1]
	v_pk_fma_f32 v[2:3], v[202:203], v[66:67], v[2:3] op_sel_hi:[0,1,1]
	v_pk_fma_f32 v[4:5], v[202:203], v[68:69], v[4:5] op_sel_hi:[0,1,1]
	v_pk_fma_f32 v[6:7], v[202:203], v[70:71], v[6:7] op_sel_hi:[0,1,1]
	v_pk_fma_f32 v[8:9], v[202:203], v[72:73], v[8:9] op_sel_hi:[0,1,1]
	v_pk_fma_f32 v[10:11], v[202:203], v[74:75], v[10:11] op_sel_hi:[0,1,1]
	v_pk_fma_f32 v[12:13], v[202:203], v[76:77], v[12:13] op_sel_hi:[0,1,1]
	v_pk_fma_f32 v[14:15], v[202:203], v[78:79], v[14:15] op_sel_hi:[0,1,1]
	v_pk_fma_f32 v[16:17], v[202:203], v[80:81], v[16:17] op_sel_hi:[0,1,1]
	v_pk_fma_f32 v[18:19], v[202:203], v[82:83], v[18:19] op_sel_hi:[0,1,1]
	v_pk_fma_f32 v[20:21], v[202:203], v[84:85], v[20:21] op_sel_hi:[0,1,1]
	v_pk_fma_f32 v[22:23], v[202:203], v[86:87], v[22:23] op_sel_hi:[0,1,1]
	v_pk_fma_f32 v[24:25], v[202:203], v[88:89], v[24:25] op_sel_hi:[0,1,1]
	v_pk_fma_f32 v[26:27], v[202:203], v[90:91], v[26:27] op_sel_hi:[0,1,1]
	v_pk_fma_f32 v[28:29], v[202:203], v[92:93], v[28:29] op_sel_hi:[0,1,1]
	v_pk_fma_f32 v[30:31], v[202:203], v[94:95], v[30:31] op_sel_hi:[0,1,1]
	v_cvt_scalef32_pk32_f32_fp6 v[64:95], v[126:131], 1.0
	v_pk_fma_f32 v[32:33], v[202:203], v[64:65], v[32:33] op_sel_hi:[0,1,1]
	v_pk_fma_f32 v[34:35], v[202:203], v[66:67], v[34:35] op_sel_hi:[0,1,1]
	v_pk_fma_f32 v[36:37], v[202:203], v[68:69], v[36:37] op_sel_hi:[0,1,1]
	v_pk_fma_f32 v[38:39], v[202:203], v[70:71], v[38:39] op_sel_hi:[0,1,1]
	v_pk_fma_f32 v[40:41], v[202:203], v[72:73], v[40:41] op_sel_hi:[0,1,1]
	v_pk_fma_f32 v[42:43], v[202:203], v[74:75], v[42:43] op_sel_hi:[0,1,1]
	v_pk_fma_f32 v[44:45], v[202:203], v[76:77], v[44:45] op_sel_hi:[0,1,1]
	v_pk_fma_f32 v[46:47], v[202:203], v[78:79], v[46:47] op_sel_hi:[0,1,1]
	v_pk_fma_f32 v[48:49], v[202:203], v[80:81], v[48:49] op_sel_hi:[0,1,1]
	v_pk_fma_f32 v[50:51], v[202:203], v[82:83], v[50:51] op_sel_hi:[0,1,1]
	v_pk_fma_f32 v[52:53], v[202:203], v[84:85], v[52:53] op_sel_hi:[0,1,1]
	v_pk_fma_f32 v[54:55], v[202:203], v[86:87], v[54:55] op_sel_hi:[0,1,1]
	v_pk_fma_f32 v[56:57], v[202:203], v[88:89], v[56:57] op_sel_hi:[0,1,1]
	v_pk_fma_f32 v[58:59], v[202:203], v[90:91], v[58:59] op_sel_hi:[0,1,1]
	v_pk_fma_f32 v[60:61], v[202:203], v[92:93], v[60:61] op_sel_hi:[0,1,1]
	v_pk_fma_f32 v[62:63], v[202:203], v[94:95], v[62:63] op_sel_hi:[0,1,1]
	s_waitcnt vmcnt(14)
	v_cvt_scalef32_pk32_f32_fp6 v[64:95], v[132:137], 1.0
	v_pk_fma_f32 v[0:1], v[202:203], v[64:65], v[0:1] op_sel:[1,0,0] op_sel_hi:[1,1,1]
	v_pk_fma_f32 v[2:3], v[202:203], v[66:67], v[2:3] op_sel:[1,0,0] op_sel_hi:[1,1,1]
	v_pk_fma_f32 v[4:5], v[202:203], v[68:69], v[4:5] op_sel:[1,0,0] op_sel_hi:[1,1,1]
	v_pk_fma_f32 v[6:7], v[202:203], v[70:71], v[6:7] op_sel:[1,0,0] op_sel_hi:[1,1,1]
	v_pk_fma_f32 v[8:9], v[202:203], v[72:73], v[8:9] op_sel:[1,0,0] op_sel_hi:[1,1,1]
	v_pk_fma_f32 v[10:11], v[202:203], v[74:75], v[10:11] op_sel:[1,0,0] op_sel_hi:[1,1,1]
	v_pk_fma_f32 v[12:13], v[202:203], v[76:77], v[12:13] op_sel:[1,0,0] op_sel_hi:[1,1,1]
	v_pk_fma_f32 v[14:15], v[202:203], v[78:79], v[14:15] op_sel:[1,0,0] op_sel_hi:[1,1,1]
	v_pk_fma_f32 v[16:17], v[202:203], v[80:81], v[16:17] op_sel:[1,0,0] op_sel_hi:[1,1,1]
	v_pk_fma_f32 v[18:19], v[202:203], v[82:83], v[18:19] op_sel:[1,0,0] op_sel_hi:[1,1,1]
	v_pk_fma_f32 v[20:21], v[202:203], v[84:85], v[20:21] op_sel:[1,0,0] op_sel_hi:[1,1,1]
	v_pk_fma_f32 v[22:23], v[202:203], v[86:87], v[22:23] op_sel:[1,0,0] op_sel_hi:[1,1,1]
	v_pk_fma_f32 v[24:25], v[202:203], v[88:89], v[24:25] op_sel:[1,0,0] op_sel_hi:[1,1,1]
	v_pk_fma_f32 v[26:27], v[202:203], v[90:91], v[26:27] op_sel:[1,0,0] op_sel_hi:[1,1,1]
	v_pk_fma_f32 v[28:29], v[202:203], v[92:93], v[28:29] op_sel:[1,0,0] op_sel_hi:[1,1,1]
	v_pk_fma_f32 v[30:31], v[202:203], v[94:95], v[30:31] op_sel:[1,0,0] op_sel_hi:[1,1,1]
	v_cvt_scalef32_pk32_f32_fp6 v[64:95], v[138:143], 1.0
	v_pk_fma_f32 v[32:33], v[202:203], v[64:65], v[32:33] op_sel:[1,0,0] op_sel_hi:[1,1,1]
	v_pk_fma_f32 v[34:35], v[202:203], v[66:67], v[34:35] op_sel:[1,0,0] op_sel_hi:[1,1,1]
	v_pk_fma_f32 v[36:37], v[202:203], v[68:69], v[36:37] op_sel:[1,0,0] op_sel_hi:[1,1,1]
	v_pk_fma_f32 v[38:39], v[202:203], v[70:71], v[38:39] op_sel:[1,0,0] op_sel_hi:[1,1,1]
	v_pk_fma_f32 v[40:41], v[202:203], v[72:73], v[40:41] op_sel:[1,0,0] op_sel_hi:[1,1,1]
	v_pk_fma_f32 v[42:43], v[202:203], v[74:75], v[42:43] op_sel:[1,0,0] op_sel_hi:[1,1,1]
	v_pk_fma_f32 v[44:45], v[202:203], v[76:77], v[44:45] op_sel:[1,0,0] op_sel_hi:[1,1,1]
	v_pk_fma_f32 v[46:47], v[202:203], v[78:79], v[46:47] op_sel:[1,0,0] op_sel_hi:[1,1,1]
	v_pk_fma_f32 v[48:49], v[202:203], v[80:81], v[48:49] op_sel:[1,0,0] op_sel_hi:[1,1,1]
	v_pk_fma_f32 v[50:51], v[202:203], v[82:83], v[50:51] op_sel:[1,0,0] op_sel_hi:[1,1,1]
	v_pk_fma_f32 v[52:53], v[202:203], v[84:85], v[52:53] op_sel:[1,0,0] op_sel_hi:[1,1,1]
	v_pk_fma_f32 v[54:55], v[202:203], v[86:87], v[54:55] op_sel:[1,0,0] op_sel_hi:[1,1,1]
	v_pk_fma_f32 v[56:57], v[202:203], v[88:89], v[56:57] op_sel:[1,0,0] op_sel_hi:[1,1,1]
	v_pk_fma_f32 v[58:59], v[202:203], v[90:91], v[58:59] op_sel:[1,0,0] op_sel_hi:[1,1,1]
	v_pk_fma_f32 v[60:61], v[202:203], v[92:93], v[60:61] op_sel:[1,0,0] op_sel_hi:[1,1,1]
	v_pk_fma_f32 v[62:63], v[202:203], v[94:95], v[62:63] op_sel:[1,0,0] op_sel_hi:[1,1,1]
	s_waitcnt lgkmcnt(0)
	v_mad_u32_u24 v192, v192, s100, v219
	v_mad_u32_u24 v193, v193, s100, v219
	v_mad_u32_u24 v194, v194, s100, v219
	v_mad_u32_u24 v195, v195, s100, v219
	global_load_dwordx4 v[96:99], v192, s[4:5]
	global_load_dwordx4 v[100:103], v192, s[4:5] offset:16
	global_load_dwordx4 v[104:107], v192, s[4:5] offset:32
	global_load_dwordx4 v[108:111], v193, s[4:5]
	global_load_dwordx4 v[112:115], v193, s[4:5] offset:16
	global_load_dwordx4 v[116:119], v193, s[4:5] offset:32
	global_load_dwordx4 v[120:123], v194, s[4:5]
	global_load_dwordx4 v[124:127], v194, s[4:5] offset:16
	global_load_dwordx4 v[128:131], v194, s[4:5] offset:32
	global_load_dwordx4 v[132:135], v195, s[4:5]
	global_load_dwordx4 v[136:139], v195, s[4:5] offset:16
	global_load_dwordx4 v[140:143], v195, s[4:5] offset:32
	ds_read2_b32 v[196:197], v221 offset0:64 offset1:80
	ds_read2_b32 v[198:199], v221 offset0:96 offset1:112
	ds_read2_b32 v[200:201], v223 offset0:0 offset1:16
	ds_read2_b32 v[202:203], v223 offset0:32 offset1:48
	s_waitcnt vmcnt(23)
	v_cvt_scalef32_pk32_f32_fp6 v[64:95], v[144:149], 1.0
	v_pk_fma_f32 v[0:1], v[208:209], v[64:65], v[0:1] op_sel_hi:[0,1,1]
	v_pk_fma_f32 v[2:3], v[208:209], v[66:67], v[2:3] op_sel_hi:[0,1,1]
	v_pk_fma_f32 v[4:5], v[208:209], v[68:69], v[4:5] op_sel_hi:[0,1,1]
	v_pk_fma_f32 v[6:7], v[208:209], v[70:71], v[6:7] op_sel_hi:[0,1,1]
	v_pk_fma_f32 v[8:9], v[208:209], v[72:73], v[8:9] op_sel_hi:[0,1,1]
	v_pk_fma_f32 v[10:11], v[208:209], v[74:75], v[10:11] op_sel_hi:[0,1,1]
	v_pk_fma_f32 v[12:13], v[208:209], v[76:77], v[12:13] op_sel_hi:[0,1,1]
	v_pk_fma_f32 v[14:15], v[208:209], v[78:79], v[14:15] op_sel_hi:[0,1,1]
	v_pk_fma_f32 v[16:17], v[208:209], v[80:81], v[16:17] op_sel_hi:[0,1,1]
	v_pk_fma_f32 v[18:19], v[208:209], v[82:83], v[18:19] op_sel_hi:[0,1,1]
	v_pk_fma_f32 v[20:21], v[208:209], v[84:85], v[20:21] op_sel_hi:[0,1,1]
	v_pk_fma_f32 v[22:23], v[208:209], v[86:87], v[22:23] op_sel_hi:[0,1,1]
	v_pk_fma_f32 v[24:25], v[208:209], v[88:89], v[24:25] op_sel_hi:[0,1,1]
	v_pk_fma_f32 v[26:27], v[208:209], v[90:91], v[26:27] op_sel_hi:[0,1,1]
	v_pk_fma_f32 v[28:29], v[208:209], v[92:93], v[28:29] op_sel_hi:[0,1,1]
	v_pk_fma_f32 v[30:31], v[208:209], v[94:95], v[30:31] op_sel_hi:[0,1,1]
	v_cvt_scalef32_pk32_f32_fp6 v[64:95], v[150:155], 1.0
	v_pk_fma_f32 v[32:33], v[208:209], v[64:65], v[32:33] op_sel_hi:[0,1,1]
	v_pk_fma_f32 v[34:35], v[208:209], v[66:67], v[34:35] op_sel_hi:[0,1,1]
	v_pk_fma_f32 v[36:37], v[208:209], v[68:69], v[36:37] op_sel_hi:[0,1,1]
	v_pk_fma_f32 v[38:39], v[208:209], v[70:71], v[38:39] op_sel_hi:[0,1,1]
	v_pk_fma_f32 v[40:41], v[208:209], v[72:73], v[40:41] op_sel_hi:[0,1,1]
	v_pk_fma_f32 v[42:43], v[208:209], v[74:75], v[42:43] op_sel_hi:[0,1,1]
	v_pk_fma_f32 v[44:45], v[208:209], v[76:77], v[44:45] op_sel_hi:[0,1,1]
	v_pk_fma_f32 v[46:47], v[208:209], v[78:79], v[46:47] op_sel_hi:[0,1,1]
	v_pk_fma_f32 v[48:49], v[208:209], v[80:81], v[48:49] op_sel_hi:[0,1,1]
	v_pk_fma_f32 v[50:51], v[208:209], v[82:83], v[50:51] op_sel_hi:[0,1,1]
	v_pk_fma_f32 v[52:53], v[208:209], v[84:85], v[52:53] op_sel_hi:[0,1,1]
	v_pk_fma_f32 v[54:55], v[208:209], v[86:87], v[54:55] op_sel_hi:[0,1,1]
	v_pk_fma_f32 v[56:57], v[208:209], v[88:89], v[56:57] op_sel_hi:[0,1,1]
	v_pk_fma_f32 v[58:59], v[208:209], v[90:91], v[58:59] op_sel_hi:[0,1,1]
	v_pk_fma_f32 v[60:61], v[208:209], v[92:93], v[60:61] op_sel_hi:[0,1,1]
	v_pk_fma_f32 v[62:63], v[208:209], v[94:95], v[62:63] op_sel_hi:[0,1,1]
	s_waitcnt vmcnt(20)
	v_cvt_scalef32_pk32_f32_fp6 v[64:95], v[156:161], 1.0
	v_pk_fma_f32 v[0:1], v[208:209], v[64:65], v[0:1] op_sel:[1,0,0] op_sel_hi:[1,1,1]
	v_pk_fma_f32 v[2:3], v[208:209], v[66:67], v[2:3] op_sel:[1,0,0] op_sel_hi:[1,1,1]
	v_pk_fma_f32 v[4:5], v[208:209], v[68:69], v[4:5] op_sel:[1,0,0] op_sel_hi:[1,1,1]
	v_pk_fma_f32 v[6:7], v[208:209], v[70:71], v[6:7] op_sel:[1,0,0] op_sel_hi:[1,1,1]
	v_pk_fma_f32 v[8:9], v[208:209], v[72:73], v[8:9] op_sel:[1,0,0] op_sel_hi:[1,1,1]
	v_pk_fma_f32 v[10:11], v[208:209], v[74:75], v[10:11] op_sel:[1,0,0] op_sel_hi:[1,1,1]
	v_pk_fma_f32 v[12:13], v[208:209], v[76:77], v[12:13] op_sel:[1,0,0] op_sel_hi:[1,1,1]
	v_pk_fma_f32 v[14:15], v[208:209], v[78:79], v[14:15] op_sel:[1,0,0] op_sel_hi:[1,1,1]
	v_pk_fma_f32 v[16:17], v[208:209], v[80:81], v[16:17] op_sel:[1,0,0] op_sel_hi:[1,1,1]
	v_pk_fma_f32 v[18:19], v[208:209], v[82:83], v[18:19] op_sel:[1,0,0] op_sel_hi:[1,1,1]
	v_pk_fma_f32 v[20:21], v[208:209], v[84:85], v[20:21] op_sel:[1,0,0] op_sel_hi:[1,1,1]
	v_pk_fma_f32 v[22:23], v[208:209], v[86:87], v[22:23] op_sel:[1,0,0] op_sel_hi:[1,1,1]
	v_pk_fma_f32 v[24:25], v[208:209], v[88:89], v[24:25] op_sel:[1,0,0] op_sel_hi:[1,1,1]
	v_pk_fma_f32 v[26:27], v[208:209], v[90:91], v[26:27] op_sel:[1,0,0] op_sel_hi:[1,1,1]
	v_pk_fma_f32 v[28:29], v[208:209], v[92:93], v[28:29] op_sel:[1,0,0] op_sel_hi:[1,1,1]
	v_pk_fma_f32 v[30:31], v[208:209], v[94:95], v[30:31] op_sel:[1,0,0] op_sel_hi:[1,1,1]
	v_cvt_scalef32_pk32_f32_fp6 v[64:95], v[162:167], 1.0
	v_pk_fma_f32 v[32:33], v[208:209], v[64:65], v[32:33] op_sel:[1,0,0] op_sel_hi:[1,1,1]
	v_pk_fma_f32 v[34:35], v[208:209], v[66:67], v[34:35] op_sel:[1,0,0] op_sel_hi:[1,1,1]
	v_pk_fma_f32 v[36:37], v[208:209], v[68:69], v[36:37] op_sel:[1,0,0] op_sel_hi:[1,1,1]
	v_pk_fma_f32 v[38:39], v[208:209], v[70:71], v[38:39] op_sel:[1,0,0] op_sel_hi:[1,1,1]
	v_pk_fma_f32 v[40:41], v[208:209], v[72:73], v[40:41] op_sel:[1,0,0] op_sel_hi:[1,1,1]
	v_pk_fma_f32 v[42:43], v[208:209], v[74:75], v[42:43] op_sel:[1,0,0] op_sel_hi:[1,1,1]
	v_pk_fma_f32 v[44:45], v[208:209], v[76:77], v[44:45] op_sel:[1,0,0] op_sel_hi:[1,1,1]
	v_pk_fma_f32 v[46:47], v[208:209], v[78:79], v[46:47] op_sel:[1,0,0] op_sel_hi:[1,1,1]
	v_pk_fma_f32 v[48:49], v[208:209], v[80:81], v[48:49] op_sel:[1,0,0] op_sel_hi:[1,1,1]
	v_pk_fma_f32 v[50:51], v[208:209], v[82:83], v[50:51] op_sel:[1,0,0] op_sel_hi:[1,1,1]
	v_pk_fma_f32 v[52:53], v[208:209], v[84:85], v[52:53] op_sel:[1,0,0] op_sel_hi:[1,1,1]
	v_pk_fma_f32 v[54:55], v[208:209], v[86:87], v[54:55] op_sel:[1,0,0] op_sel_hi:[1,1,1]
	v_pk_fma_f32 v[56:57], v[208:209], v[88:89], v[56:57] op_sel:[1,0,0] op_sel_hi:[1,1,1]
	v_pk_fma_f32 v[58:59], v[208:209], v[90:91], v[58:59] op_sel:[1,0,0] op_sel_hi:[1,1,1]
	v_pk_fma_f32 v[60:61], v[208:209], v[92:93], v[60:61] op_sel:[1,0,0] op_sel_hi:[1,1,1]
	v_pk_fma_f32 v[62:63], v[208:209], v[94:95], v[62:63] op_sel:[1,0,0] op_sel_hi:[1,1,1]
	s_waitcnt vmcnt(17)
	v_cvt_scalef32_pk32_f32_fp6 v[64:95], v[168:173], 1.0
	v_pk_fma_f32 v[0:1], v[210:211], v[64:65], v[0:1] op_sel_hi:[0,1,1]
	v_pk_fma_f32 v[2:3], v[210:211], v[66:67], v[2:3] op_sel_hi:[0,1,1]
	v_pk_fma_f32 v[4:5], v[210:211], v[68:69], v[4:5] op_sel_hi:[0,1,1]
	v_pk_fma_f32 v[6:7], v[210:211], v[70:71], v[6:7] op_sel_hi:[0,1,1]
	v_pk_fma_f32 v[8:9], v[210:211], v[72:73], v[8:9] op_sel_hi:[0,1,1]
	v_pk_fma_f32 v[10:11], v[210:211], v[74:75], v[10:11] op_sel_hi:[0,1,1]
	v_pk_fma_f32 v[12:13], v[210:211], v[76:77], v[12:13] op_sel_hi:[0,1,1]
	v_pk_fma_f32 v[14:15], v[210:211], v[78:79], v[14:15] op_sel_hi:[0,1,1]
	v_pk_fma_f32 v[16:17], v[210:211], v[80:81], v[16:17] op_sel_hi:[0,1,1]
	v_pk_fma_f32 v[18:19], v[210:211], v[82:83], v[18:19] op_sel_hi:[0,1,1]
	v_pk_fma_f32 v[20:21], v[210:211], v[84:85], v[20:21] op_sel_hi:[0,1,1]
	v_pk_fma_f32 v[22:23], v[210:211], v[86:87], v[22:23] op_sel_hi:[0,1,1]
	v_pk_fma_f32 v[24:25], v[210:211], v[88:89], v[24:25] op_sel_hi:[0,1,1]
	v_pk_fma_f32 v[26:27], v[210:211], v[90:91], v[26:27] op_sel_hi:[0,1,1]
	v_pk_fma_f32 v[28:29], v[210:211], v[92:93], v[28:29] op_sel_hi:[0,1,1]
	v_pk_fma_f32 v[30:31], v[210:211], v[94:95], v[30:31] op_sel_hi:[0,1,1]
	v_cvt_scalef32_pk32_f32_fp6 v[64:95], v[174:179], 1.0
	v_pk_fma_f32 v[32:33], v[210:211], v[64:65], v[32:33] op_sel_hi:[0,1,1]
	v_pk_fma_f32 v[34:35], v[210:211], v[66:67], v[34:35] op_sel_hi:[0,1,1]
	v_pk_fma_f32 v[36:37], v[210:211], v[68:69], v[36:37] op_sel_hi:[0,1,1]
	v_pk_fma_f32 v[38:39], v[210:211], v[70:71], v[38:39] op_sel_hi:[0,1,1]
	v_pk_fma_f32 v[40:41], v[210:211], v[72:73], v[40:41] op_sel_hi:[0,1,1]
	v_pk_fma_f32 v[42:43], v[210:211], v[74:75], v[42:43] op_sel_hi:[0,1,1]
	v_pk_fma_f32 v[44:45], v[210:211], v[76:77], v[44:45] op_sel_hi:[0,1,1]
	v_pk_fma_f32 v[46:47], v[210:211], v[78:79], v[46:47] op_sel_hi:[0,1,1]
	v_pk_fma_f32 v[48:49], v[210:211], v[80:81], v[48:49] op_sel_hi:[0,1,1]
	v_pk_fma_f32 v[50:51], v[210:211], v[82:83], v[50:51] op_sel_hi:[0,1,1]
	v_pk_fma_f32 v[52:53], v[210:211], v[84:85], v[52:53] op_sel_hi:[0,1,1]
	v_pk_fma_f32 v[54:55], v[210:211], v[86:87], v[54:55] op_sel_hi:[0,1,1]
	v_pk_fma_f32 v[56:57], v[210:211], v[88:89], v[56:57] op_sel_hi:[0,1,1]
	v_pk_fma_f32 v[58:59], v[210:211], v[90:91], v[58:59] op_sel_hi:[0,1,1]
	v_pk_fma_f32 v[60:61], v[210:211], v[92:93], v[60:61] op_sel_hi:[0,1,1]
	v_pk_fma_f32 v[62:63], v[210:211], v[94:95], v[62:63] op_sel_hi:[0,1,1]
	s_waitcnt vmcnt(14)
	v_cvt_scalef32_pk32_f32_fp6 v[64:95], v[180:185], 1.0
	v_pk_fma_f32 v[0:1], v[210:211], v[64:65], v[0:1] op_sel:[1,0,0] op_sel_hi:[1,1,1]
	v_pk_fma_f32 v[2:3], v[210:211], v[66:67], v[2:3] op_sel:[1,0,0] op_sel_hi:[1,1,1]
	v_pk_fma_f32 v[4:5], v[210:211], v[68:69], v[4:5] op_sel:[1,0,0] op_sel_hi:[1,1,1]
	v_pk_fma_f32 v[6:7], v[210:211], v[70:71], v[6:7] op_sel:[1,0,0] op_sel_hi:[1,1,1]
	v_pk_fma_f32 v[8:9], v[210:211], v[72:73], v[8:9] op_sel:[1,0,0] op_sel_hi:[1,1,1]
	v_pk_fma_f32 v[10:11], v[210:211], v[74:75], v[10:11] op_sel:[1,0,0] op_sel_hi:[1,1,1]
	v_pk_fma_f32 v[12:13], v[210:211], v[76:77], v[12:13] op_sel:[1,0,0] op_sel_hi:[1,1,1]
	v_pk_fma_f32 v[14:15], v[210:211], v[78:79], v[14:15] op_sel:[1,0,0] op_sel_hi:[1,1,1]
	v_pk_fma_f32 v[16:17], v[210:211], v[80:81], v[16:17] op_sel:[1,0,0] op_sel_hi:[1,1,1]
	v_pk_fma_f32 v[18:19], v[210:211], v[82:83], v[18:19] op_sel:[1,0,0] op_sel_hi:[1,1,1]
	v_pk_fma_f32 v[20:21], v[210:211], v[84:85], v[20:21] op_sel:[1,0,0] op_sel_hi:[1,1,1]
	v_pk_fma_f32 v[22:23], v[210:211], v[86:87], v[22:23] op_sel:[1,0,0] op_sel_hi:[1,1,1]
	v_pk_fma_f32 v[24:25], v[210:211], v[88:89], v[24:25] op_sel:[1,0,0] op_sel_hi:[1,1,1]
	v_pk_fma_f32 v[26:27], v[210:211], v[90:91], v[26:27] op_sel:[1,0,0] op_sel_hi:[1,1,1]
	v_pk_fma_f32 v[28:29], v[210:211], v[92:93], v[28:29] op_sel:[1,0,0] op_sel_hi:[1,1,1]
	v_pk_fma_f32 v[30:31], v[210:211], v[94:95], v[30:31] op_sel:[1,0,0] op_sel_hi:[1,1,1]
	v_cvt_scalef32_pk32_f32_fp6 v[64:95], v[186:191], 1.0
	v_pk_fma_f32 v[32:33], v[210:211], v[64:65], v[32:33] op_sel:[1,0,0] op_sel_hi:[1,1,1]
	v_pk_fma_f32 v[34:35], v[210:211], v[66:67], v[34:35] op_sel:[1,0,0] op_sel_hi:[1,1,1]
	v_pk_fma_f32 v[36:37], v[210:211], v[68:69], v[36:37] op_sel:[1,0,0] op_sel_hi:[1,1,1]
	v_pk_fma_f32 v[38:39], v[210:211], v[70:71], v[38:39] op_sel:[1,0,0] op_sel_hi:[1,1,1]
	v_pk_fma_f32 v[40:41], v[210:211], v[72:73], v[40:41] op_sel:[1,0,0] op_sel_hi:[1,1,1]
	v_pk_fma_f32 v[42:43], v[210:211], v[74:75], v[42:43] op_sel:[1,0,0] op_sel_hi:[1,1,1]
	v_pk_fma_f32 v[44:45], v[210:211], v[76:77], v[44:45] op_sel:[1,0,0] op_sel_hi:[1,1,1]
	v_pk_fma_f32 v[46:47], v[210:211], v[78:79], v[46:47] op_sel:[1,0,0] op_sel_hi:[1,1,1]
	v_pk_fma_f32 v[48:49], v[210:211], v[80:81], v[48:49] op_sel:[1,0,0] op_sel_hi:[1,1,1]
	v_pk_fma_f32 v[50:51], v[210:211], v[82:83], v[50:51] op_sel:[1,0,0] op_sel_hi:[1,1,1]
	v_pk_fma_f32 v[52:53], v[210:211], v[84:85], v[52:53] op_sel:[1,0,0] op_sel_hi:[1,1,1]
	v_pk_fma_f32 v[54:55], v[210:211], v[86:87], v[54:55] op_sel:[1,0,0] op_sel_hi:[1,1,1]
	v_pk_fma_f32 v[56:57], v[210:211], v[88:89], v[56:57] op_sel:[1,0,0] op_sel_hi:[1,1,1]
	v_pk_fma_f32 v[58:59], v[210:211], v[90:91], v[58:59] op_sel:[1,0,0] op_sel_hi:[1,1,1]
	v_pk_fma_f32 v[60:61], v[210:211], v[92:93], v[60:61] op_sel:[1,0,0] op_sel_hi:[1,1,1]
	v_pk_fma_f32 v[62:63], v[210:211], v[94:95], v[62:63] op_sel:[1,0,0] op_sel_hi:[1,1,1]
	s_waitcnt lgkmcnt(0)
	v_mad_u32_u24 v196, v196, s100, v219
	v_mad_u32_u24 v197, v197, s100, v219
	v_mad_u32_u24 v198, v198, s100, v219
	v_mad_u32_u24 v199, v199, s100, v219
	global_load_dwordx4 v[144:147], v196, s[4:5]
	global_load_dwordx4 v[148:151], v196, s[4:5] offset:16
	global_load_dwordx4 v[152:155], v196, s[4:5] offset:32
	global_load_dwordx4 v[156:159], v197, s[4:5]
	global_load_dwordx4 v[160:163], v197, s[4:5] offset:16
	global_load_dwordx4 v[164:167], v197, s[4:5] offset:32
	global_load_dwordx4 v[168:171], v198, s[4:5]
	global_load_dwordx4 v[172:175], v198, s[4:5] offset:16
	global_load_dwordx4 v[176:179], v198, s[4:5] offset:32
	global_load_dwordx4 v[180:183], v199, s[4:5]
	global_load_dwordx4 v[184:187], v199, s[4:5] offset:16
	global_load_dwordx4 v[188:191], v199, s[4:5] offset:32
	s_nop 1
	v_permlane32_swap_b32_e32 v0, v32
	v_permlane32_swap_b32_e32 v1, v33
	v_permlane32_swap_b32_e32 v2, v34
	v_permlane32_swap_b32_e32 v3, v35
	v_permlane32_swap_b32_e32 v4, v36
	v_permlane32_swap_b32_e32 v5, v37
	v_permlane32_swap_b32_e32 v6, v38
	v_permlane32_swap_b32_e32 v7, v39
	v_permlane32_swap_b32_e32 v8, v40
	v_permlane32_swap_b32_e32 v9, v41
	v_permlane32_swap_b32_e32 v10, v42
	v_permlane32_swap_b32_e32 v11, v43
	v_permlane32_swap_b32_e32 v12, v44
	v_permlane32_swap_b32_e32 v13, v45
	v_permlane32_swap_b32_e32 v14, v46
	v_permlane32_swap_b32_e32 v15, v47
	v_permlane32_swap_b32_e32 v16, v48
	v_permlane32_swap_b32_e32 v17, v49
	v_permlane32_swap_b32_e32 v18, v50
	v_permlane32_swap_b32_e32 v19, v51
	v_permlane32_swap_b32_e32 v20, v52
	v_permlane32_swap_b32_e32 v21, v53
	v_permlane32_swap_b32_e32 v22, v54
	v_permlane32_swap_b32_e32 v23, v55
	v_permlane32_swap_b32_e32 v24, v56
	v_permlane32_swap_b32_e32 v25, v57
	v_permlane32_swap_b32_e32 v26, v58
	v_permlane32_swap_b32_e32 v27, v59
	v_permlane32_swap_b32_e32 v28, v60
	v_permlane32_swap_b32_e32 v29, v61
	v_permlane32_swap_b32_e32 v30, v62
	v_permlane32_swap_b32_e32 v31, v63
	v_pk_add_f32 v[0:1], v[0:1], v[32:33]
	v_pk_add_f32 v[2:3], v[2:3], v[34:35]
	v_pk_add_f32 v[4:5], v[4:5], v[36:37]
	v_pk_add_f32 v[6:7], v[6:7], v[38:39]
	v_pk_add_f32 v[8:9], v[8:9], v[40:41]
	v_pk_add_f32 v[10:11], v[10:11], v[42:43]
	v_pk_add_f32 v[12:13], v[12:13], v[44:45]
	v_pk_add_f32 v[14:15], v[14:15], v[46:47]
	v_pk_add_f32 v[16:17], v[16:17], v[48:49]
	v_pk_add_f32 v[18:19], v[18:19], v[50:51]
	v_pk_add_f32 v[20:21], v[20:21], v[52:53]
	v_pk_add_f32 v[22:23], v[22:23], v[54:55]
	v_pk_add_f32 v[24:25], v[24:25], v[56:57]
	v_pk_add_f32 v[26:27], v[26:27], v[58:59]
	v_pk_add_f32 v[28:29], v[28:29], v[60:61]
	v_pk_add_f32 v[30:31], v[30:31], v[62:63]
	s_nop 1
	v_permlane16_swap_b32_e32 v0, v16
	v_permlane16_swap_b32_e32 v1, v17
	v_permlane16_swap_b32_e32 v2, v18
	v_permlane16_swap_b32_e32 v3, v19
	v_permlane16_swap_b32_e32 v4, v20
	v_permlane16_swap_b32_e32 v5, v21
	v_permlane16_swap_b32_e32 v6, v22
	v_permlane16_swap_b32_e32 v7, v23
	v_permlane16_swap_b32_e32 v8, v24
	v_permlane16_swap_b32_e32 v9, v25
	v_permlane16_swap_b32_e32 v10, v26
	v_permlane16_swap_b32_e32 v11, v27
	v_permlane16_swap_b32_e32 v12, v28
	v_permlane16_swap_b32_e32 v13, v29
	v_permlane16_swap_b32_e32 v14, v30
	v_permlane16_swap_b32_e32 v15, v31
	v_pk_add_f32 v[0:1], v[0:1], v[16:17]
	v_pk_add_f32 v[2:3], v[2:3], v[18:19]
	v_pk_add_f32 v[4:5], v[4:5], v[20:21]
	v_pk_add_f32 v[6:7], v[6:7], v[22:23]
	v_pk_add_f32 v[8:9], v[8:9], v[24:25]
	v_pk_add_f32 v[10:11], v[10:11], v[26:27]
	v_pk_add_f32 v[12:13], v[12:13], v[28:29]
	v_pk_add_f32 v[14:15], v[14:15], v[30:31]
	s_nop 1
	v_add_f32_dpp v0, v0, v0 row_ror:8 row_mask:0xf bank_mask:0x3
	v_add_f32_dpp v1, v1, v1 row_ror:8 row_mask:0xf bank_mask:0x3
	v_add_f32_dpp v2, v2, v2 row_ror:8 row_mask:0xf bank_mask:0x3
	v_add_f32_dpp v3, v3, v3 row_ror:8 row_mask:0xf bank_mask:0x3
	v_add_f32_dpp v4, v4, v4 row_ror:8 row_mask:0xf bank_mask:0x3
	v_add_f32_dpp v5, v5, v5 row_ror:8 row_mask:0xf bank_mask:0x3
	v_add_f32_dpp v6, v6, v6 row_ror:8 row_mask:0xf bank_mask:0x3
	v_add_f32_dpp v7, v7, v7 row_ror:8 row_mask:0xf bank_mask:0x3
	v_add_f32_dpp v0, v8, v8 row_ror:8 row_mask:0xf bank_mask:0xc
	v_add_f32_dpp v1, v9, v9 row_ror:8 row_mask:0xf bank_mask:0xc
	v_add_f32_dpp v2, v10, v10 row_ror:8 row_mask:0xf bank_mask:0xc
	v_add_f32_dpp v3, v11, v11 row_ror:8 row_mask:0xf bank_mask:0xc
	v_add_f32_dpp v4, v12, v12 row_ror:8 row_mask:0xf bank_mask:0xc
	v_add_f32_dpp v5, v13, v13 row_ror:8 row_mask:0xf bank_mask:0xc
	v_add_f32_dpp v6, v14, v14 row_ror:8 row_mask:0xf bank_mask:0xc
	v_add_f32_dpp v7, v15, v15 row_ror:8 row_mask:0xf bank_mask:0xc
	s_mov_b32 vcc_lo, 0xaaaaaaaa
	s_mov_b32 vcc_hi, 0xaaaaaaaa
	v_cndmask_b32_e32 v64, v0, v4, vcc
	v_cndmask_b32_e32 v65, v1, v5, vcc
	v_cndmask_b32_e32 v66, v2, v6, vcc
	v_cndmask_b32_e32 v67, v3, v7, vcc
	v_cndmask_b32_e32 v68, v4, v0, vcc
	v_cndmask_b32_e32 v69, v5, v1, vcc
	v_cndmask_b32_e32 v70, v6, v2, vcc
	v_cndmask_b32_e32 v71, v7, v3, vcc
	s_nop 1
	v_add_f32_dpp v0, v68, v64 quad_perm:[1,0,3,2] row_mask:0xf bank_mask:0xf
	v_add_f32_dpp v1, v69, v65 quad_perm:[1,0,3,2] row_mask:0xf bank_mask:0xf
	v_add_f32_dpp v2, v70, v66 quad_perm:[1,0,3,2] row_mask:0xf bank_mask:0xf
	v_add_f32_dpp v3, v71, v67 quad_perm:[1,0,3,2] row_mask:0xf bank_mask:0xf
	s_waitcnt vmcnt(24)
	v_pk_add_f32 v[212:213], v[212:213], v[0:1]
	v_pk_add_f32 v[214:215], v[214:215], v[2:3]
	global_store_dwordx4 v220, v[212:215], s[10:11]
	s_add_u32 s14, s14, 1
	s_and_b32 s14, s14, 63
	s_add_u32 s18, s14, 1
	s_and_b32 s98, s18, 63
	s_mov_b32 s100, s98
	s_and_b32 s19, s100, 15
	s_lshr_b32 s98, s100, 4
	s_lshl_b32 s99, s19, 9
	s_mul_i32 s15, s19, s16
	s_lshl_b32 s18, s98, 7
	s_add_u32 s15, s15, s18
	s_lshl_b32 s18, s101, 12
	s_add_u32 s15, s15, s18
	s_add_u32 s10, s24, s15
	s_addc_u32 s11, s25, 0
	s_mul_i32 s15, s98, 0x300000
	s_add_u32 s4, s26, 0x4800000
	s_addc_u32 s5, s27, 0
	s_add_u32 s4, s4, s15
	s_addc_u32 s5, s5, 0
	v_add_u32_e32 v222, s99, v217
	v_add_u32_e32 v224, s99, v218
	s_movk_i32 s100, 0xc0
	ds_read2_b32 v[192:193], v222 offset0:0 offset1:16
	ds_read2_b32 v[194:195], v222 offset0:32 offset1:48
	s_cmp_lg_u32 s14, 0
	s_cbranch_scc1 .Lgv1_loop
	s_waitcnt vmcnt(0) lgkmcnt(0)
	s_lshl_b32 s15, s92, 6
	s_add_u32 s101, s101, s15
	s_cmpk_lt_u32 s101, 0x8000
	s_cbranch_scc1 .Lgv1_chunk
	s_branch .LBB0_1104
